# baseline (speedup 1.0000x reference)
.LBB0_43:
	s_cmpk_lt_i32 s22, 0x400
	s_mov_b32 s23, 0x17c00000
	s_cselect_b32 s23, s23, 0x1bc00000
	s_add_u32 s38, s26, s23
	s_addc_u32 s39, s27, 0
	s_and_b32 s22, s22, 0x300
	v_or_b32_e32 v132, s22, v158
	v_add_lshl_u32 v133, v138, v156, 11
	v_lshl_or_b32 v138, v132, 1, v133
	v_cndmask_b32_e64 v132, v124, v125, s[12:13]
	v_mov_b32_e32 v133, v129
	s_nop 1
	v_mov_b32_dpp v133, v132 quad_perm:[1,0,3,2] row_mask:0xf bank_mask:0xf
	v_cndmask_b32_e64 v124, v133, v124, s[12:13]
	v_cndmask_b32_e64 v125, v125, v133, s[12:13]
	v_cvt_pk_bf16_f32 v124, v124, v125
	global_store_dword v138, v124, s[38:39] nt
	v_cndmask_b32_e64 v124, v126, v127, s[12:13]
	v_mov_b32_e32 v125, v129
	s_nop 1
	v_mov_b32_dpp v125, v124 quad_perm:[1,0,3,2] row_mask:0xf bank_mask:0xf
	v_cndmask_b32_e64 v124, v125, v126, s[12:13]
	v_cndmask_b32_e64 v125, v127, v125, s[12:13]
	v_cvt_pk_bf16_f32 v124, v124, v125
	v_add_u32_e32 v125, 0x1000, v138
	global_store_dword v125, v124, s[38:39] nt
	v_cndmask_b32_e64 v124, v116, v117, s[12:13]
	v_mov_b32_e32 v125, v129
	s_nop 1
	v_mov_b32_dpp v125, v124 quad_perm:[1,0,3,2] row_mask:0xf bank_mask:0xf
	v_cndmask_b32_e64 v116, v125, v116, s[12:13]
	v_cndmask_b32_e64 v117, v117, v125, s[12:13]
	v_cvt_pk_bf16_f32 v116, v116, v117
	global_store_dword v138, v116, s[38:39] offset:32 nt
	v_cndmask_b32_e64 v116, v118, v119, s[12:13]
	v_mov_b32_e32 v117, v129
	s_nop 1
	v_mov_b32_dpp v117, v116 quad_perm:[1,0,3,2] row_mask:0xf bank_mask:0xf
	v_cndmask_b32_e64 v116, v117, v118, s[12:13]
	v_cndmask_b32_e64 v117, v119, v117, s[12:13]
	v_cvt_pk_bf16_f32 v116, v116, v117
	v_add_u32_e32 v117, 0x1020, v138
	global_store_dword v117, v116, s[38:39] nt
	v_cndmask_b32_e64 v116, v120, v121, s[12:13]
	v_mov_b32_e32 v117, v129
	s_nop 1
	v_mov_b32_dpp v117, v116 quad_perm:[1,0,3,2] row_mask:0xf bank_mask:0xf
	v_cndmask_b32_e64 v116, v117, v120, s[12:13]
	v_cndmask_b32_e64 v117, v121, v117, s[12:13]
	v_cvt_pk_bf16_f32 v116, v116, v117
	global_store_dword v138, v116, s[38:39] offset:256 nt
	v_cndmask_b32_e64 v116, v122, v123, s[12:13]
	v_mov_b32_e32 v117, v129
	s_nop 1
	v_mov_b32_dpp v117, v116 quad_perm:[1,0,3,2] row_mask:0xf bank_mask:0xf
	v_cndmask_b32_e64 v116, v117, v122, s[12:13]
	v_cndmask_b32_e64 v117, v123, v117, s[12:13]
	v_cvt_pk_bf16_f32 v116, v116, v117
	v_add_u32_e32 v117, 0x1100, v138
	global_store_dword v117, v116, s[38:39] nt
	v_cndmask_b32_e64 v116, v112, v113, s[12:13]
	v_mov_b32_e32 v117, v129
	s_nop 1
	v_mov_b32_dpp v117, v116 quad_perm:[1,0,3,2] row_mask:0xf bank_mask:0xf
	v_cndmask_b32_e64 v112, v117, v112, s[12:13]
	v_cndmask_b32_e64 v113, v113, v117, s[12:13]
	v_cvt_pk_bf16_f32 v112, v112, v113
	global_store_dword v138, v112, s[38:39] offset:288 nt
	v_cndmask_b32_e64 v112, v114, v115, s[12:13]
	v_mov_b32_e32 v113, v129
	s_nop 1
	v_mov_b32_dpp v113, v112 quad_perm:[1,0,3,2] row_mask:0xf bank_mask:0xf
	v_cndmask_b32_e64 v112, v113, v114, s[12:13]
	v_cndmask_b32_e64 v113, v115, v113, s[12:13]
	v_cvt_pk_bf16_f32 v112, v112, v113
	v_add_u32_e32 v113, 0x1120, v138
	global_store_dword v113, v112, s[38:39] nt
	v_cndmask_b32_e64 v112, v108, v109, s[12:13]
	v_mov_b32_e32 v113, v129
	s_nop 1
	v_mov_b32_dpp v113, v112 quad_perm:[1,0,3,2] row_mask:0xf bank_mask:0xf
	v_cndmask_b32_e64 v108, v113, v108, s[12:13]
	v_cndmask_b32_e64 v109, v109, v113, s[12:13]
	v_cvt_pk_bf16_f32 v108, v108, v109
	v_add_u32_e32 v109, 0x8000, v138
	global_store_dword v109, v108, s[38:39] nt
	v_cndmask_b32_e64 v108, v110, v111, s[12:13]
	v_mov_b32_e32 v109, v129
	s_nop 1
	v_mov_b32_dpp v109, v108 quad_perm:[1,0,3,2] row_mask:0xf bank_mask:0xf
	v_cndmask_b32_e64 v108, v109, v110, s[12:13]
	v_cndmask_b32_e64 v109, v111, v109, s[12:13]
	v_cvt_pk_bf16_f32 v108, v108, v109
	v_add_u32_e32 v109, 0x9000, v138
	global_store_dword v109, v108, s[38:39] nt
	v_cndmask_b32_e64 v108, v100, v101, s[12:13]
	v_mov_b32_e32 v109, v129
	s_nop 1
	v_mov_b32_dpp v109, v108 quad_perm:[1,0,3,2] row_mask:0xf bank_mask:0xf
	v_cndmask_b32_e64 v100, v109, v100, s[12:13]
	v_cndmask_b32_e64 v101, v101, v109, s[12:13]
	v_cvt_pk_bf16_f32 v100, v100, v101
	v_add_u32_e32 v101, 0x8020, v138
	global_store_dword v101, v100, s[38:39] nt
	v_cndmask_b32_e64 v100, v102, v103, s[12:13]
	v_mov_b32_e32 v101, v129
	s_nop 1
	v_mov_b32_dpp v101, v100 quad_perm:[1,0,3,2] row_mask:0xf bank_mask:0xf
	v_cndmask_b32_e64 v100, v101, v102, s[12:13]
	v_cndmask_b32_e64 v101, v103, v101, s[12:13]
	v_cvt_pk_bf16_f32 v100, v100, v101
	v_add_u32_e32 v101, 0x9020, v138
	global_store_dword v101, v100, s[38:39] nt
	v_cndmask_b32_e64 v100, v104, v105, s[12:13]
	v_mov_b32_e32 v101, v129
	s_nop 1
	v_mov_b32_dpp v101, v100 quad_perm:[1,0,3,2] row_mask:0xf bank_mask:0xf
	v_cndmask_b32_e64 v100, v101, v104, s[12:13]
	v_cndmask_b32_e64 v101, v105, v101, s[12:13]
	v_cvt_pk_bf16_f32 v100, v100, v101
	v_add_u32_e32 v101, 0x8100, v138
	global_store_dword v101, v100, s[38:39] nt
	v_cndmask_b32_e64 v100, v106, v107, s[12:13]
	v_mov_b32_e32 v101, v129
	s_nop 1
	v_mov_b32_dpp v101, v100 quad_perm:[1,0,3,2] row_mask:0xf bank_mask:0xf
	v_cndmask_b32_e64 v100, v101, v106, s[12:13]
	v_cndmask_b32_e64 v101, v107, v101, s[12:13]
	v_cvt_pk_bf16_f32 v100, v100, v101
	v_add_u32_e32 v101, 0x9100, v138
	global_store_dword v101, v100, s[38:39] nt
	v_cndmask_b32_e64 v100, v96, v97, s[12:13]
	v_mov_b32_e32 v101, v129
	s_nop 1
	v_mov_b32_dpp v101, v100 quad_perm:[1,0,3,2] row_mask:0xf bank_mask:0xf
	v_cndmask_b32_e64 v96, v101, v96, s[12:13]
	v_cndmask_b32_e64 v97, v97, v101, s[12:13]
	v_cvt_pk_bf16_f32 v96, v96, v97
	v_add_u32_e32 v97, 0x8120, v138
	global_store_dword v97, v96, s[38:39] nt
	v_cndmask_b32_e64 v96, v98, v99, s[12:13]
	v_mov_b32_e32 v97, v129
	s_nop 1
	v_mov_b32_dpp v97, v96 quad_perm:[1,0,3,2] row_mask:0xf bank_mask:0xf
	v_cndmask_b32_e64 v96, v97, v98, s[12:13]
	v_cndmask_b32_e64 v97, v99, v97, s[12:13]
	v_cvt_pk_bf16_f32 v96, v96, v97
	v_add_u32_e32 v97, 0x9120, v138
	global_store_dword v97, v96, s[38:39] nt
	v_cndmask_b32_e64 v96, v92, v93, s[12:13]
	v_mov_b32_e32 v97, v129
	s_nop 1
	v_mov_b32_dpp v97, v96 quad_perm:[1,0,3,2] row_mask:0xf bank_mask:0xf
	v_cndmask_b32_e64 v92, v97, v92, s[12:13]
	v_cndmask_b32_e64 v93, v93, v97, s[12:13]
	v_cvt_pk_bf16_f32 v92, v92, v93
	v_add_u32_e32 v93, 0x10000, v138
	global_store_dword v93, v92, s[38:39] nt
	v_cndmask_b32_e64 v92, v94, v95, s[12:13]
	v_mov_b32_e32 v93, v129
	s_nop 1
	v_mov_b32_dpp v93, v92 quad_perm:[1,0,3,2] row_mask:0xf bank_mask:0xf
	v_cndmask_b32_e64 v92, v93, v94, s[12:13]
	v_cndmask_b32_e64 v93, v95, v93, s[12:13]
	v_cvt_pk_bf16_f32 v92, v92, v93
	v_add_u32_e32 v93, 0x11000, v138
	global_store_dword v93, v92, s[38:39] nt
	v_cndmask_b32_e64 v92, v84, v85, s[12:13]
	v_mov_b32_e32 v93, v129
	s_nop 1
	v_mov_b32_dpp v93, v92 quad_perm:[1,0,3,2] row_mask:0xf bank_mask:0xf
	v_cndmask_b32_e64 v84, v93, v84, s[12:13]
	v_cndmask_b32_e64 v85, v85, v93, s[12:13]
	v_cvt_pk_bf16_f32 v84, v84, v85
	v_add_u32_e32 v85, 0x10020, v138
	global_store_dword v85, v84, s[38:39] nt
	v_cndmask_b32_e64 v84, v86, v87, s[12:13]
	v_mov_b32_e32 v85, v129
	s_nop 1
	v_mov_b32_dpp v85, v84 quad_perm:[1,0,3,2] row_mask:0xf bank_mask:0xf
	v_cndmask_b32_e64 v84, v85, v86, s[12:13]
	v_cndmask_b32_e64 v85, v87, v85, s[12:13]
	v_cvt_pk_bf16_f32 v84, v84, v85
	v_add_u32_e32 v85, 0x11020, v138
	global_store_dword v85, v84, s[38:39] nt
	v_cndmask_b32_e64 v84, v88, v89, s[12:13]
	v_mov_b32_e32 v85, v129
	s_nop 1
	v_mov_b32_dpp v85, v84 quad_perm:[1,0,3,2] row_mask:0xf bank_mask:0xf
	v_cndmask_b32_e64 v84, v85, v88, s[12:13]
	v_cndmask_b32_e64 v85, v89, v85, s[12:13]
	v_cvt_pk_bf16_f32 v84, v84, v85
	v_add_u32_e32 v85, 0x10100, v138
	global_store_dword v85, v84, s[38:39] nt
	v_cndmask_b32_e64 v84, v90, v91, s[12:13]
	v_mov_b32_e32 v85, v129
	s_nop 1
	v_mov_b32_dpp v85, v84 quad_perm:[1,0,3,2] row_mask:0xf bank_mask:0xf
	v_cndmask_b32_e64 v84, v85, v90, s[12:13]
	v_cndmask_b32_e64 v85, v91, v85, s[12:13]
	v_cvt_pk_bf16_f32 v84, v84, v85
	v_add_u32_e32 v85, 0x11100, v138
	global_store_dword v85, v84, s[38:39] nt
	v_cndmask_b32_e64 v84, v80, v81, s[12:13]
	v_mov_b32_e32 v85, v129
	s_nop 1
	v_mov_b32_dpp v85, v84 quad_perm:[1,0,3,2] row_mask:0xf bank_mask:0xf
	v_cndmask_b32_e64 v80, v85, v80, s[12:13]
	v_cndmask_b32_e64 v81, v81, v85, s[12:13]
	v_cvt_pk_bf16_f32 v80, v80, v81
	v_add_u32_e32 v81, 0x10120, v138
	global_store_dword v81, v80, s[38:39] nt
	v_cndmask_b32_e64 v80, v82, v83, s[12:13]
	v_mov_b32_e32 v81, v129
	s_nop 1
	v_mov_b32_dpp v81, v80 quad_perm:[1,0,3,2] row_mask:0xf bank_mask:0xf
	v_cndmask_b32_e64 v80, v81, v82, s[12:13]
	v_cndmask_b32_e64 v81, v83, v81, s[12:13]
	v_cvt_pk_bf16_f32 v80, v80, v81
	v_add_u32_e32 v81, 0x11120, v138
	global_store_dword v81, v80, s[38:39] nt
	v_cndmask_b32_e64 v80, v76, v77, s[12:13]
	v_mov_b32_e32 v81, v129
	s_nop 1
	v_mov_b32_dpp v81, v80 quad_perm:[1,0,3,2] row_mask:0xf bank_mask:0xf
	v_cndmask_b32_e64 v76, v81, v76, s[12:13]
	v_cndmask_b32_e64 v77, v77, v81, s[12:13]
	v_cvt_pk_bf16_f32 v76, v76, v77
	v_add_u32_e32 v77, 0x18000, v138
	global_store_dword v77, v76, s[38:39] nt
	v_cndmask_b32_e64 v76, v78, v79, s[12:13]
	v_mov_b32_e32 v77, v129
	s_nop 1
	v_mov_b32_dpp v77, v76 quad_perm:[1,0,3,2] row_mask:0xf bank_mask:0xf
	v_cndmask_b32_e64 v76, v77, v78, s[12:13]
	v_cndmask_b32_e64 v77, v79, v77, s[12:13]
	v_cvt_pk_bf16_f32 v76, v76, v77
	v_add_u32_e32 v77, 0x19000, v138
	global_store_dword v77, v76, s[38:39] nt
	v_cndmask_b32_e64 v76, v68, v69, s[12:13]
	v_mov_b32_e32 v77, v129
	s_nop 1
	v_mov_b32_dpp v77, v76 quad_perm:[1,0,3,2] row_mask:0xf bank_mask:0xf
	v_cndmask_b32_e64 v68, v77, v68, s[12:13]
	v_cndmask_b32_e64 v69, v69, v77, s[12:13]
	v_cvt_pk_bf16_f32 v68, v68, v69
	v_add_u32_e32 v69, 0x18020, v138
	global_store_dword v69, v68, s[38:39] nt
	v_cndmask_b32_e64 v68, v70, v71, s[12:13]
	v_mov_b32_e32 v69, v129
	s_nop 1
	v_mov_b32_dpp v69, v68 quad_perm:[1,0,3,2] row_mask:0xf bank_mask:0xf
	v_cndmask_b32_e64 v68, v69, v70, s[12:13]
	v_cndmask_b32_e64 v69, v71, v69, s[12:13]
	v_cvt_pk_bf16_f32 v68, v68, v69
	v_add_u32_e32 v69, 0x19020, v138
	global_store_dword v69, v68, s[38:39] nt
	v_cndmask_b32_e64 v68, v72, v73, s[12:13]
	v_mov_b32_e32 v69, v129
	s_nop 1
	v_mov_b32_dpp v69, v68 quad_perm:[1,0,3,2] row_mask:0xf bank_mask:0xf
	v_cndmask_b32_e64 v68, v69, v72, s[12:13]
	v_cndmask_b32_e64 v69, v73, v69, s[12:13]
	v_cvt_pk_bf16_f32 v68, v68, v69
	v_add_u32_e32 v69, 0x18100, v138
	global_store_dword v69, v68, s[38:39] nt
	v_cndmask_b32_e64 v68, v74, v75, s[12:13]
	v_mov_b32_e32 v69, v129
	s_nop 1
	v_mov_b32_dpp v69, v68 quad_perm:[1,0,3,2] row_mask:0xf bank_mask:0xf
	v_cndmask_b32_e64 v68, v69, v74, s[12:13]
	v_cndmask_b32_e64 v69, v75, v69, s[12:13]
	v_cvt_pk_bf16_f32 v68, v68, v69
	v_add_u32_e32 v69, 0x19100, v138
	global_store_dword v69, v68, s[38:39] nt
	v_cndmask_b32_e64 v68, v64, v65, s[12:13]
	v_mov_b32_e32 v69, v129
	s_nop 1
	v_mov_b32_dpp v69, v68 quad_perm:[1,0,3,2] row_mask:0xf bank_mask:0xf
	v_cndmask_b32_e64 v64, v69, v64, s[12:13]
	v_cndmask_b32_e64 v65, v65, v69, s[12:13]
	v_cvt_pk_bf16_f32 v64, v64, v65
	v_add_u32_e32 v65, 0x18120, v138
	global_store_dword v65, v64, s[38:39] nt
	v_cndmask_b32_e64 v64, v66, v67, s[12:13]
	v_mov_b32_e32 v65, v129
	s_nop 1
	v_mov_b32_dpp v65, v64 quad_perm:[1,0,3,2] row_mask:0xf bank_mask:0xf
	v_cndmask_b32_e64 v64, v65, v66, s[12:13]
	v_cndmask_b32_e64 v65, v67, v65, s[12:13]
	v_cvt_pk_bf16_f32 v64, v64, v65
	v_add_u32_e32 v65, 0x19120, v138
	global_store_dword v65, v64, s[38:39] nt
	v_cndmask_b32_e64 v64, v60, v61, s[12:13]
	v_mov_b32_e32 v65, v129
	s_nop 1
	v_mov_b32_dpp v65, v64 quad_perm:[1,0,3,2] row_mask:0xf bank_mask:0xf
	v_cndmask_b32_e64 v60, v65, v60, s[12:13]
	v_cndmask_b32_e64 v61, v61, v65, s[12:13]
	v_cvt_pk_bf16_f32 v60, v60, v61
	v_add_u32_e32 v61, 0x40000, v138
	global_store_dword v61, v60, s[38:39] nt
	v_cndmask_b32_e64 v60, v62, v63, s[12:13]
	v_mov_b32_e32 v61, v129
	s_nop 1
	v_mov_b32_dpp v61, v60 quad_perm:[1,0,3,2] row_mask:0xf bank_mask:0xf
	v_cndmask_b32_e64 v60, v61, v62, s[12:13]
	v_cndmask_b32_e64 v61, v63, v61, s[12:13]
	v_cvt_pk_bf16_f32 v60, v60, v61
	v_add_u32_e32 v61, 0x41000, v138
	global_store_dword v61, v60, s[38:39] nt
	v_cndmask_b32_e64 v60, v52, v53, s[12:13]
	v_mov_b32_e32 v61, v129
	s_nop 1
	v_mov_b32_dpp v61, v60 quad_perm:[1,0,3,2] row_mask:0xf bank_mask:0xf
	v_cndmask_b32_e64 v52, v61, v52, s[12:13]
	v_cndmask_b32_e64 v53, v53, v61, s[12:13]
	v_cvt_pk_bf16_f32 v52, v52, v53
	v_add_u32_e32 v53, 0x40020, v138
	global_store_dword v53, v52, s[38:39] nt
	v_cndmask_b32_e64 v52, v54, v55, s[12:13]
	v_mov_b32_e32 v53, v129
	s_nop 1
	v_mov_b32_dpp v53, v52 quad_perm:[1,0,3,2] row_mask:0xf bank_mask:0xf
	v_cndmask_b32_e64 v52, v53, v54, s[12:13]
	v_cndmask_b32_e64 v53, v55, v53, s[12:13]
	v_cvt_pk_bf16_f32 v52, v52, v53
	v_add_u32_e32 v53, 0x41020, v138
	global_store_dword v53, v52, s[38:39] nt
	v_cndmask_b32_e64 v52, v56, v57, s[12:13]
	v_mov_b32_e32 v53, v129
	s_nop 1
	v_mov_b32_dpp v53, v52 quad_perm:[1,0,3,2] row_mask:0xf bank_mask:0xf
	v_cndmask_b32_e64 v52, v53, v56, s[12:13]
	v_cndmask_b32_e64 v53, v57, v53, s[12:13]
	v_cvt_pk_bf16_f32 v52, v52, v53
	v_add_u32_e32 v53, 0x40100, v138
	global_store_dword v53, v52, s[38:39] nt
	v_cndmask_b32_e64 v52, v58, v59, s[12:13]
	v_mov_b32_e32 v53, v129
	s_nop 1
	v_mov_b32_dpp v53, v52 quad_perm:[1,0,3,2] row_mask:0xf bank_mask:0xf
	v_cndmask_b32_e64 v52, v53, v58, s[12:13]
	v_cndmask_b32_e64 v53, v59, v53, s[12:13]
	v_cvt_pk_bf16_f32 v52, v52, v53
	v_add_u32_e32 v53, 0x41100, v138
	global_store_dword v53, v52, s[38:39] nt
	v_cndmask_b32_e64 v52, v48, v49, s[12:13]
	v_mov_b32_e32 v53, v129
	s_nop 1
	v_mov_b32_dpp v53, v52 quad_perm:[1,0,3,2] row_mask:0xf bank_mask:0xf
	v_cndmask_b32_e64 v48, v53, v48, s[12:13]
	v_cndmask_b32_e64 v49, v49, v53, s[12:13]
	v_cvt_pk_bf16_f32 v48, v48, v49
	v_add_u32_e32 v49, 0x40120, v138
	global_store_dword v49, v48, s[38:39] nt
	v_cndmask_b32_e64 v48, v50, v51, s[12:13]
	v_mov_b32_e32 v49, v129
	s_nop 1
	v_mov_b32_dpp v49, v48 quad_perm:[1,0,3,2] row_mask:0xf bank_mask:0xf
	v_cndmask_b32_e64 v48, v49, v50, s[12:13]
	v_cndmask_b32_e64 v49, v51, v49, s[12:13]
	v_cvt_pk_bf16_f32 v48, v48, v49
	v_add_u32_e32 v49, 0x41120, v138
	global_store_dword v49, v48, s[38:39] nt
	v_cndmask_b32_e64 v48, v44, v45, s[12:13]
	v_mov_b32_e32 v49, v129
	s_nop 1
	v_mov_b32_dpp v49, v48 quad_perm:[1,0,3,2] row_mask:0xf bank_mask:0xf
	v_cndmask_b32_e64 v44, v49, v44, s[12:13]
	v_cndmask_b32_e64 v45, v45, v49, s[12:13]
	v_cvt_pk_bf16_f32 v44, v44, v45
	v_add_u32_e32 v45, 0x48000, v138
	global_store_dword v45, v44, s[38:39] nt
	v_cndmask_b32_e64 v44, v46, v47, s[12:13]
	v_mov_b32_e32 v45, v129
	s_nop 1
	v_mov_b32_dpp v45, v44 quad_perm:[1,0,3,2] row_mask:0xf bank_mask:0xf
	v_cndmask_b32_e64 v44, v45, v46, s[12:13]
	v_cndmask_b32_e64 v45, v47, v45, s[12:13]
	v_cvt_pk_bf16_f32 v44, v44, v45
	v_add_u32_e32 v45, 0x49000, v138
	global_store_dword v45, v44, s[38:39] nt
	v_cndmask_b32_e64 v44, v36, v37, s[12:13]
	v_mov_b32_e32 v45, v129
	s_nop 1
	v_mov_b32_dpp v45, v44 quad_perm:[1,0,3,2] row_mask:0xf bank_mask:0xf
	v_cndmask_b32_e64 v36, v45, v36, s[12:13]
	v_cndmask_b32_e64 v37, v37, v45, s[12:13]
	v_cvt_pk_bf16_f32 v36, v36, v37
	v_add_u32_e32 v37, 0x48020, v138
	global_store_dword v37, v36, s[38:39] nt
	v_cndmask_b32_e64 v36, v38, v39, s[12:13]
	v_mov_b32_e32 v37, v129
	s_nop 1
	v_mov_b32_dpp v37, v36 quad_perm:[1,0,3,2] row_mask:0xf bank_mask:0xf
	v_cndmask_b32_e64 v36, v37, v38, s[12:13]
	v_cndmask_b32_e64 v37, v39, v37, s[12:13]
	v_cvt_pk_bf16_f32 v36, v36, v37
	v_add_u32_e32 v37, 0x49020, v138
	global_store_dword v37, v36, s[38:39] nt
	v_cndmask_b32_e64 v36, v40, v41, s[12:13]
	v_mov_b32_e32 v37, v129
	s_nop 1
	v_mov_b32_dpp v37, v36 quad_perm:[1,0,3,2] row_mask:0xf bank_mask:0xf
	v_cndmask_b32_e64 v36, v37, v40, s[12:13]
	v_cndmask_b32_e64 v37, v41, v37, s[12:13]
	v_cvt_pk_bf16_f32 v36, v36, v37
	v_add_u32_e32 v37, 0x48100, v138
	global_store_dword v37, v36, s[38:39] nt
	v_cndmask_b32_e64 v36, v42, v43, s[12:13]
	v_mov_b32_e32 v37, v129
	s_nop 1
	v_mov_b32_dpp v37, v36 quad_perm:[1,0,3,2] row_mask:0xf bank_mask:0xf
	v_cndmask_b32_e64 v36, v37, v42, s[12:13]
	v_cndmask_b32_e64 v37, v43, v37, s[12:13]
	v_cvt_pk_bf16_f32 v36, v36, v37
	v_add_u32_e32 v37, 0x49100, v138
	global_store_dword v37, v36, s[38:39] nt
	v_cndmask_b32_e64 v36, v32, v33, s[12:13]
	v_mov_b32_e32 v37, v129
	s_nop 1
	v_mov_b32_dpp v37, v36 quad_perm:[1,0,3,2] row_mask:0xf bank_mask:0xf
	v_cndmask_b32_e64 v32, v37, v32, s[12:13]
	v_cndmask_b32_e64 v33, v33, v37, s[12:13]
	v_cvt_pk_bf16_f32 v32, v32, v33
	v_add_u32_e32 v33, 0x48120, v138
	global_store_dword v33, v32, s[38:39] nt
	v_cndmask_b32_e64 v32, v34, v35, s[12:13]
	v_mov_b32_e32 v33, v129
	s_nop 1
	v_mov_b32_dpp v33, v32 quad_perm:[1,0,3,2] row_mask:0xf bank_mask:0xf
	v_cndmask_b32_e64 v32, v33, v34, s[12:13]
	v_cndmask_b32_e64 v33, v35, v33, s[12:13]
	v_cvt_pk_bf16_f32 v32, v32, v33
	v_add_u32_e32 v33, 0x49120, v138
	global_store_dword v33, v32, s[38:39] nt
	v_cndmask_b32_e64 v32, v28, v29, s[12:13]
	v_mov_b32_e32 v33, v129
	s_nop 1
	v_mov_b32_dpp v33, v32 quad_perm:[1,0,3,2] row_mask:0xf bank_mask:0xf
	v_cndmask_b32_e64 v28, v33, v28, s[12:13]
	v_cndmask_b32_e64 v29, v29, v33, s[12:13]
	v_cvt_pk_bf16_f32 v28, v28, v29
	v_add_u32_e32 v29, 0x50000, v138
	global_store_dword v29, v28, s[38:39] nt
	v_cndmask_b32_e64 v28, v30, v31, s[12:13]
	v_mov_b32_e32 v29, v129
	s_nop 1
	v_mov_b32_dpp v29, v28 quad_perm:[1,0,3,2] row_mask:0xf bank_mask:0xf
	v_cndmask_b32_e64 v28, v29, v30, s[12:13]
	v_cndmask_b32_e64 v29, v31, v29, s[12:13]
	v_cvt_pk_bf16_f32 v28, v28, v29
	v_add_u32_e32 v29, 0x51000, v138
	global_store_dword v29, v28, s[38:39] nt
	v_cndmask_b32_e64 v28, v20, v21, s[12:13]
	v_mov_b32_e32 v29, v129
	s_nop 1
	v_mov_b32_dpp v29, v28 quad_perm:[1,0,3,2] row_mask:0xf bank_mask:0xf
	v_cndmask_b32_e64 v20, v29, v20, s[12:13]
	v_cndmask_b32_e64 v21, v21, v29, s[12:13]
	v_cvt_pk_bf16_f32 v20, v20, v21
	v_add_u32_e32 v21, 0x50020, v138
	global_store_dword v21, v20, s[38:39] nt
	v_cndmask_b32_e64 v20, v22, v23, s[12:13]
	v_mov_b32_e32 v21, v129
	s_nop 1
	v_mov_b32_dpp v21, v20 quad_perm:[1,0,3,2] row_mask:0xf bank_mask:0xf
	v_cndmask_b32_e64 v20, v21, v22, s[12:13]
	v_cndmask_b32_e64 v21, v23, v21, s[12:13]
	v_cvt_pk_bf16_f32 v20, v20, v21
	v_add_u32_e32 v21, 0x51020, v138
	global_store_dword v21, v20, s[38:39] nt
	v_cndmask_b32_e64 v20, v24, v25, s[12:13]
	v_mov_b32_e32 v21, v129
	s_nop 1
	v_mov_b32_dpp v21, v20 quad_perm:[1,0,3,2] row_mask:0xf bank_mask:0xf
	v_cndmask_b32_e64 v20, v21, v24, s[12:13]
	v_cndmask_b32_e64 v21, v25, v21, s[12:13]
	v_cvt_pk_bf16_f32 v20, v20, v21
	v_add_u32_e32 v21, 0x50100, v138
	global_store_dword v21, v20, s[38:39] nt
	v_cndmask_b32_e64 v20, v26, v27, s[12:13]
	v_mov_b32_e32 v21, v129
	s_nop 1
	v_mov_b32_dpp v21, v20 quad_perm:[1,0,3,2] row_mask:0xf bank_mask:0xf
	v_cndmask_b32_e64 v20, v21, v26, s[12:13]
	v_cndmask_b32_e64 v21, v27, v21, s[12:13]
	v_cvt_pk_bf16_f32 v20, v20, v21
	v_add_u32_e32 v21, 0x51100, v138
	global_store_dword v21, v20, s[38:39] nt
	v_cndmask_b32_e64 v20, v16, v17, s[12:13]
	v_mov_b32_e32 v21, v129
	s_nop 1
	v_mov_b32_dpp v21, v20 quad_perm:[1,0,3,2] row_mask:0xf bank_mask:0xf
	v_cndmask_b32_e64 v16, v21, v16, s[12:13]
	v_cndmask_b32_e64 v17, v17, v21, s[12:13]
	v_cvt_pk_bf16_f32 v16, v16, v17
	v_add_u32_e32 v17, 0x50120, v138
	global_store_dword v17, v16, s[38:39] nt
	v_cndmask_b32_e64 v16, v18, v19, s[12:13]
	v_mov_b32_e32 v17, v129
	s_nop 1
	v_mov_b32_dpp v17, v16 quad_perm:[1,0,3,2] row_mask:0xf bank_mask:0xf
	v_cndmask_b32_e64 v16, v17, v18, s[12:13]
	v_cndmask_b32_e64 v17, v19, v17, s[12:13]
	v_cvt_pk_bf16_f32 v16, v16, v17
	v_add_u32_e32 v17, 0x51120, v138
	global_store_dword v17, v16, s[38:39] nt
	v_cndmask_b32_e64 v16, v12, v13, s[12:13]
	v_mov_b32_e32 v17, v129
	s_nop 1
	v_mov_b32_dpp v17, v16 quad_perm:[1,0,3,2] row_mask:0xf bank_mask:0xf
	v_cndmask_b32_e64 v12, v17, v12, s[12:13]
	v_cndmask_b32_e64 v13, v13, v17, s[12:13]
	v_cvt_pk_bf16_f32 v12, v12, v13
	v_add_u32_e32 v13, 0x58000, v138
	global_store_dword v13, v12, s[38:39] nt
	v_cndmask_b32_e64 v12, v14, v15, s[12:13]
	v_mov_b32_e32 v13, v129
	s_nop 1
	v_mov_b32_dpp v13, v12 quad_perm:[1,0,3,2] row_mask:0xf bank_mask:0xf
	v_cndmask_b32_e64 v12, v13, v14, s[12:13]
	v_cndmask_b32_e64 v13, v15, v13, s[12:13]
	v_cvt_pk_bf16_f32 v12, v12, v13
	v_add_u32_e32 v13, 0x59000, v138
	global_store_dword v13, v12, s[38:39] nt
	v_cndmask_b32_e64 v12, v4, v5, s[12:13]
	v_mov_b32_e32 v13, v129
	s_nop 1
	v_mov_b32_dpp v13, v12 quad_perm:[1,0,3,2] row_mask:0xf bank_mask:0xf
	v_cndmask_b32_e64 v4, v13, v4, s[12:13]
	v_cndmask_b32_e64 v5, v5, v13, s[12:13]
	v_cvt_pk_bf16_f32 v4, v4, v5
	v_add_u32_e32 v5, 0x58020, v138
	global_store_dword v5, v4, s[38:39] nt
	v_cndmask_b32_e64 v4, v6, v7, s[12:13]
	v_mov_b32_e32 v5, v129
	s_nop 1
	v_mov_b32_dpp v5, v4 quad_perm:[1,0,3,2] row_mask:0xf bank_mask:0xf
	v_cndmask_b32_e64 v4, v5, v6, s[12:13]
	v_cndmask_b32_e64 v5, v7, v5, s[12:13]
	v_cvt_pk_bf16_f32 v4, v4, v5
	v_add_u32_e32 v5, 0x59020, v138
	global_store_dword v5, v4, s[38:39] nt
	v_cndmask_b32_e64 v4, v8, v9, s[12:13]
	v_mov_b32_e32 v5, v129
	s_nop 1
	v_mov_b32_dpp v5, v4 quad_perm:[1,0,3,2] row_mask:0xf bank_mask:0xf
	v_cndmask_b32_e64 v4, v5, v8, s[12:13]
	v_cndmask_b32_e64 v5, v9, v5, s[12:13]
	v_cvt_pk_bf16_f32 v4, v4, v5
	v_add_u32_e32 v5, 0x58100, v138
	global_store_dword v5, v4, s[38:39] nt
	v_cndmask_b32_e64 v4, v10, v11, s[12:13]
	v_mov_b32_e32 v5, v129
	s_nop 1
	v_mov_b32_dpp v5, v4 quad_perm:[1,0,3,2] row_mask:0xf bank_mask:0xf
	v_cndmask_b32_e64 v4, v5, v10, s[12:13]
	v_cndmask_b32_e64 v5, v11, v5, s[12:13]
	v_cvt_pk_bf16_f32 v4, v4, v5
	v_add_u32_e32 v5, 0x59100, v138
	global_store_dword v5, v4, s[38:39] nt
	v_cndmask_b32_e64 v4, v0, v1, s[12:13]
	v_mov_b32_e32 v5, v129
	s_nop 1
	v_mov_b32_dpp v5, v4 quad_perm:[1,0,3,2] row_mask:0xf bank_mask:0xf
	v_cndmask_b32_e64 v0, v5, v0, s[12:13]
	v_cndmask_b32_e64 v1, v1, v5, s[12:13]
	v_cvt_pk_bf16_f32 v0, v0, v1
	v_add_u32_e32 v1, 0x58120, v138
	global_store_dword v1, v0, s[38:39] nt
	v_cndmask_b32_e64 v0, v2, v3, s[12:13]
	v_mov_b32_e32 v1, v129
	s_nop 1
	v_mov_b32_dpp v1, v0 quad_perm:[1,0,3,2] row_mask:0xf bank_mask:0xf
	v_cndmask_b32_e64 v0, v1, v2, s[12:13]
	v_cndmask_b32_e64 v1, v3, v1, s[12:13]
	v_cvt_pk_bf16_f32 v0, v0, v1
	v_add_u32_e32 v1, 0x59120, v138
	global_store_dword v1, v0, s[38:39] nt
	s_branch .LBB0_29

.LBB0_73:
	v_or_b32_e32 v158, s19, v149
	v_add_lshl_u32 v159, v148, s18, 11
	v_lshl_add_u32 v158, v158, 1, v159
	v_cvt_pk_bf16_f32 v159, v124, v125
	s_nop 1
	v_mov_b32_dpp v160, v159 quad_perm:[1,0,3,2] row_mask:0xf bank_mask:0xf
	v_perm_b32 v124, v160, v159, v250
	global_store_dword v158, v124, s[12:13] nt
	v_cvt_pk_bf16_f32 v124, v126, v127
	s_nop 1
	v_mov_b32_dpp v125, v124 quad_perm:[1,0,3,2] row_mask:0xf bank_mask:0xf
	v_perm_b32 v124, v125, v124, v250
	v_add_u32_e32 v125, 0x1000, v158
	global_store_dword v125, v124, s[12:13] nt
	v_cndmask_b32_e64 v125, v116, v117, s[10:11]
	v_mov_b32_e32 v126, v129
	v_or_b32_e32 v124, 32, v158
	s_nop 0
	v_mov_b32_dpp v126, v125 quad_perm:[1,0,3,2] row_mask:0xf bank_mask:0xf
	v_cndmask_b32_e64 v116, v126, v116, s[10:11]
	v_cndmask_b32_e64 v117, v117, v126, s[10:11]
	v_cvt_pk_bf16_f32 v116, v116, v117
	global_store_dword v124, v116, s[12:13] nt
	v_cvt_pk_bf16_f32 v116, v118, v119
	s_nop 1
	v_mov_b32_dpp v117, v116 quad_perm:[1,0,3,2] row_mask:0xf bank_mask:0xf
	v_perm_b32 v116, v117, v116, v250
	v_add_u32_e32 v117, 0x1020, v158
	global_store_dword v117, v116, s[12:13] nt
	v_cndmask_b32_e64 v117, v120, v121, s[10:11]
	v_mov_b32_e32 v118, v129
	v_or_b32_e32 v116, 0x100, v158
	s_nop 0
	v_mov_b32_dpp v118, v117 quad_perm:[1,0,3,2] row_mask:0xf bank_mask:0xf
	v_cndmask_b32_e64 v117, v118, v120, s[10:11]
	v_cndmask_b32_e64 v118, v121, v118, s[10:11]
	v_cvt_pk_bf16_f32 v117, v117, v118
	global_store_dword v116, v117, s[12:13] nt
	v_cndmask_b32_e64 v116, v122, v123, s[10:11]
	v_mov_b32_e32 v117, v129
	v_mov_b32_e32 v118, v129
	s_nop 0
	v_mov_b32_dpp v117, v116 quad_perm:[1,0,3,2] row_mask:0xf bank_mask:0xf
	v_cndmask_b32_e64 v116, v117, v122, s[10:11]
	v_cndmask_b32_e64 v117, v123, v117, s[10:11]
	v_cvt_pk_bf16_f32 v116, v116, v117
	v_add_u32_e32 v117, 0x1100, v158
	global_store_dword v117, v116, s[12:13] nt
	v_cndmask_b32_e64 v117, v112, v113, s[10:11]
	v_or_b32_e32 v116, 0x120, v158
	s_nop 0
	v_mov_b32_dpp v118, v117 quad_perm:[1,0,3,2] row_mask:0xf bank_mask:0xf
	v_cndmask_b32_e64 v112, v118, v112, s[10:11]
	v_cndmask_b32_e64 v113, v113, v118, s[10:11]
	v_cvt_pk_bf16_f32 v112, v112, v113
	global_store_dword v116, v112, s[12:13] nt
	v_cvt_pk_bf16_f32 v112, v114, v115
	s_nop 1
	v_mov_b32_dpp v113, v112 quad_perm:[1,0,3,2] row_mask:0xf bank_mask:0xf
	v_perm_b32 v112, v113, v112, v250
	v_add_u32_e32 v113, 0x1120, v158
	global_store_dword v113, v112, s[12:13] nt
	v_cvt_pk_bf16_f32 v112, v108, v109
	s_nop 1
	v_mov_b32_dpp v113, v112 quad_perm:[1,0,3,2] row_mask:0xf bank_mask:0xf
	v_perm_b32 v108, v113, v112, v250
	v_add_u32_e32 v109, 0x8000, v158
	global_store_dword v109, v108, s[12:13] nt
	v_cvt_pk_bf16_f32 v108, v110, v111
	s_nop 1
	v_mov_b32_dpp v109, v108 quad_perm:[1,0,3,2] row_mask:0xf bank_mask:0xf
	v_perm_b32 v108, v109, v108, v250
	v_add_u32_e32 v109, 0x9000, v158
	global_store_dword v109, v108, s[12:13] nt
	v_cvt_pk_bf16_f32 v108, v100, v101
	s_nop 1
	v_mov_b32_dpp v109, v108 quad_perm:[1,0,3,2] row_mask:0xf bank_mask:0xf
	v_perm_b32 v100, v109, v108, v250
	v_add_u32_e32 v101, 0x8020, v158
	global_store_dword v101, v100, s[12:13] nt
	v_cvt_pk_bf16_f32 v100, v102, v103
	s_nop 1
	v_mov_b32_dpp v101, v100 quad_perm:[1,0,3,2] row_mask:0xf bank_mask:0xf
	v_perm_b32 v100, v101, v100, v250
	v_add_u32_e32 v101, 0x9020, v158
	global_store_dword v101, v100, s[12:13] nt
	v_cvt_pk_bf16_f32 v100, v104, v105
	s_nop 1
	v_mov_b32_dpp v101, v100 quad_perm:[1,0,3,2] row_mask:0xf bank_mask:0xf
	v_perm_b32 v100, v101, v100, v250
	v_add_u32_e32 v101, 0x8100, v158
	global_store_dword v101, v100, s[12:13] nt
	v_cvt_pk_bf16_f32 v100, v106, v107
	s_nop 1
	v_mov_b32_dpp v101, v100 quad_perm:[1,0,3,2] row_mask:0xf bank_mask:0xf
	v_perm_b32 v100, v101, v100, v250
	v_add_u32_e32 v101, 0x9100, v158
	global_store_dword v101, v100, s[12:13] nt
	v_cvt_pk_bf16_f32 v100, v96, v97
	s_nop 1
	v_mov_b32_dpp v101, v100 quad_perm:[1,0,3,2] row_mask:0xf bank_mask:0xf
	v_perm_b32 v96, v101, v100, v250
	v_add_u32_e32 v97, 0x8120, v158
	global_store_dword v97, v96, s[12:13] nt
	v_cvt_pk_bf16_f32 v96, v98, v99
	s_nop 1
	v_mov_b32_dpp v97, v96 quad_perm:[1,0,3,2] row_mask:0xf bank_mask:0xf
	v_perm_b32 v96, v97, v96, v250
	v_add_u32_e32 v97, 0x9120, v158
	global_store_dword v97, v96, s[12:13] nt
	v_cvt_pk_bf16_f32 v96, v92, v93
	s_nop 1
	v_mov_b32_dpp v97, v96 quad_perm:[1,0,3,2] row_mask:0xf bank_mask:0xf
	v_perm_b32 v92, v97, v96, v250
	v_add_u32_e32 v93, 0x10000, v158
	global_store_dword v93, v92, s[12:13] nt
	v_cvt_pk_bf16_f32 v92, v94, v95
	s_nop 1
	v_mov_b32_dpp v93, v92 quad_perm:[1,0,3,2] row_mask:0xf bank_mask:0xf
	v_perm_b32 v92, v93, v92, v250
	v_add_u32_e32 v93, 0x11000, v158
	global_store_dword v93, v92, s[12:13] nt
	v_cvt_pk_bf16_f32 v92, v84, v85
	s_nop 1
	v_mov_b32_dpp v93, v92 quad_perm:[1,0,3,2] row_mask:0xf bank_mask:0xf
	v_perm_b32 v84, v93, v92, v250
	v_add_u32_e32 v85, 0x10020, v158
	global_store_dword v85, v84, s[12:13] nt
	v_cvt_pk_bf16_f32 v84, v86, v87
	s_nop 1
	v_mov_b32_dpp v85, v84 quad_perm:[1,0,3,2] row_mask:0xf bank_mask:0xf
	v_perm_b32 v84, v85, v84, v250
	v_add_u32_e32 v85, 0x11020, v158
	global_store_dword v85, v84, s[12:13] nt
	v_cvt_pk_bf16_f32 v84, v88, v89
	s_nop 1
	v_mov_b32_dpp v85, v84 quad_perm:[1,0,3,2] row_mask:0xf bank_mask:0xf
	v_perm_b32 v84, v85, v84, v250
	v_add_u32_e32 v85, 0x10100, v158
	global_store_dword v85, v84, s[12:13] nt
	v_cvt_pk_bf16_f32 v84, v90, v91
	s_nop 1
	v_mov_b32_dpp v85, v84 quad_perm:[1,0,3,2] row_mask:0xf bank_mask:0xf
	v_perm_b32 v84, v85, v84, v250
	v_add_u32_e32 v85, 0x11100, v158
	global_store_dword v85, v84, s[12:13] nt
	v_cvt_pk_bf16_f32 v84, v80, v81
	s_nop 1
	v_mov_b32_dpp v85, v84 quad_perm:[1,0,3,2] row_mask:0xf bank_mask:0xf
	v_perm_b32 v80, v85, v84, v250
	v_add_u32_e32 v81, 0x10120, v158
	global_store_dword v81, v80, s[12:13] nt
	v_cvt_pk_bf16_f32 v80, v82, v83
	s_nop 1
	v_mov_b32_dpp v81, v80 quad_perm:[1,0,3,2] row_mask:0xf bank_mask:0xf
	v_perm_b32 v80, v81, v80, v250
	v_add_u32_e32 v81, 0x11120, v158
	global_store_dword v81, v80, s[12:13] nt
	v_cvt_pk_bf16_f32 v80, v76, v77
	s_nop 1
	v_mov_b32_dpp v81, v80 quad_perm:[1,0,3,2] row_mask:0xf bank_mask:0xf
	v_perm_b32 v76, v81, v80, v250
	v_add_u32_e32 v77, 0x18000, v158
	global_store_dword v77, v76, s[12:13] nt
	v_cvt_pk_bf16_f32 v76, v78, v79
	s_nop 1
	v_mov_b32_dpp v77, v76 quad_perm:[1,0,3,2] row_mask:0xf bank_mask:0xf
	v_perm_b32 v76, v77, v76, v250
	v_add_u32_e32 v77, 0x19000, v158
	global_store_dword v77, v76, s[12:13] nt
	v_cvt_pk_bf16_f32 v76, v68, v69
	s_nop 1
	v_mov_b32_dpp v77, v76 quad_perm:[1,0,3,2] row_mask:0xf bank_mask:0xf
	v_perm_b32 v68, v77, v76, v250
	v_add_u32_e32 v69, 0x18020, v158
	global_store_dword v69, v68, s[12:13] nt
	v_cvt_pk_bf16_f32 v68, v70, v71
	s_nop 1
	v_mov_b32_dpp v69, v68 quad_perm:[1,0,3,2] row_mask:0xf bank_mask:0xf
	v_perm_b32 v68, v69, v68, v250
	v_add_u32_e32 v69, 0x19020, v158
	global_store_dword v69, v68, s[12:13] nt
	v_cvt_pk_bf16_f32 v68, v72, v73
	s_nop 1
	v_mov_b32_dpp v69, v68 quad_perm:[1,0,3,2] row_mask:0xf bank_mask:0xf
	v_perm_b32 v68, v69, v68, v250
	v_add_u32_e32 v69, 0x18100, v158
	global_store_dword v69, v68, s[12:13] nt
	v_cvt_pk_bf16_f32 v68, v74, v75
	s_nop 1
	v_mov_b32_dpp v69, v68 quad_perm:[1,0,3,2] row_mask:0xf bank_mask:0xf
	v_perm_b32 v68, v69, v68, v250
	v_add_u32_e32 v69, 0x19100, v158
	global_store_dword v69, v68, s[12:13] nt
	v_cvt_pk_bf16_f32 v68, v64, v65
	s_nop 1
	v_mov_b32_dpp v69, v68 quad_perm:[1,0,3,2] row_mask:0xf bank_mask:0xf
	v_perm_b32 v64, v69, v68, v250
	v_add_u32_e32 v65, 0x18120, v158
	global_store_dword v65, v64, s[12:13] nt
	v_cvt_pk_bf16_f32 v64, v66, v67
	s_nop 1
	v_mov_b32_dpp v65, v64 quad_perm:[1,0,3,2] row_mask:0xf bank_mask:0xf
	v_perm_b32 v64, v65, v64, v250
	v_add_u32_e32 v65, 0x19120, v158
	global_store_dword v65, v64, s[12:13] nt
	v_cvt_pk_bf16_f32 v64, v60, v61
	s_nop 1
	v_mov_b32_dpp v65, v64 quad_perm:[1,0,3,2] row_mask:0xf bank_mask:0xf
	v_perm_b32 v60, v65, v64, v250
	v_add_u32_e32 v61, 0x40000, v158
	global_store_dword v61, v60, s[12:13] nt
	v_cvt_pk_bf16_f32 v60, v62, v63
	s_nop 1
	v_mov_b32_dpp v61, v60 quad_perm:[1,0,3,2] row_mask:0xf bank_mask:0xf
	v_perm_b32 v60, v61, v60, v250
	v_add_u32_e32 v61, 0x41000, v158
	global_store_dword v61, v60, s[12:13] nt
	v_cvt_pk_bf16_f32 v60, v52, v53
	s_nop 1
	v_mov_b32_dpp v61, v60 quad_perm:[1,0,3,2] row_mask:0xf bank_mask:0xf
	v_perm_b32 v52, v61, v60, v250
	v_add_u32_e32 v53, 0x40020, v158
	global_store_dword v53, v52, s[12:13] nt
	v_cvt_pk_bf16_f32 v52, v54, v55
	s_nop 1
	v_mov_b32_dpp v53, v52 quad_perm:[1,0,3,2] row_mask:0xf bank_mask:0xf
	v_perm_b32 v52, v53, v52, v250
	v_add_u32_e32 v53, 0x41020, v158
	global_store_dword v53, v52, s[12:13] nt
	v_cvt_pk_bf16_f32 v52, v56, v57
	s_nop 1
	v_mov_b32_dpp v53, v52 quad_perm:[1,0,3,2] row_mask:0xf bank_mask:0xf
	v_perm_b32 v52, v53, v52, v250
	v_add_u32_e32 v53, 0x40100, v158
	global_store_dword v53, v52, s[12:13] nt
	v_cvt_pk_bf16_f32 v52, v58, v59
	s_nop 1
	v_mov_b32_dpp v53, v52 quad_perm:[1,0,3,2] row_mask:0xf bank_mask:0xf
	v_perm_b32 v52, v53, v52, v250
	v_add_u32_e32 v53, 0x41100, v158
	global_store_dword v53, v52, s[12:13] nt
	v_cvt_pk_bf16_f32 v52, v48, v49
	s_nop 1
	v_mov_b32_dpp v53, v52 quad_perm:[1,0,3,2] row_mask:0xf bank_mask:0xf
	v_perm_b32 v48, v53, v52, v250
	v_add_u32_e32 v49, 0x40120, v158
	global_store_dword v49, v48, s[12:13] nt
	v_cvt_pk_bf16_f32 v48, v50, v51
	s_nop 1
	v_mov_b32_dpp v49, v48 quad_perm:[1,0,3,2] row_mask:0xf bank_mask:0xf
	v_perm_b32 v48, v49, v48, v250
	v_add_u32_e32 v49, 0x41120, v158
	global_store_dword v49, v48, s[12:13] nt
	v_cvt_pk_bf16_f32 v48, v44, v45
	s_nop 1
	v_mov_b32_dpp v49, v48 quad_perm:[1,0,3,2] row_mask:0xf bank_mask:0xf
	v_perm_b32 v44, v49, v48, v250
	v_add_u32_e32 v45, 0x48000, v158
	global_store_dword v45, v44, s[12:13] nt
	v_cvt_pk_bf16_f32 v44, v46, v47
	s_nop 1
	v_mov_b32_dpp v45, v44 quad_perm:[1,0,3,2] row_mask:0xf bank_mask:0xf
	v_perm_b32 v44, v45, v44, v250
	v_add_u32_e32 v45, 0x49000, v158
	global_store_dword v45, v44, s[12:13] nt
	v_cvt_pk_bf16_f32 v44, v36, v37
	s_nop 1
	v_mov_b32_dpp v45, v44 quad_perm:[1,0,3,2] row_mask:0xf bank_mask:0xf
	v_perm_b32 v36, v45, v44, v250
	v_add_u32_e32 v37, 0x48020, v158
	global_store_dword v37, v36, s[12:13] nt
	v_cvt_pk_bf16_f32 v36, v38, v39
	s_nop 1
	v_mov_b32_dpp v37, v36 quad_perm:[1,0,3,2] row_mask:0xf bank_mask:0xf
	v_perm_b32 v36, v37, v36, v250
	v_add_u32_e32 v37, 0x49020, v158
	global_store_dword v37, v36, s[12:13] nt
	v_cvt_pk_bf16_f32 v36, v40, v41
	s_nop 1
	v_mov_b32_dpp v37, v36 quad_perm:[1,0,3,2] row_mask:0xf bank_mask:0xf
	v_perm_b32 v36, v37, v36, v250
	v_add_u32_e32 v37, 0x48100, v158
	global_store_dword v37, v36, s[12:13] nt
	v_cvt_pk_bf16_f32 v36, v42, v43
	s_nop 1
	v_mov_b32_dpp v37, v36 quad_perm:[1,0,3,2] row_mask:0xf bank_mask:0xf
	v_perm_b32 v36, v37, v36, v250
	v_add_u32_e32 v37, 0x49100, v158
	global_store_dword v37, v36, s[12:13] nt
	v_cvt_pk_bf16_f32 v36, v32, v33
	s_nop 1
	v_mov_b32_dpp v37, v36 quad_perm:[1,0,3,2] row_mask:0xf bank_mask:0xf
	v_perm_b32 v32, v37, v36, v250
	v_add_u32_e32 v33, 0x48120, v158
	global_store_dword v33, v32, s[12:13] nt
	v_cvt_pk_bf16_f32 v32, v34, v35
	s_nop 1
	v_mov_b32_dpp v33, v32 quad_perm:[1,0,3,2] row_mask:0xf bank_mask:0xf
	v_perm_b32 v32, v33, v32, v250
	v_add_u32_e32 v33, 0x49120, v158
	global_store_dword v33, v32, s[12:13] nt
	v_cvt_pk_bf16_f32 v32, v28, v29
	s_nop 1
	v_mov_b32_dpp v33, v32 quad_perm:[1,0,3,2] row_mask:0xf bank_mask:0xf
	v_perm_b32 v28, v33, v32, v250
	v_add_u32_e32 v29, 0x50000, v158
	global_store_dword v29, v28, s[12:13] nt
	v_cvt_pk_bf16_f32 v28, v30, v31
	s_nop 1
	v_mov_b32_dpp v29, v28 quad_perm:[1,0,3,2] row_mask:0xf bank_mask:0xf
	v_perm_b32 v28, v29, v28, v250
	v_add_u32_e32 v29, 0x51000, v158
	global_store_dword v29, v28, s[12:13] nt
	v_cvt_pk_bf16_f32 v28, v20, v21
	s_nop 1
	v_mov_b32_dpp v29, v28 quad_perm:[1,0,3,2] row_mask:0xf bank_mask:0xf
	v_perm_b32 v20, v29, v28, v250
	v_add_u32_e32 v21, 0x50020, v158
	global_store_dword v21, v20, s[12:13] nt
	v_cvt_pk_bf16_f32 v20, v22, v23
	s_nop 1
	v_mov_b32_dpp v21, v20 quad_perm:[1,0,3,2] row_mask:0xf bank_mask:0xf
	v_perm_b32 v20, v21, v20, v250
	v_add_u32_e32 v21, 0x51020, v158
	global_store_dword v21, v20, s[12:13] nt
	v_cvt_pk_bf16_f32 v20, v24, v25
	s_nop 1
	v_mov_b32_dpp v21, v20 quad_perm:[1,0,3,2] row_mask:0xf bank_mask:0xf
	v_perm_b32 v20, v21, v20, v250
	v_add_u32_e32 v21, 0x50100, v158
	global_store_dword v21, v20, s[12:13] nt
	v_cvt_pk_bf16_f32 v20, v26, v27
	s_nop 1
	v_mov_b32_dpp v21, v20 quad_perm:[1,0,3,2] row_mask:0xf bank_mask:0xf
	v_perm_b32 v20, v21, v20, v250
	v_add_u32_e32 v21, 0x51100, v158
	global_store_dword v21, v20, s[12:13] nt
	v_cvt_pk_bf16_f32 v20, v16, v17
	s_nop 1
	v_mov_b32_dpp v21, v20 quad_perm:[1,0,3,2] row_mask:0xf bank_mask:0xf
	v_perm_b32 v16, v21, v20, v250
	v_add_u32_e32 v17, 0x50120, v158
	global_store_dword v17, v16, s[12:13] nt
	v_cvt_pk_bf16_f32 v16, v18, v19
	s_nop 1
	v_mov_b32_dpp v17, v16 quad_perm:[1,0,3,2] row_mask:0xf bank_mask:0xf
	v_perm_b32 v16, v17, v16, v250
	v_add_u32_e32 v17, 0x51120, v158
	global_store_dword v17, v16, s[12:13] nt
	v_cvt_pk_bf16_f32 v16, v12, v13
	s_nop 1
	v_mov_b32_dpp v17, v16 quad_perm:[1,0,3,2] row_mask:0xf bank_mask:0xf
	v_perm_b32 v12, v17, v16, v250
	v_add_u32_e32 v13, 0x58000, v158
	global_store_dword v13, v12, s[12:13] nt
	v_cvt_pk_bf16_f32 v12, v14, v15
	s_nop 1
	v_mov_b32_dpp v13, v12 quad_perm:[1,0,3,2] row_mask:0xf bank_mask:0xf
	v_perm_b32 v12, v13, v12, v250
	v_add_u32_e32 v13, 0x59000, v158
	global_store_dword v13, v12, s[12:13] nt
	v_cvt_pk_bf16_f32 v12, v4, v5
	s_nop 1
	v_mov_b32_dpp v13, v12 quad_perm:[1,0,3,2] row_mask:0xf bank_mask:0xf
	v_perm_b32 v4, v13, v12, v250
	v_add_u32_e32 v5, 0x58020, v158
	global_store_dword v5, v4, s[12:13] nt
	v_cvt_pk_bf16_f32 v4, v6, v7
	s_nop 1
	v_mov_b32_dpp v5, v4 quad_perm:[1,0,3,2] row_mask:0xf bank_mask:0xf
	v_perm_b32 v4, v5, v4, v250
	v_add_u32_e32 v5, 0x59020, v158
	global_store_dword v5, v4, s[12:13] nt
	v_cvt_pk_bf16_f32 v4, v8, v9
	s_nop 1
	v_mov_b32_dpp v5, v4 quad_perm:[1,0,3,2] row_mask:0xf bank_mask:0xf
	v_perm_b32 v4, v5, v4, v250
	v_add_u32_e32 v5, 0x58100, v158
	global_store_dword v5, v4, s[12:13] nt
	v_cvt_pk_bf16_f32 v4, v10, v11
	s_nop 1
	v_mov_b32_dpp v5, v4 quad_perm:[1,0,3,2] row_mask:0xf bank_mask:0xf
	v_perm_b32 v4, v5, v4, v250
	v_add_u32_e32 v5, 0x59100, v158
	global_store_dword v5, v4, s[12:13] nt
	v_cvt_pk_bf16_f32 v4, v0, v1
	s_nop 1
	v_mov_b32_dpp v5, v4 quad_perm:[1,0,3,2] row_mask:0xf bank_mask:0xf
	v_perm_b32 v0, v5, v4, v250
	v_add_u32_e32 v1, 0x58120, v158
	global_store_dword v1, v0, s[12:13] nt
	v_cvt_pk_bf16_f32 v0, v2, v3
	s_nop 1
	v_mov_b32_dpp v1, v0 quad_perm:[1,0,3,2] row_mask:0xf bank_mask:0xf
	v_perm_b32 v0, v1, v0, v250
	v_add_u32_e32 v1, 0x59120, v158
	global_store_dword v1, v0, s[12:13] nt
	s_and_b64 vcc, exec, s[38:39]
	s_mov_b32 s18, s36
	s_mov_b32 s19, s37
	s_cbranch_vccnz .LBB0_87

.LBB0_95:
	v_pk_mul_f32 v[160:161], v[120:121], s[72:73] op_sel_hi:[1,0]
	v_add_u32_e32 v158, s76, v148
	v_exp_f32_e32 v160, v160
	v_exp_f32_e32 v161, v161
	s_movk_i32 s18, 0xb00
	v_mul_lo_u32 v158, v158, s18
	s_lshr_b32 s18, s78, 1
	v_pk_add_f32 v[160:161], v[160:161], 1.0 op_sel_hi:[1,0]
	v_or_b32_e32 v159, s18, v149
	v_rcp_f32_e32 v160, v160
	v_rcp_f32_e32 v161, v161
	v_add_lshl_u32 v158, v159, v158, 1
	v_pk_mul_f32 v[120:121], v[120:121], v[160:161]
	s_nop 0
	v_pk_mul_f32 v[120:121], v[120:121], v[124:125]
	v_cvt_pk_bf16_f32 v124, v120, v121
	s_nop 1
	v_mov_b32_dpp v125, v124 quad_perm:[1,0,3,2] row_mask:0xf bank_mask:0xf
	v_perm_b32 v120, v125, v124, v250
	global_store_dword v158, v120, s[14:15] nt
	v_pk_mul_f32 v[120:121], v[122:123], s[72:73] op_sel_hi:[1,0]
	s_nop 0
	v_exp_f32_e32 v120, v120
	v_exp_f32_e32 v121, v121
	s_nop 0
	v_pk_add_f32 v[120:121], v[120:121], 1.0 op_sel_hi:[1,0]
	s_nop 0
	v_rcp_f32_e32 v120, v120
	v_rcp_f32_e32 v121, v121
	s_nop 0
	v_pk_mul_f32 v[120:121], v[122:123], v[120:121]
	s_nop 0
	v_pk_mul_f32 v[120:121], v[120:121], v[126:127]
	v_cvt_pk_bf16_f32 v122, v120, v121
	s_nop 1
	v_mov_b32_dpp v123, v122 quad_perm:[1,0,3,2] row_mask:0xf bank_mask:0xf
	v_perm_b32 v120, v123, v122, v250
	v_add_u32_e32 v121, 0x2c00, v158
	global_store_dword v121, v120, s[14:15] nt
	v_pk_mul_f32 v[120:121], v[112:113], s[72:73] op_sel_hi:[1,0]
	v_or_b32_e32 v122, 32, v158
	v_exp_f32_e32 v120, v120
	v_exp_f32_e32 v121, v121
	s_nop 0
	v_pk_add_f32 v[120:121], v[120:121], 1.0 op_sel_hi:[1,0]
	s_nop 0
	v_rcp_f32_e32 v120, v120
	v_rcp_f32_e32 v121, v121
	s_nop 0
	v_pk_mul_f32 v[112:113], v[112:113], v[120:121]
	s_nop 0
	v_pk_mul_f32 v[112:113], v[112:113], v[116:117]
	v_cvt_pk_bf16_f32 v116, v112, v113
	s_nop 1
	v_mov_b32_dpp v117, v116 quad_perm:[1,0,3,2] row_mask:0xf bank_mask:0xf
	v_perm_b32 v112, v117, v116, v250
	global_store_dword v122, v112, s[14:15] nt
	v_pk_mul_f32 v[112:113], v[114:115], s[72:73] op_sel_hi:[1,0]
	s_nop 0
	v_exp_f32_e32 v112, v112
	v_exp_f32_e32 v113, v113
	s_nop 0
	v_pk_add_f32 v[112:113], v[112:113], 1.0 op_sel_hi:[1,0]
	s_nop 0
	v_rcp_f32_e32 v112, v112
	v_rcp_f32_e32 v113, v113
	s_nop 0
	v_pk_mul_f32 v[112:113], v[114:115], v[112:113]
	s_nop 0
	v_pk_mul_f32 v[112:113], v[112:113], v[118:119]
	v_cvt_pk_bf16_f32 v114, v112, v113
	s_nop 1
	v_mov_b32_dpp v115, v114 quad_perm:[1,0,3,2] row_mask:0xf bank_mask:0xf
	v_perm_b32 v112, v115, v114, v250
	v_add_u32_e32 v113, 0x2c20, v158
	global_store_dword v113, v112, s[14:15] nt
	v_pk_mul_f32 v[112:113], v[104:105], s[72:73] op_sel_hi:[1,0]
	s_nop 0
	v_exp_f32_e32 v112, v112
	v_exp_f32_e32 v113, v113
	s_nop 0
	v_pk_add_f32 v[112:113], v[112:113], 1.0 op_sel_hi:[1,0]
	s_nop 0
	v_rcp_f32_e32 v112, v112
	v_rcp_f32_e32 v113, v113
	s_nop 0
	v_pk_mul_f32 v[104:105], v[104:105], v[112:113]
	s_nop 0
	v_pk_mul_f32 v[104:105], v[104:105], v[108:109]
	v_cvt_pk_bf16_f32 v108, v104, v105
	s_nop 1
	v_mov_b32_dpp v109, v108 quad_perm:[1,0,3,2] row_mask:0xf bank_mask:0xf
	v_perm_b32 v104, v109, v108, v250
	v_add_u32_e32 v105, 0x16000, v158
	global_store_dword v105, v104, s[14:15] nt
	v_pk_mul_f32 v[104:105], v[106:107], s[72:73] op_sel_hi:[1,0]
	s_nop 0
	v_exp_f32_e32 v104, v104
	v_exp_f32_e32 v105, v105
	s_nop 0
	v_pk_add_f32 v[104:105], v[104:105], 1.0 op_sel_hi:[1,0]
	s_nop 0
	v_rcp_f32_e32 v104, v104
	v_rcp_f32_e32 v105, v105
	s_nop 0
	v_pk_mul_f32 v[104:105], v[106:107], v[104:105]
	s_nop 0
	v_pk_mul_f32 v[104:105], v[104:105], v[110:111]
	v_cvt_pk_bf16_f32 v106, v104, v105
	s_nop 1
	v_mov_b32_dpp v107, v106 quad_perm:[1,0,3,2] row_mask:0xf bank_mask:0xf
	v_perm_b32 v104, v107, v106, v250
	v_add_u32_e32 v105, 0x18c00, v158
	global_store_dword v105, v104, s[14:15] nt
	v_pk_mul_f32 v[104:105], v[96:97], s[72:73] op_sel_hi:[1,0]
	s_nop 0
	v_exp_f32_e32 v104, v104
	v_exp_f32_e32 v105, v105
	s_nop 0
	v_pk_add_f32 v[104:105], v[104:105], 1.0 op_sel_hi:[1,0]
	s_nop 0
	v_rcp_f32_e32 v104, v104
	v_rcp_f32_e32 v105, v105
	s_nop 0
	v_pk_mul_f32 v[96:97], v[96:97], v[104:105]
	s_nop 0
	v_pk_mul_f32 v[96:97], v[96:97], v[100:101]
	v_cvt_pk_bf16_f32 v100, v96, v97
	s_nop 1
	v_mov_b32_dpp v101, v100 quad_perm:[1,0,3,2] row_mask:0xf bank_mask:0xf
	v_perm_b32 v96, v101, v100, v250
	v_add_u32_e32 v97, 0x16020, v158
	global_store_dword v97, v96, s[14:15] nt
	v_pk_mul_f32 v[96:97], v[98:99], s[72:73] op_sel_hi:[1,0]
	s_nop 0
	v_exp_f32_e32 v96, v96
	v_exp_f32_e32 v97, v97
	s_nop 0
	v_pk_add_f32 v[96:97], v[96:97], 1.0 op_sel_hi:[1,0]
	s_nop 0
	v_rcp_f32_e32 v96, v96
	v_rcp_f32_e32 v97, v97
	s_nop 0
	v_pk_mul_f32 v[96:97], v[98:99], v[96:97]
	s_nop 0
	v_pk_mul_f32 v[96:97], v[96:97], v[102:103]
	v_cvt_pk_bf16_f32 v98, v96, v97
	s_nop 1
	v_mov_b32_dpp v99, v98 quad_perm:[1,0,3,2] row_mask:0xf bank_mask:0xf
	v_perm_b32 v96, v99, v98, v250
	v_add_u32_e32 v97, 0x18c20, v158
	global_store_dword v97, v96, s[14:15] nt
	v_pk_mul_f32 v[96:97], v[88:89], s[72:73] op_sel_hi:[1,0]
	s_nop 0
	v_exp_f32_e32 v96, v96
	v_exp_f32_e32 v97, v97
	s_nop 0
	v_pk_add_f32 v[96:97], v[96:97], 1.0 op_sel_hi:[1,0]
	s_nop 0
	v_rcp_f32_e32 v96, v96
	v_rcp_f32_e32 v97, v97
	s_nop 0
	v_pk_mul_f32 v[88:89], v[88:89], v[96:97]
	s_nop 0
	v_pk_mul_f32 v[88:89], v[88:89], v[92:93]
	v_cvt_pk_bf16_f32 v92, v88, v89
	s_nop 1
	v_mov_b32_dpp v93, v92 quad_perm:[1,0,3,2] row_mask:0xf bank_mask:0xf
	v_perm_b32 v88, v93, v92, v250
	v_add_u32_e32 v89, 0x2c000, v158
	global_store_dword v89, v88, s[14:15] nt
	v_pk_mul_f32 v[88:89], v[90:91], s[72:73] op_sel_hi:[1,0]
	s_nop 0
	v_exp_f32_e32 v88, v88
	v_exp_f32_e32 v89, v89
	s_nop 0
	v_pk_add_f32 v[88:89], v[88:89], 1.0 op_sel_hi:[1,0]
	s_nop 0
	v_rcp_f32_e32 v88, v88
	v_rcp_f32_e32 v89, v89
	s_nop 0
	v_pk_mul_f32 v[88:89], v[90:91], v[88:89]
	s_nop 0
	v_pk_mul_f32 v[88:89], v[88:89], v[94:95]
	v_cvt_pk_bf16_f32 v90, v88, v89
	s_nop 1
	v_mov_b32_dpp v91, v90 quad_perm:[1,0,3,2] row_mask:0xf bank_mask:0xf
	v_perm_b32 v88, v91, v90, v250
	v_add_u32_e32 v89, 0x2ec00, v158
	global_store_dword v89, v88, s[14:15] nt
	v_pk_mul_f32 v[88:89], v[80:81], s[72:73] op_sel_hi:[1,0]
	s_nop 0
	v_exp_f32_e32 v88, v88
	v_exp_f32_e32 v89, v89
	s_nop 0
	v_pk_add_f32 v[88:89], v[88:89], 1.0 op_sel_hi:[1,0]
	s_nop 0
	v_rcp_f32_e32 v88, v88
	v_rcp_f32_e32 v89, v89
	s_nop 0
	v_pk_mul_f32 v[80:81], v[80:81], v[88:89]
	s_nop 0
	v_pk_mul_f32 v[80:81], v[80:81], v[84:85]
	v_cvt_pk_bf16_f32 v84, v80, v81
	s_nop 1
	v_mov_b32_dpp v85, v84 quad_perm:[1,0,3,2] row_mask:0xf bank_mask:0xf
	v_perm_b32 v80, v85, v84, v250
	v_add_u32_e32 v81, 0x2c020, v158
	global_store_dword v81, v80, s[14:15] nt
	v_pk_mul_f32 v[80:81], v[82:83], s[72:73] op_sel_hi:[1,0]
	s_nop 0
	v_exp_f32_e32 v80, v80
	v_exp_f32_e32 v81, v81
	s_nop 0
	v_pk_add_f32 v[80:81], v[80:81], 1.0 op_sel_hi:[1,0]
	s_nop 0
	v_rcp_f32_e32 v80, v80
	v_rcp_f32_e32 v81, v81
	s_nop 0
	v_pk_mul_f32 v[80:81], v[82:83], v[80:81]
	s_nop 0
	v_pk_mul_f32 v[80:81], v[80:81], v[86:87]
	v_cvt_pk_bf16_f32 v82, v80, v81
	s_nop 1
	v_mov_b32_dpp v83, v82 quad_perm:[1,0,3,2] row_mask:0xf bank_mask:0xf
	v_perm_b32 v80, v83, v82, v250
	v_add_u32_e32 v81, 0x2ec20, v158
	global_store_dword v81, v80, s[14:15] nt
	v_pk_mul_f32 v[80:81], v[72:73], s[72:73] op_sel_hi:[1,0]
	s_nop 0
	v_exp_f32_e32 v80, v80
	v_exp_f32_e32 v81, v81
	s_nop 0
	v_pk_add_f32 v[80:81], v[80:81], 1.0 op_sel_hi:[1,0]
	s_nop 0
	v_rcp_f32_e32 v80, v80
	v_rcp_f32_e32 v81, v81
	s_nop 0
	v_pk_mul_f32 v[72:73], v[72:73], v[80:81]
	s_nop 0
	v_pk_mul_f32 v[72:73], v[72:73], v[76:77]
	v_cvt_pk_bf16_f32 v76, v72, v73
	s_nop 1
	v_mov_b32_dpp v77, v76 quad_perm:[1,0,3,2] row_mask:0xf bank_mask:0xf
	v_perm_b32 v72, v77, v76, v250
	v_add_u32_e32 v73, 0x42000, v158
	global_store_dword v73, v72, s[14:15] nt
	v_pk_mul_f32 v[72:73], v[74:75], s[72:73] op_sel_hi:[1,0]
	s_nop 0
	v_exp_f32_e32 v72, v72
	v_exp_f32_e32 v73, v73
	s_nop 0
	v_pk_add_f32 v[72:73], v[72:73], 1.0 op_sel_hi:[1,0]
	s_nop 0
	v_rcp_f32_e32 v72, v72
	v_rcp_f32_e32 v73, v73
	s_nop 0
	v_pk_mul_f32 v[72:73], v[74:75], v[72:73]
	s_nop 0
	v_pk_mul_f32 v[72:73], v[72:73], v[78:79]
	v_cvt_pk_bf16_f32 v74, v72, v73
	s_nop 1
	v_mov_b32_dpp v75, v74 quad_perm:[1,0,3,2] row_mask:0xf bank_mask:0xf
	v_perm_b32 v72, v75, v74, v250
	v_add_u32_e32 v73, 0x44c00, v158
	global_store_dword v73, v72, s[14:15] nt
	v_pk_mul_f32 v[72:73], v[64:65], s[72:73] op_sel_hi:[1,0]
	s_nop 0
	v_exp_f32_e32 v72, v72
	v_exp_f32_e32 v73, v73
	s_nop 0
	v_pk_add_f32 v[72:73], v[72:73], 1.0 op_sel_hi:[1,0]
	s_nop 0
	v_rcp_f32_e32 v72, v72
	v_rcp_f32_e32 v73, v73
	s_nop 0
	v_pk_mul_f32 v[64:65], v[64:65], v[72:73]
	s_nop 0
	v_pk_mul_f32 v[64:65], v[64:65], v[68:69]
	v_cvt_pk_bf16_f32 v68, v64, v65
	s_nop 1
	v_mov_b32_dpp v69, v68 quad_perm:[1,0,3,2] row_mask:0xf bank_mask:0xf
	v_perm_b32 v64, v69, v68, v250
	v_add_u32_e32 v65, 0x42020, v158
	global_store_dword v65, v64, s[14:15] nt
	v_pk_mul_f32 v[64:65], v[66:67], s[72:73] op_sel_hi:[1,0]
	s_nop 0
	v_exp_f32_e32 v64, v64
	v_exp_f32_e32 v65, v65
	s_nop 0
	v_pk_add_f32 v[64:65], v[64:65], 1.0 op_sel_hi:[1,0]
	s_nop 0
	v_rcp_f32_e32 v64, v64
	v_rcp_f32_e32 v65, v65
	s_nop 0
	v_pk_mul_f32 v[64:65], v[66:67], v[64:65]
	s_nop 0
	v_pk_mul_f32 v[64:65], v[64:65], v[70:71]
	v_cvt_pk_bf16_f32 v66, v64, v65
	s_nop 1
	v_mov_b32_dpp v67, v66 quad_perm:[1,0,3,2] row_mask:0xf bank_mask:0xf
	v_perm_b32 v64, v67, v66, v250
	v_add_u32_e32 v65, 0x44c20, v158
	global_store_dword v65, v64, s[14:15] nt
	v_pk_mul_f32 v[64:65], v[56:57], s[72:73] op_sel_hi:[1,0]
	s_nop 0
	v_exp_f32_e32 v64, v64
	v_exp_f32_e32 v65, v65
	s_nop 0
	v_pk_add_f32 v[64:65], v[64:65], 1.0 op_sel_hi:[1,0]
	s_nop 0
	v_rcp_f32_e32 v64, v64
	v_rcp_f32_e32 v65, v65
	s_nop 0
	v_pk_mul_f32 v[56:57], v[56:57], v[64:65]
	s_nop 0
	v_pk_mul_f32 v[56:57], v[56:57], v[60:61]
	v_cvt_pk_bf16_f32 v60, v56, v57
	s_nop 1
	v_mov_b32_dpp v61, v60 quad_perm:[1,0,3,2] row_mask:0xf bank_mask:0xf
	v_perm_b32 v56, v61, v60, v250
	v_add_u32_e32 v57, 0xb0000, v158
	global_store_dword v57, v56, s[14:15] nt
	v_pk_mul_f32 v[56:57], v[58:59], s[72:73] op_sel_hi:[1,0]
	s_nop 0
	v_exp_f32_e32 v56, v56
	v_exp_f32_e32 v57, v57
	s_nop 0
	v_pk_add_f32 v[56:57], v[56:57], 1.0 op_sel_hi:[1,0]
	s_nop 0
	v_rcp_f32_e32 v56, v56
	v_rcp_f32_e32 v57, v57
	s_nop 0
	v_pk_mul_f32 v[56:57], v[58:59], v[56:57]
	s_nop 0
	v_pk_mul_f32 v[56:57], v[56:57], v[62:63]
	v_cvt_pk_bf16_f32 v58, v56, v57
	s_nop 1
	v_mov_b32_dpp v59, v58 quad_perm:[1,0,3,2] row_mask:0xf bank_mask:0xf
	v_perm_b32 v56, v59, v58, v250
	v_add_u32_e32 v57, 0xb2c00, v158
	global_store_dword v57, v56, s[14:15] nt
	v_pk_mul_f32 v[56:57], v[48:49], s[72:73] op_sel_hi:[1,0]
	s_nop 0
	v_exp_f32_e32 v56, v56
	v_exp_f32_e32 v57, v57
	s_nop 0
	v_pk_add_f32 v[56:57], v[56:57], 1.0 op_sel_hi:[1,0]
	s_nop 0
	v_rcp_f32_e32 v56, v56
	v_rcp_f32_e32 v57, v57
	s_nop 0
	v_pk_mul_f32 v[48:49], v[48:49], v[56:57]
	s_nop 0
	v_pk_mul_f32 v[48:49], v[48:49], v[52:53]
	v_cvt_pk_bf16_f32 v52, v48, v49
	s_nop 1
	v_mov_b32_dpp v53, v52 quad_perm:[1,0,3,2] row_mask:0xf bank_mask:0xf
	v_perm_b32 v48, v53, v52, v250
	v_add_u32_e32 v49, 0xb0020, v158
	global_store_dword v49, v48, s[14:15] nt
	v_pk_mul_f32 v[48:49], v[50:51], s[72:73] op_sel_hi:[1,0]
	s_nop 0
	v_exp_f32_e32 v48, v48
	v_exp_f32_e32 v49, v49
	s_nop 0
	v_pk_add_f32 v[48:49], v[48:49], 1.0 op_sel_hi:[1,0]
	s_nop 0
	v_rcp_f32_e32 v48, v48
	v_rcp_f32_e32 v49, v49
	s_nop 0
	v_pk_mul_f32 v[48:49], v[50:51], v[48:49]
	s_nop 0
	v_pk_mul_f32 v[48:49], v[48:49], v[54:55]
	v_cvt_pk_bf16_f32 v50, v48, v49
	s_nop 1
	v_mov_b32_dpp v51, v50 quad_perm:[1,0,3,2] row_mask:0xf bank_mask:0xf
	v_perm_b32 v48, v51, v50, v250
	v_add_u32_e32 v49, 0xb2c20, v158
	global_store_dword v49, v48, s[14:15] nt
	v_pk_mul_f32 v[48:49], v[40:41], s[72:73] op_sel_hi:[1,0]
	s_nop 0
	v_exp_f32_e32 v48, v48
	v_exp_f32_e32 v49, v49
	s_nop 0
	v_pk_add_f32 v[48:49], v[48:49], 1.0 op_sel_hi:[1,0]
	s_nop 0
	v_rcp_f32_e32 v48, v48
	v_rcp_f32_e32 v49, v49
	s_nop 0
	v_pk_mul_f32 v[40:41], v[40:41], v[48:49]
	s_nop 0
	v_pk_mul_f32 v[40:41], v[40:41], v[44:45]
	v_cvt_pk_bf16_f32 v44, v40, v41
	s_nop 1
	v_mov_b32_dpp v45, v44 quad_perm:[1,0,3,2] row_mask:0xf bank_mask:0xf
	v_perm_b32 v40, v45, v44, v250
	v_add_u32_e32 v41, 0xc6000, v158
	global_store_dword v41, v40, s[14:15] nt
	v_pk_mul_f32 v[40:41], v[42:43], s[72:73] op_sel_hi:[1,0]
	s_nop 0
	v_exp_f32_e32 v40, v40
	v_exp_f32_e32 v41, v41
	s_nop 0
	v_pk_add_f32 v[40:41], v[40:41], 1.0 op_sel_hi:[1,0]
	s_nop 0
	v_rcp_f32_e32 v40, v40
	v_rcp_f32_e32 v41, v41
	s_nop 0
	v_pk_mul_f32 v[40:41], v[42:43], v[40:41]
	s_nop 0
	v_pk_mul_f32 v[40:41], v[40:41], v[46:47]
	v_cvt_pk_bf16_f32 v42, v40, v41
	s_nop 1
	v_mov_b32_dpp v43, v42 quad_perm:[1,0,3,2] row_mask:0xf bank_mask:0xf
	v_perm_b32 v40, v43, v42, v250
	v_add_u32_e32 v41, 0xc8c00, v158
	global_store_dword v41, v40, s[14:15] nt
	v_pk_mul_f32 v[40:41], v[32:33], s[72:73] op_sel_hi:[1,0]
	s_nop 0
	v_exp_f32_e32 v40, v40
	v_exp_f32_e32 v41, v41
	s_nop 0
	v_pk_add_f32 v[40:41], v[40:41], 1.0 op_sel_hi:[1,0]
	s_nop 0
	v_rcp_f32_e32 v40, v40
	v_rcp_f32_e32 v41, v41
	s_nop 0
	v_pk_mul_f32 v[32:33], v[32:33], v[40:41]
	s_nop 0
	v_pk_mul_f32 v[32:33], v[32:33], v[36:37]
	v_cvt_pk_bf16_f32 v36, v32, v33
	s_nop 1
	v_mov_b32_dpp v37, v36 quad_perm:[1,0,3,2] row_mask:0xf bank_mask:0xf
	v_perm_b32 v32, v37, v36, v250
	v_add_u32_e32 v33, 0xc6020, v158
	global_store_dword v33, v32, s[14:15] nt
	v_pk_mul_f32 v[32:33], v[34:35], s[72:73] op_sel_hi:[1,0]
	s_nop 0
	v_exp_f32_e32 v32, v32
	v_exp_f32_e32 v33, v33
	s_nop 0
	v_pk_add_f32 v[32:33], v[32:33], 1.0 op_sel_hi:[1,0]
	s_nop 0
	v_rcp_f32_e32 v32, v32
	v_rcp_f32_e32 v33, v33
	s_nop 0
	v_pk_mul_f32 v[32:33], v[34:35], v[32:33]
	s_nop 0
	v_pk_mul_f32 v[32:33], v[32:33], v[38:39]
	v_cvt_pk_bf16_f32 v34, v32, v33
	s_nop 1
	v_mov_b32_dpp v35, v34 quad_perm:[1,0,3,2] row_mask:0xf bank_mask:0xf
	v_perm_b32 v32, v35, v34, v250
	v_add_u32_e32 v33, 0xc8c20, v158
	global_store_dword v33, v32, s[14:15] nt
	v_pk_mul_f32 v[32:33], v[24:25], s[72:73] op_sel_hi:[1,0]
	s_nop 0
	v_exp_f32_e32 v32, v32
	v_exp_f32_e32 v33, v33
	s_nop 0
	v_pk_add_f32 v[32:33], v[32:33], 1.0 op_sel_hi:[1,0]
	s_nop 0
	v_rcp_f32_e32 v32, v32
	v_rcp_f32_e32 v33, v33
	s_nop 0
	v_pk_mul_f32 v[24:25], v[24:25], v[32:33]
	s_nop 0
	v_pk_mul_f32 v[24:25], v[24:25], v[28:29]
	v_cvt_pk_bf16_f32 v28, v24, v25
	s_nop 1
	v_mov_b32_dpp v29, v28 quad_perm:[1,0,3,2] row_mask:0xf bank_mask:0xf
	v_perm_b32 v24, v29, v28, v250
	v_add_u32_e32 v25, 0xdc000, v158
	global_store_dword v25, v24, s[14:15] nt
	v_pk_mul_f32 v[24:25], v[26:27], s[72:73] op_sel_hi:[1,0]
	s_nop 0
	v_exp_f32_e32 v24, v24
	v_exp_f32_e32 v25, v25
	s_nop 0
	v_pk_add_f32 v[24:25], v[24:25], 1.0 op_sel_hi:[1,0]
	s_nop 0
	v_rcp_f32_e32 v24, v24
	v_rcp_f32_e32 v25, v25
	s_nop 0
	v_pk_mul_f32 v[24:25], v[26:27], v[24:25]
	s_nop 0
	v_pk_mul_f32 v[24:25], v[24:25], v[30:31]
	v_cvt_pk_bf16_f32 v26, v24, v25
	s_nop 1
	v_mov_b32_dpp v27, v26 quad_perm:[1,0,3,2] row_mask:0xf bank_mask:0xf
	v_perm_b32 v24, v27, v26, v250
	v_add_u32_e32 v25, 0xdec00, v158
	global_store_dword v25, v24, s[14:15] nt
	v_pk_mul_f32 v[24:25], v[16:17], s[72:73] op_sel_hi:[1,0]
	s_nop 0
	v_exp_f32_e32 v24, v24
	v_exp_f32_e32 v25, v25
	s_nop 0
	v_pk_add_f32 v[24:25], v[24:25], 1.0 op_sel_hi:[1,0]
	s_nop 0
	v_rcp_f32_e32 v24, v24
	v_rcp_f32_e32 v25, v25
	s_nop 0
	v_pk_mul_f32 v[16:17], v[16:17], v[24:25]
	s_nop 0
	v_pk_mul_f32 v[16:17], v[16:17], v[20:21]
	v_cvt_pk_bf16_f32 v20, v16, v17
	s_nop 1
	v_mov_b32_dpp v21, v20 quad_perm:[1,0,3,2] row_mask:0xf bank_mask:0xf
	v_perm_b32 v16, v21, v20, v250
	v_add_u32_e32 v17, 0xdc020, v158
	global_store_dword v17, v16, s[14:15] nt
	v_pk_mul_f32 v[16:17], v[18:19], s[72:73] op_sel_hi:[1,0]
	s_nop 0
	v_exp_f32_e32 v16, v16
	v_exp_f32_e32 v17, v17
	s_nop 0
	v_pk_add_f32 v[16:17], v[16:17], 1.0 op_sel_hi:[1,0]
	s_nop 0
	v_rcp_f32_e32 v16, v16
	v_rcp_f32_e32 v17, v17
	s_nop 0
	v_pk_mul_f32 v[16:17], v[18:19], v[16:17]
	s_nop 0
	v_pk_mul_f32 v[16:17], v[16:17], v[22:23]
	v_cvt_pk_bf16_f32 v18, v16, v17
	s_nop 1
	v_mov_b32_dpp v19, v18 quad_perm:[1,0,3,2] row_mask:0xf bank_mask:0xf
	v_perm_b32 v16, v19, v18, v250
	v_add_u32_e32 v17, 0xdec20, v158
	global_store_dword v17, v16, s[14:15] nt
	v_pk_mul_f32 v[16:17], v[8:9], s[72:73] op_sel_hi:[1,0]
	s_nop 0
	v_exp_f32_e32 v16, v16
	v_exp_f32_e32 v17, v17
	s_nop 0
	v_pk_add_f32 v[16:17], v[16:17], 1.0 op_sel_hi:[1,0]
	s_nop 0
	v_rcp_f32_e32 v16, v16
	v_rcp_f32_e32 v17, v17
	s_nop 0
	v_pk_mul_f32 v[8:9], v[8:9], v[16:17]
	s_nop 0
	v_pk_mul_f32 v[8:9], v[8:9], v[12:13]
	v_cvt_pk_bf16_f32 v12, v8, v9
	s_nop 1
	v_mov_b32_dpp v13, v12 quad_perm:[1,0,3,2] row_mask:0xf bank_mask:0xf
	v_perm_b32 v8, v13, v12, v250
	v_add_u32_e32 v9, 0xf2000, v158
	global_store_dword v9, v8, s[14:15] nt
	v_pk_mul_f32 v[8:9], v[10:11], s[72:73] op_sel_hi:[1,0]
	s_nop 0
	v_exp_f32_e32 v8, v8
	v_exp_f32_e32 v9, v9
	s_nop 0
	v_pk_add_f32 v[8:9], v[8:9], 1.0 op_sel_hi:[1,0]
	s_nop 0
	v_rcp_f32_e32 v8, v8
	v_rcp_f32_e32 v9, v9
	s_nop 0
	v_pk_mul_f32 v[8:9], v[10:11], v[8:9]
	s_nop 0
	v_pk_mul_f32 v[8:9], v[8:9], v[14:15]
	v_cvt_pk_bf16_f32 v10, v8, v9
	s_nop 1
	v_mov_b32_dpp v11, v10 quad_perm:[1,0,3,2] row_mask:0xf bank_mask:0xf
	v_perm_b32 v8, v11, v10, v250
	v_add_u32_e32 v9, 0xf4c00, v158
	global_store_dword v9, v8, s[14:15] nt
	v_pk_mul_f32 v[8:9], v[0:1], s[72:73] op_sel_hi:[1,0]
	s_nop 0
	v_exp_f32_e32 v8, v8
	v_exp_f32_e32 v9, v9
	s_nop 0
	v_pk_add_f32 v[8:9], v[8:9], 1.0 op_sel_hi:[1,0]
	s_nop 0
	v_rcp_f32_e32 v8, v8
	v_rcp_f32_e32 v9, v9
	s_nop 0
	v_pk_mul_f32 v[0:1], v[0:1], v[8:9]
	s_nop 0
	v_pk_mul_f32 v[0:1], v[0:1], v[4:5]
	v_cvt_pk_bf16_f32 v4, v0, v1
	s_nop 1
	v_mov_b32_dpp v5, v4 quad_perm:[1,0,3,2] row_mask:0xf bank_mask:0xf
	v_perm_b32 v0, v5, v4, v250
	v_add_u32_e32 v1, 0xf2020, v158
	global_store_dword v1, v0, s[14:15] nt
	v_pk_mul_f32 v[0:1], v[2:3], s[72:73] op_sel_hi:[1,0]
	s_nop 0
	v_exp_f32_e32 v0, v0
	v_exp_f32_e32 v1, v1
	s_nop 0
	v_pk_add_f32 v[0:1], v[0:1], 1.0 op_sel_hi:[1,0]
	s_nop 0
	v_rcp_f32_e32 v0, v0
	v_rcp_f32_e32 v1, v1
	s_nop 0
	v_pk_mul_f32 v[0:1], v[2:3], v[0:1]
	s_nop 0
	v_pk_mul_f32 v[0:1], v[0:1], v[6:7]
	v_cvt_pk_bf16_f32 v2, v0, v1
	s_nop 1
	v_mov_b32_dpp v3, v2 quad_perm:[1,0,3,2] row_mask:0xf bank_mask:0xf
	v_perm_b32 v0, v3, v2, v250
	v_add_u32_e32 v1, 0xf4c20, v158
	global_store_dword v1, v0, s[14:15] nt
	s_and_b64 vcc, exec, s[38:39]
	s_mov_b32 s76, s40
	s_mov_b32 s78, s42
	s_cbranch_vccnz .LBB0_104

.LBB0_131:
	v_or_b32_e32 v158, s80, v149
	v_add_lshl_u32 v159, v148, s19, 11
	v_lshl_add_u32 v158, v158, 1, v159
	v_cvt_pk_bf16_f32 v159, v124, v125
	s_nop 1
	v_mov_b32_dpp v160, v159 quad_perm:[1,0,3,2] row_mask:0xf bank_mask:0xf
	v_perm_b32 v124, v160, v159, v250
	global_store_dword v158, v124, s[12:13] nt
	v_cvt_pk_bf16_f32 v124, v126, v127
	s_nop 1
	v_mov_b32_dpp v125, v124 quad_perm:[1,0,3,2] row_mask:0xf bank_mask:0xf
	v_perm_b32 v124, v125, v124, v250
	v_add_u32_e32 v125, 0x1000, v158
	global_store_dword v125, v124, s[12:13] nt
	v_cndmask_b32_e64 v125, v116, v117, s[10:11]
	v_mov_b32_e32 v126, v129
	v_or_b32_e32 v124, 32, v158
	s_nop 0
	v_mov_b32_dpp v126, v125 quad_perm:[1,0,3,2] row_mask:0xf bank_mask:0xf
	v_cndmask_b32_e64 v116, v126, v116, s[10:11]
	v_cndmask_b32_e64 v117, v117, v126, s[10:11]
	v_cvt_pk_bf16_f32 v116, v116, v117
	global_store_dword v124, v116, s[12:13] nt
	v_cvt_pk_bf16_f32 v116, v118, v119
	s_nop 1
	v_mov_b32_dpp v117, v116 quad_perm:[1,0,3,2] row_mask:0xf bank_mask:0xf
	v_perm_b32 v116, v117, v116, v250
	v_add_u32_e32 v117, 0x1020, v158
	global_store_dword v117, v116, s[12:13] nt
	v_cndmask_b32_e64 v117, v120, v121, s[10:11]
	v_mov_b32_e32 v118, v129
	v_or_b32_e32 v116, 0x100, v158
	s_nop 0
	v_mov_b32_dpp v118, v117 quad_perm:[1,0,3,2] row_mask:0xf bank_mask:0xf
	v_cndmask_b32_e64 v117, v118, v120, s[10:11]
	v_cndmask_b32_e64 v118, v121, v118, s[10:11]
	v_cvt_pk_bf16_f32 v117, v117, v118
	global_store_dword v116, v117, s[12:13] nt
	v_cndmask_b32_e64 v116, v122, v123, s[10:11]
	v_mov_b32_e32 v117, v129
	v_mov_b32_e32 v118, v129
	s_nop 0
	v_mov_b32_dpp v117, v116 quad_perm:[1,0,3,2] row_mask:0xf bank_mask:0xf
	v_cndmask_b32_e64 v116, v117, v122, s[10:11]
	v_cndmask_b32_e64 v117, v123, v117, s[10:11]
	v_cvt_pk_bf16_f32 v116, v116, v117
	v_add_u32_e32 v117, 0x1100, v158
	global_store_dword v117, v116, s[12:13] nt
	v_cndmask_b32_e64 v117, v112, v113, s[10:11]
	v_or_b32_e32 v116, 0x120, v158
	s_nop 0
	v_mov_b32_dpp v118, v117 quad_perm:[1,0,3,2] row_mask:0xf bank_mask:0xf
	v_cndmask_b32_e64 v112, v118, v112, s[10:11]
	v_cndmask_b32_e64 v113, v113, v118, s[10:11]
	v_cvt_pk_bf16_f32 v112, v112, v113
	global_store_dword v116, v112, s[12:13] nt
	v_cvt_pk_bf16_f32 v112, v114, v115
	s_nop 1
	v_mov_b32_dpp v113, v112 quad_perm:[1,0,3,2] row_mask:0xf bank_mask:0xf
	v_perm_b32 v112, v113, v112, v250
	v_add_u32_e32 v113, 0x1120, v158
	global_store_dword v113, v112, s[12:13] nt
	v_cvt_pk_bf16_f32 v112, v108, v109
	s_nop 1
	v_mov_b32_dpp v113, v112 quad_perm:[1,0,3,2] row_mask:0xf bank_mask:0xf
	v_perm_b32 v108, v113, v112, v250
	v_add_u32_e32 v109, 0x8000, v158
	global_store_dword v109, v108, s[12:13] nt
	v_cvt_pk_bf16_f32 v108, v110, v111
	s_nop 1
	v_mov_b32_dpp v109, v108 quad_perm:[1,0,3,2] row_mask:0xf bank_mask:0xf
	v_perm_b32 v108, v109, v108, v250
	v_add_u32_e32 v109, 0x9000, v158
	global_store_dword v109, v108, s[12:13] nt
	v_cvt_pk_bf16_f32 v108, v100, v101
	s_nop 1
	v_mov_b32_dpp v109, v108 quad_perm:[1,0,3,2] row_mask:0xf bank_mask:0xf
	v_perm_b32 v100, v109, v108, v250
	v_add_u32_e32 v101, 0x8020, v158
	global_store_dword v101, v100, s[12:13] nt
	v_cvt_pk_bf16_f32 v100, v102, v103
	s_nop 1
	v_mov_b32_dpp v101, v100 quad_perm:[1,0,3,2] row_mask:0xf bank_mask:0xf
	v_perm_b32 v100, v101, v100, v250
	v_add_u32_e32 v101, 0x9020, v158
	global_store_dword v101, v100, s[12:13] nt
	v_cvt_pk_bf16_f32 v100, v104, v105
	s_nop 1
	v_mov_b32_dpp v101, v100 quad_perm:[1,0,3,2] row_mask:0xf bank_mask:0xf
	v_perm_b32 v100, v101, v100, v250
	v_add_u32_e32 v101, 0x8100, v158
	global_store_dword v101, v100, s[12:13] nt
	v_cvt_pk_bf16_f32 v100, v106, v107
	s_nop 1
	v_mov_b32_dpp v101, v100 quad_perm:[1,0,3,2] row_mask:0xf bank_mask:0xf
	v_perm_b32 v100, v101, v100, v250
	v_add_u32_e32 v101, 0x9100, v158
	global_store_dword v101, v100, s[12:13] nt
	v_cvt_pk_bf16_f32 v100, v96, v97
	s_nop 1
	v_mov_b32_dpp v101, v100 quad_perm:[1,0,3,2] row_mask:0xf bank_mask:0xf
	v_perm_b32 v96, v101, v100, v250
	v_add_u32_e32 v97, 0x8120, v158
	global_store_dword v97, v96, s[12:13] nt
	v_cvt_pk_bf16_f32 v96, v98, v99
	s_nop 1
	v_mov_b32_dpp v97, v96 quad_perm:[1,0,3,2] row_mask:0xf bank_mask:0xf
	v_perm_b32 v96, v97, v96, v250
	v_add_u32_e32 v97, 0x9120, v158
	global_store_dword v97, v96, s[12:13] nt
	v_cvt_pk_bf16_f32 v96, v92, v93
	s_nop 1
	v_mov_b32_dpp v97, v96 quad_perm:[1,0,3,2] row_mask:0xf bank_mask:0xf
	v_perm_b32 v92, v97, v96, v250
	v_add_u32_e32 v93, 0x10000, v158
	global_store_dword v93, v92, s[12:13] nt
	v_cvt_pk_bf16_f32 v92, v94, v95
	s_nop 1
	v_mov_b32_dpp v93, v92 quad_perm:[1,0,3,2] row_mask:0xf bank_mask:0xf
	v_perm_b32 v92, v93, v92, v250
	v_add_u32_e32 v93, 0x11000, v158
	global_store_dword v93, v92, s[12:13] nt
	v_cvt_pk_bf16_f32 v92, v84, v85
	s_nop 1
	v_mov_b32_dpp v93, v92 quad_perm:[1,0,3,2] row_mask:0xf bank_mask:0xf
	v_perm_b32 v84, v93, v92, v250
	v_add_u32_e32 v85, 0x10020, v158
	global_store_dword v85, v84, s[12:13] nt
	v_cvt_pk_bf16_f32 v84, v86, v87
	s_nop 1
	v_mov_b32_dpp v85, v84 quad_perm:[1,0,3,2] row_mask:0xf bank_mask:0xf
	v_perm_b32 v84, v85, v84, v250
	v_add_u32_e32 v85, 0x11020, v158
	global_store_dword v85, v84, s[12:13] nt
	v_cvt_pk_bf16_f32 v84, v88, v89
	s_nop 1
	v_mov_b32_dpp v85, v84 quad_perm:[1,0,3,2] row_mask:0xf bank_mask:0xf
	v_perm_b32 v84, v85, v84, v250
	v_add_u32_e32 v85, 0x10100, v158
	global_store_dword v85, v84, s[12:13] nt
	v_cvt_pk_bf16_f32 v84, v90, v91
	s_nop 1
	v_mov_b32_dpp v85, v84 quad_perm:[1,0,3,2] row_mask:0xf bank_mask:0xf
	v_perm_b32 v84, v85, v84, v250
	v_add_u32_e32 v85, 0x11100, v158
	global_store_dword v85, v84, s[12:13] nt
	v_cvt_pk_bf16_f32 v84, v80, v81
	s_nop 1
	v_mov_b32_dpp v85, v84 quad_perm:[1,0,3,2] row_mask:0xf bank_mask:0xf
	v_perm_b32 v80, v85, v84, v250
	v_add_u32_e32 v81, 0x10120, v158
	global_store_dword v81, v80, s[12:13] nt
	v_cvt_pk_bf16_f32 v80, v82, v83
	s_nop 1
	v_mov_b32_dpp v81, v80 quad_perm:[1,0,3,2] row_mask:0xf bank_mask:0xf
	v_perm_b32 v80, v81, v80, v250
	v_add_u32_e32 v81, 0x11120, v158
	global_store_dword v81, v80, s[12:13] nt
	v_cvt_pk_bf16_f32 v80, v76, v77
	s_nop 1
	v_mov_b32_dpp v81, v80 quad_perm:[1,0,3,2] row_mask:0xf bank_mask:0xf
	v_perm_b32 v76, v81, v80, v250
	v_add_u32_e32 v77, 0x18000, v158
	global_store_dword v77, v76, s[12:13] nt
	v_cvt_pk_bf16_f32 v76, v78, v79
	s_nop 1
	v_mov_b32_dpp v77, v76 quad_perm:[1,0,3,2] row_mask:0xf bank_mask:0xf
	v_perm_b32 v76, v77, v76, v250
	v_add_u32_e32 v77, 0x19000, v158
	global_store_dword v77, v76, s[12:13] nt
	v_cvt_pk_bf16_f32 v76, v68, v69
	s_nop 1
	v_mov_b32_dpp v77, v76 quad_perm:[1,0,3,2] row_mask:0xf bank_mask:0xf
	v_perm_b32 v68, v77, v76, v250
	v_add_u32_e32 v69, 0x18020, v158
	global_store_dword v69, v68, s[12:13] nt
	v_cvt_pk_bf16_f32 v68, v70, v71
	s_nop 1
	v_mov_b32_dpp v69, v68 quad_perm:[1,0,3,2] row_mask:0xf bank_mask:0xf
	v_perm_b32 v68, v69, v68, v250
	v_add_u32_e32 v69, 0x19020, v158
	global_store_dword v69, v68, s[12:13] nt
	v_cvt_pk_bf16_f32 v68, v72, v73
	s_nop 1
	v_mov_b32_dpp v69, v68 quad_perm:[1,0,3,2] row_mask:0xf bank_mask:0xf
	v_perm_b32 v68, v69, v68, v250
	v_add_u32_e32 v69, 0x18100, v158
	global_store_dword v69, v68, s[12:13] nt
	v_cvt_pk_bf16_f32 v68, v74, v75
	s_nop 1
	v_mov_b32_dpp v69, v68 quad_perm:[1,0,3,2] row_mask:0xf bank_mask:0xf
	v_perm_b32 v68, v69, v68, v250
	v_add_u32_e32 v69, 0x19100, v158
	global_store_dword v69, v68, s[12:13] nt
	v_cvt_pk_bf16_f32 v68, v64, v65
	s_nop 1
	v_mov_b32_dpp v69, v68 quad_perm:[1,0,3,2] row_mask:0xf bank_mask:0xf
	v_perm_b32 v64, v69, v68, v250
	v_add_u32_e32 v65, 0x18120, v158
	global_store_dword v65, v64, s[12:13] nt
	v_cvt_pk_bf16_f32 v64, v66, v67
	s_nop 1
	v_mov_b32_dpp v65, v64 quad_perm:[1,0,3,2] row_mask:0xf bank_mask:0xf
	v_perm_b32 v64, v65, v64, v250
	v_add_u32_e32 v65, 0x19120, v158
	global_store_dword v65, v64, s[12:13] nt
	v_cvt_pk_bf16_f32 v64, v60, v61
	s_nop 1
	v_mov_b32_dpp v65, v64 quad_perm:[1,0,3,2] row_mask:0xf bank_mask:0xf
	v_perm_b32 v60, v65, v64, v250
	v_add_u32_e32 v61, 0x40000, v158
	global_store_dword v61, v60, s[12:13] nt
	v_cvt_pk_bf16_f32 v60, v62, v63
	s_nop 1
	v_mov_b32_dpp v61, v60 quad_perm:[1,0,3,2] row_mask:0xf bank_mask:0xf
	v_perm_b32 v60, v61, v60, v250
	v_add_u32_e32 v61, 0x41000, v158
	global_store_dword v61, v60, s[12:13] nt
	v_cvt_pk_bf16_f32 v60, v52, v53
	s_nop 1
	v_mov_b32_dpp v61, v60 quad_perm:[1,0,3,2] row_mask:0xf bank_mask:0xf
	v_perm_b32 v52, v61, v60, v250
	v_add_u32_e32 v53, 0x40020, v158
	global_store_dword v53, v52, s[12:13] nt
	v_cvt_pk_bf16_f32 v52, v54, v55
	s_nop 1
	v_mov_b32_dpp v53, v52 quad_perm:[1,0,3,2] row_mask:0xf bank_mask:0xf
	v_perm_b32 v52, v53, v52, v250
	v_add_u32_e32 v53, 0x41020, v158
	global_store_dword v53, v52, s[12:13] nt
	v_cvt_pk_bf16_f32 v52, v56, v57
	s_nop 1
	v_mov_b32_dpp v53, v52 quad_perm:[1,0,3,2] row_mask:0xf bank_mask:0xf
	v_perm_b32 v52, v53, v52, v250
	v_add_u32_e32 v53, 0x40100, v158
	global_store_dword v53, v52, s[12:13] nt
	v_cvt_pk_bf16_f32 v52, v58, v59
	s_nop 1
	v_mov_b32_dpp v53, v52 quad_perm:[1,0,3,2] row_mask:0xf bank_mask:0xf
	v_perm_b32 v52, v53, v52, v250
	v_add_u32_e32 v53, 0x41100, v158
	global_store_dword v53, v52, s[12:13] nt
	v_cvt_pk_bf16_f32 v52, v48, v49
	s_nop 1
	v_mov_b32_dpp v53, v52 quad_perm:[1,0,3,2] row_mask:0xf bank_mask:0xf
	v_perm_b32 v48, v53, v52, v250
	v_add_u32_e32 v49, 0x40120, v158
	global_store_dword v49, v48, s[12:13] nt
	v_cvt_pk_bf16_f32 v48, v50, v51
	s_nop 1
	v_mov_b32_dpp v49, v48 quad_perm:[1,0,3,2] row_mask:0xf bank_mask:0xf
	v_perm_b32 v48, v49, v48, v250
	v_add_u32_e32 v49, 0x41120, v158
	global_store_dword v49, v48, s[12:13] nt
	v_cvt_pk_bf16_f32 v48, v44, v45
	s_nop 1
	v_mov_b32_dpp v49, v48 quad_perm:[1,0,3,2] row_mask:0xf bank_mask:0xf
	v_perm_b32 v44, v49, v48, v250
	v_add_u32_e32 v45, 0x48000, v158
	global_store_dword v45, v44, s[12:13] nt
	v_cvt_pk_bf16_f32 v44, v46, v47
	s_nop 1
	v_mov_b32_dpp v45, v44 quad_perm:[1,0,3,2] row_mask:0xf bank_mask:0xf
	v_perm_b32 v44, v45, v44, v250
	v_add_u32_e32 v45, 0x49000, v158
	global_store_dword v45, v44, s[12:13] nt
	v_cvt_pk_bf16_f32 v44, v36, v37
	s_nop 1
	v_mov_b32_dpp v45, v44 quad_perm:[1,0,3,2] row_mask:0xf bank_mask:0xf
	v_perm_b32 v36, v45, v44, v250
	v_add_u32_e32 v37, 0x48020, v158
	global_store_dword v37, v36, s[12:13] nt
	v_cvt_pk_bf16_f32 v36, v38, v39
	s_nop 1
	v_mov_b32_dpp v37, v36 quad_perm:[1,0,3,2] row_mask:0xf bank_mask:0xf
	v_perm_b32 v36, v37, v36, v250
	v_add_u32_e32 v37, 0x49020, v158
	global_store_dword v37, v36, s[12:13] nt
	v_cvt_pk_bf16_f32 v36, v40, v41
	s_nop 1
	v_mov_b32_dpp v37, v36 quad_perm:[1,0,3,2] row_mask:0xf bank_mask:0xf
	v_perm_b32 v36, v37, v36, v250
	v_add_u32_e32 v37, 0x48100, v158
	global_store_dword v37, v36, s[12:13] nt
	v_cvt_pk_bf16_f32 v36, v42, v43
	s_nop 1
	v_mov_b32_dpp v37, v36 quad_perm:[1,0,3,2] row_mask:0xf bank_mask:0xf
	v_perm_b32 v36, v37, v36, v250
	v_add_u32_e32 v37, 0x49100, v158
	global_store_dword v37, v36, s[12:13] nt
	v_cvt_pk_bf16_f32 v36, v32, v33
	s_nop 1
	v_mov_b32_dpp v37, v36 quad_perm:[1,0,3,2] row_mask:0xf bank_mask:0xf
	v_perm_b32 v32, v37, v36, v250
	v_add_u32_e32 v33, 0x48120, v158
	global_store_dword v33, v32, s[12:13] nt
	v_cvt_pk_bf16_f32 v32, v34, v35
	s_nop 1
	v_mov_b32_dpp v33, v32 quad_perm:[1,0,3,2] row_mask:0xf bank_mask:0xf
	v_perm_b32 v32, v33, v32, v250
	v_add_u32_e32 v33, 0x49120, v158
	global_store_dword v33, v32, s[12:13] nt
	v_cvt_pk_bf16_f32 v32, v28, v29
	s_nop 1
	v_mov_b32_dpp v33, v32 quad_perm:[1,0,3,2] row_mask:0xf bank_mask:0xf
	v_perm_b32 v28, v33, v32, v250
	v_add_u32_e32 v29, 0x50000, v158
	global_store_dword v29, v28, s[12:13] nt
	v_cvt_pk_bf16_f32 v28, v30, v31
	s_nop 1
	v_mov_b32_dpp v29, v28 quad_perm:[1,0,3,2] row_mask:0xf bank_mask:0xf
	v_perm_b32 v28, v29, v28, v250
	v_add_u32_e32 v29, 0x51000, v158
	global_store_dword v29, v28, s[12:13] nt
	v_cvt_pk_bf16_f32 v28, v20, v21
	s_nop 1
	v_mov_b32_dpp v29, v28 quad_perm:[1,0,3,2] row_mask:0xf bank_mask:0xf
	v_perm_b32 v20, v29, v28, v250
	v_add_u32_e32 v21, 0x50020, v158
	global_store_dword v21, v20, s[12:13] nt
	v_cvt_pk_bf16_f32 v20, v22, v23
	s_nop 1
	v_mov_b32_dpp v21, v20 quad_perm:[1,0,3,2] row_mask:0xf bank_mask:0xf
	v_perm_b32 v20, v21, v20, v250
	v_add_u32_e32 v21, 0x51020, v158
	global_store_dword v21, v20, s[12:13] nt
	v_cvt_pk_bf16_f32 v20, v24, v25
	s_nop 1
	v_mov_b32_dpp v21, v20 quad_perm:[1,0,3,2] row_mask:0xf bank_mask:0xf
	v_perm_b32 v20, v21, v20, v250
	v_add_u32_e32 v21, 0x50100, v158
	global_store_dword v21, v20, s[12:13] nt
	v_cvt_pk_bf16_f32 v20, v26, v27
	s_nop 1
	v_mov_b32_dpp v21, v20 quad_perm:[1,0,3,2] row_mask:0xf bank_mask:0xf
	v_perm_b32 v20, v21, v20, v250
	v_add_u32_e32 v21, 0x51100, v158
	global_store_dword v21, v20, s[12:13] nt
	v_cvt_pk_bf16_f32 v20, v16, v17
	s_nop 1
	v_mov_b32_dpp v21, v20 quad_perm:[1,0,3,2] row_mask:0xf bank_mask:0xf
	v_perm_b32 v16, v21, v20, v250
	v_add_u32_e32 v17, 0x50120, v158
	global_store_dword v17, v16, s[12:13] nt
	v_cvt_pk_bf16_f32 v16, v18, v19
	s_nop 1
	v_mov_b32_dpp v17, v16 quad_perm:[1,0,3,2] row_mask:0xf bank_mask:0xf
	v_perm_b32 v16, v17, v16, v250
	v_add_u32_e32 v17, 0x51120, v158
	global_store_dword v17, v16, s[12:13] nt
	v_cvt_pk_bf16_f32 v16, v12, v13
	s_nop 1
	v_mov_b32_dpp v17, v16 quad_perm:[1,0,3,2] row_mask:0xf bank_mask:0xf
	v_perm_b32 v12, v17, v16, v250
	v_add_u32_e32 v13, 0x58000, v158
	global_store_dword v13, v12, s[12:13] nt
	v_cvt_pk_bf16_f32 v12, v14, v15
	s_nop 1
	v_mov_b32_dpp v13, v12 quad_perm:[1,0,3,2] row_mask:0xf bank_mask:0xf
	v_perm_b32 v12, v13, v12, v250
	v_add_u32_e32 v13, 0x59000, v158
	global_store_dword v13, v12, s[12:13] nt
	v_cvt_pk_bf16_f32 v12, v4, v5
	s_nop 1
	v_mov_b32_dpp v13, v12 quad_perm:[1,0,3,2] row_mask:0xf bank_mask:0xf
	v_perm_b32 v4, v13, v12, v250
	v_add_u32_e32 v5, 0x58020, v158
	global_store_dword v5, v4, s[12:13] nt
	v_cvt_pk_bf16_f32 v4, v6, v7
	s_nop 1
	v_mov_b32_dpp v5, v4 quad_perm:[1,0,3,2] row_mask:0xf bank_mask:0xf
	v_perm_b32 v4, v5, v4, v250
	v_add_u32_e32 v5, 0x59020, v158
	global_store_dword v5, v4, s[12:13] nt
	v_cvt_pk_bf16_f32 v4, v8, v9
	s_nop 1
	v_mov_b32_dpp v5, v4 quad_perm:[1,0,3,2] row_mask:0xf bank_mask:0xf
	v_perm_b32 v4, v5, v4, v250
	v_add_u32_e32 v5, 0x58100, v158
	global_store_dword v5, v4, s[12:13] nt
	v_cvt_pk_bf16_f32 v4, v10, v11
	s_nop 1
	v_mov_b32_dpp v5, v4 quad_perm:[1,0,3,2] row_mask:0xf bank_mask:0xf
	v_perm_b32 v4, v5, v4, v250
	v_add_u32_e32 v5, 0x59100, v158
	global_store_dword v5, v4, s[12:13] nt
	v_cvt_pk_bf16_f32 v4, v0, v1
	s_nop 1
	v_mov_b32_dpp v5, v4 quad_perm:[1,0,3,2] row_mask:0xf bank_mask:0xf
	v_perm_b32 v0, v5, v4, v250
	v_add_u32_e32 v1, 0x58120, v158
	global_store_dword v1, v0, s[12:13] nt
	v_cvt_pk_bf16_f32 v0, v2, v3
	s_nop 1
	v_mov_b32_dpp v1, v0 quad_perm:[1,0,3,2] row_mask:0xf bank_mask:0xf
	v_perm_b32 v0, v1, v0, v250
	v_add_u32_e32 v1, 0x59120, v158
	global_store_dword v1, v0, s[12:13] nt
	s_and_b64 vcc, exec, s[22:23]
	s_mov_b32 s19, s42
	s_mov_b32 s80, s43
	s_cbranch_vccnz .LBB0_143

.LBB0_1536:
	v_or_b32_e32 v164, s40, v152
	v_ashrrev_i32_e32 v165, 31, v164
	v_lshl_add_u64 v[164:165], v[164:165], 2, s[12:13]
	global_load_dword v140, v[164:165], off
	global_load_dword v138, v[164:165], off offset:64
	global_load_dword v136, v[164:165], off offset:512
	global_load_dword v134, v[164:165], off offset:576
	v_or_b32_e32 v163, s40, v154
	v_add_lshl_u32 v164, v153, s38, 13
	v_lshl_add_u32 v163, v163, 1, v164
	s_mov_b32 s18, 0xc0135761
	s_waitcnt vmcnt(0)
	v_pk_add_f32 v[164:165], v[124:125], v[140:141] op_sel_hi:[1,0]
	s_nop 0
	v_pk_mul_f32 v[166:167], v[164:165], v[164:165]
	v_mov_b64_e32 v[124:125], s[18:19]
	v_pk_fma_f32 v[166:167], v[166:167], s[88:89], v[124:125] op_sel_hi:[1,0,0] neg_lo:[1,0,0] neg_hi:[1,0,0]
	v_pk_add_f32 v[126:127], v[126:127], v[140:141] op_sel_hi:[1,0]
	v_pk_mul_f32 v[166:167], v[164:165], v[166:167]
	v_pk_add_f32 v[120:121], v[120:121], v[138:139] op_sel_hi:[1,0]
	v_exp_f32_e32 v166, v166
	v_exp_f32_e32 v167, v167
	v_pk_add_f32 v[116:117], v[116:117], v[136:137] op_sel_hi:[1,0]
	v_pk_add_f32 v[112:113], v[112:113], v[134:135] op_sel_hi:[1,0]
	v_pk_add_f32 v[166:167], v[166:167], 1.0 op_sel_hi:[1,0]
	s_nop 0
	v_rcp_f32_e32 v166, v166
	v_rcp_f32_e32 v167, v167
	s_nop 0
	v_pk_mul_f32 v[164:165], v[164:165], v[166:167]
	s_nop 0
	v_cvt_pk_bf16_f32 v166, v164, v165
	s_nop 1
	v_mov_b32_dpp v167, v166 quad_perm:[1,0,3,2] row_mask:0xf bank_mask:0xf
	v_perm_b32 v164, v167, v166, v250
	global_store_dword v163, v164, s[2:3] nt
	v_pk_mul_f32 v[164:165], v[126:127], v[126:127]
	s_nop 0
	v_pk_fma_f32 v[164:165], v[164:165], s[88:89], v[124:125] op_sel_hi:[1,0,0] neg_lo:[1,0,0] neg_hi:[1,0,0]
	s_nop 0
	v_pk_mul_f32 v[164:165], v[126:127], v[164:165]
	s_nop 0
	v_exp_f32_e32 v164, v164
	v_exp_f32_e32 v165, v165
	s_nop 0
	v_pk_add_f32 v[164:165], v[164:165], 1.0 op_sel_hi:[1,0]
	s_nop 0
	v_rcp_f32_e32 v164, v164
	v_rcp_f32_e32 v165, v165
	s_nop 0
	v_pk_mul_f32 v[126:127], v[126:127], v[164:165]
	s_nop 0
	v_cvt_pk_bf16_f32 v164, v126, v127
	s_nop 1
	v_mov_b32_dpp v165, v164 quad_perm:[1,0,3,2] row_mask:0xf bank_mask:0xf
	v_perm_b32 v126, v165, v164, v250
	v_add_u32_e32 v127, 0x4000, v163
	global_store_dword v127, v126, s[2:3] nt
	v_pk_mul_f32 v[126:127], v[120:121], v[120:121]
	v_or_b32_e32 v164, 32, v163
	v_pk_fma_f32 v[126:127], v[126:127], s[88:89], v[124:125] op_sel_hi:[1,0,0] neg_lo:[1,0,0] neg_hi:[1,0,0]
	s_nop 0
	v_pk_mul_f32 v[126:127], v[120:121], v[126:127]
	s_nop 0
	v_exp_f32_e32 v126, v126
	v_exp_f32_e32 v127, v127
	s_nop 0
	v_pk_add_f32 v[126:127], v[126:127], 1.0 op_sel_hi:[1,0]
	s_nop 0
	v_rcp_f32_e32 v126, v126
	v_rcp_f32_e32 v127, v127
	s_nop 0
	v_pk_mul_f32 v[120:121], v[120:121], v[126:127]
	s_nop 0
	v_cvt_pk_bf16_f32 v126, v120, v121
	s_nop 1
	v_mov_b32_dpp v127, v126 quad_perm:[1,0,3,2] row_mask:0xf bank_mask:0xf
	v_perm_b32 v120, v127, v126, v250
	global_store_dword v164, v120, s[2:3] nt
	v_pk_add_f32 v[120:121], v[122:123], v[138:139] op_sel_hi:[1,0]
	s_nop 0
	v_pk_mul_f32 v[122:123], v[120:121], v[120:121]
	s_nop 0
	v_pk_fma_f32 v[122:123], v[122:123], s[88:89], v[124:125] op_sel_hi:[1,0,0] neg_lo:[1,0,0] neg_hi:[1,0,0]
	s_nop 0
	v_pk_mul_f32 v[122:123], v[120:121], v[122:123]
	s_nop 0
	v_exp_f32_e32 v122, v122
	v_exp_f32_e32 v123, v123
	s_nop 0
	v_pk_add_f32 v[122:123], v[122:123], 1.0 op_sel_hi:[1,0]
	s_nop 0
	v_rcp_f32_e32 v122, v122
	v_rcp_f32_e32 v123, v123
	s_nop 0
	v_pk_mul_f32 v[120:121], v[120:121], v[122:123]
	s_nop 0
	v_cvt_pk_bf16_f32 v122, v120, v121
	s_nop 1
	v_mov_b32_dpp v123, v122 quad_perm:[1,0,3,2] row_mask:0xf bank_mask:0xf
	v_perm_b32 v120, v123, v122, v250
	v_add_u32_e32 v121, 0x4020, v163
	global_store_dword v121, v120, s[2:3] nt
	v_pk_mul_f32 v[120:121], v[116:117], v[116:117]
	v_or_b32_e32 v122, 0x100, v163
	v_pk_fma_f32 v[120:121], v[120:121], s[88:89], v[124:125] op_sel_hi:[1,0,0] neg_lo:[1,0,0] neg_hi:[1,0,0]
	s_nop 0
	v_pk_mul_f32 v[120:121], v[116:117], v[120:121]
	s_nop 0
	v_exp_f32_e32 v120, v120
	v_exp_f32_e32 v121, v121
	s_nop 0
	v_pk_add_f32 v[120:121], v[120:121], 1.0 op_sel_hi:[1,0]
	s_nop 0
	v_rcp_f32_e32 v120, v120
	v_rcp_f32_e32 v121, v121
	s_nop 0
	v_pk_mul_f32 v[116:117], v[116:117], v[120:121]
	s_nop 0
	v_cvt_pk_bf16_f32 v120, v116, v117
	s_nop 1
	v_mov_b32_dpp v121, v120 quad_perm:[1,0,3,2] row_mask:0xf bank_mask:0xf
	v_perm_b32 v116, v121, v120, v250
	global_store_dword v122, v116, s[2:3] nt
	v_pk_add_f32 v[116:117], v[118:119], v[136:137] op_sel_hi:[1,0]
	s_nop 0
	v_pk_mul_f32 v[118:119], v[116:117], v[116:117]
	s_nop 0
	v_pk_fma_f32 v[118:119], v[118:119], s[88:89], v[124:125] op_sel_hi:[1,0,0] neg_lo:[1,0,0] neg_hi:[1,0,0]
	s_nop 0
	v_pk_mul_f32 v[118:119], v[116:117], v[118:119]
	s_nop 0
	v_exp_f32_e32 v118, v118
	v_exp_f32_e32 v119, v119
	s_nop 0
	v_pk_add_f32 v[118:119], v[118:119], 1.0 op_sel_hi:[1,0]
	s_nop 0
	v_rcp_f32_e32 v118, v118
	v_rcp_f32_e32 v119, v119
	s_nop 0
	v_pk_mul_f32 v[116:117], v[116:117], v[118:119]
	s_nop 0
	v_cvt_pk_bf16_f32 v118, v116, v117
	s_nop 1
	v_mov_b32_dpp v119, v118 quad_perm:[1,0,3,2] row_mask:0xf bank_mask:0xf
	v_perm_b32 v116, v119, v118, v250
	v_add_u32_e32 v117, 0x4100, v163
	global_store_dword v117, v116, s[2:3] nt
	v_pk_mul_f32 v[116:117], v[112:113], v[112:113]
	v_or_b32_e32 v118, 0x120, v163
	v_pk_fma_f32 v[116:117], v[116:117], s[88:89], v[124:125] op_sel_hi:[1,0,0] neg_lo:[1,0,0] neg_hi:[1,0,0]
	s_nop 0
	v_pk_mul_f32 v[116:117], v[112:113], v[116:117]
	s_nop 0
	v_exp_f32_e32 v116, v116
	v_exp_f32_e32 v117, v117
	s_nop 0
	v_pk_add_f32 v[116:117], v[116:117], 1.0 op_sel_hi:[1,0]
	s_nop 0
	v_rcp_f32_e32 v116, v116
	v_rcp_f32_e32 v117, v117
	s_nop 0
	v_pk_mul_f32 v[112:113], v[112:113], v[116:117]
	s_nop 0
	v_cvt_pk_bf16_f32 v116, v112, v113
	s_nop 1
	v_mov_b32_dpp v117, v116 quad_perm:[1,0,3,2] row_mask:0xf bank_mask:0xf
	v_perm_b32 v112, v117, v116, v250
	global_store_dword v118, v112, s[2:3] nt
	v_pk_add_f32 v[112:113], v[114:115], v[134:135] op_sel_hi:[1,0]
	s_nop 0
	v_pk_mul_f32 v[114:115], v[112:113], v[112:113]
	s_nop 0
	v_pk_fma_f32 v[114:115], v[114:115], s[88:89], v[124:125] op_sel_hi:[1,0,0] neg_lo:[1,0,0] neg_hi:[1,0,0]
	s_nop 0
	v_pk_mul_f32 v[114:115], v[112:113], v[114:115]
	s_nop 0
	v_exp_f32_e32 v114, v114
	v_exp_f32_e32 v115, v115
	s_nop 0
	v_pk_add_f32 v[114:115], v[114:115], 1.0 op_sel_hi:[1,0]
	s_nop 0
	v_rcp_f32_e32 v114, v114
	v_rcp_f32_e32 v115, v115
	s_nop 0
	v_pk_mul_f32 v[112:113], v[112:113], v[114:115]
	s_nop 0
	v_cvt_pk_bf16_f32 v114, v112, v113
	s_nop 1
	v_mov_b32_dpp v115, v114 quad_perm:[1,0,3,2] row_mask:0xf bank_mask:0xf
	v_perm_b32 v112, v115, v114, v250
	v_add_u32_e32 v113, 0x4120, v163
	global_store_dword v113, v112, s[2:3] nt
	v_pk_add_f32 v[108:109], v[108:109], v[140:141] op_sel_hi:[1,0]
	v_pk_add_f32 v[104:105], v[104:105], v[138:139] op_sel_hi:[1,0]
	v_pk_mul_f32 v[112:113], v[108:109], v[108:109]
	v_pk_add_f32 v[100:101], v[100:101], v[136:137] op_sel_hi:[1,0]
	v_pk_fma_f32 v[112:113], v[112:113], s[88:89], v[124:125] op_sel_hi:[1,0,0] neg_lo:[1,0,0] neg_hi:[1,0,0]
	v_pk_add_f32 v[96:97], v[96:97], v[134:135] op_sel_hi:[1,0]
	v_pk_mul_f32 v[112:113], v[108:109], v[112:113]
	s_nop 0
	v_exp_f32_e32 v112, v112
	v_exp_f32_e32 v113, v113
	s_nop 0
	v_pk_add_f32 v[112:113], v[112:113], 1.0 op_sel_hi:[1,0]
	s_nop 0
	v_rcp_f32_e32 v112, v112
	v_rcp_f32_e32 v113, v113
	s_nop 0
	v_pk_mul_f32 v[108:109], v[108:109], v[112:113]
	s_nop 0
	v_cvt_pk_bf16_f32 v112, v108, v109
	s_nop 1
	v_mov_b32_dpp v113, v112 quad_perm:[1,0,3,2] row_mask:0xf bank_mask:0xf
	v_perm_b32 v108, v113, v112, v250
	v_add_u32_e32 v109, 0x20000, v163
	global_store_dword v109, v108, s[2:3] nt
	v_pk_add_f32 v[108:109], v[110:111], v[140:141] op_sel_hi:[1,0]
	s_nop 0
	v_pk_mul_f32 v[110:111], v[108:109], v[108:109]
	s_nop 0
	v_pk_fma_f32 v[110:111], v[110:111], s[88:89], v[124:125] op_sel_hi:[1,0,0] neg_lo:[1,0,0] neg_hi:[1,0,0]
	s_nop 0
	v_pk_mul_f32 v[110:111], v[108:109], v[110:111]
	s_nop 0
	v_exp_f32_e32 v110, v110
	v_exp_f32_e32 v111, v111
	s_nop 0
	v_pk_add_f32 v[110:111], v[110:111], 1.0 op_sel_hi:[1,0]
	s_nop 0
	v_rcp_f32_e32 v110, v110
	v_rcp_f32_e32 v111, v111
	s_nop 0
	v_pk_mul_f32 v[108:109], v[108:109], v[110:111]
	s_nop 0
	v_cvt_pk_bf16_f32 v110, v108, v109
	s_nop 1
	v_mov_b32_dpp v111, v110 quad_perm:[1,0,3,2] row_mask:0xf bank_mask:0xf
	v_perm_b32 v108, v111, v110, v250
	v_add_u32_e32 v109, 0x24000, v163
	global_store_dword v109, v108, s[2:3] nt
	v_pk_mul_f32 v[108:109], v[104:105], v[104:105]
	s_nop 0
	v_pk_fma_f32 v[108:109], v[108:109], s[88:89], v[124:125] op_sel_hi:[1,0,0] neg_lo:[1,0,0] neg_hi:[1,0,0]
	s_nop 0
	v_pk_mul_f32 v[108:109], v[104:105], v[108:109]
	s_nop 0
	v_exp_f32_e32 v108, v108
	v_exp_f32_e32 v109, v109
	s_nop 0
	v_pk_add_f32 v[108:109], v[108:109], 1.0 op_sel_hi:[1,0]
	s_nop 0
	v_rcp_f32_e32 v108, v108
	v_rcp_f32_e32 v109, v109
	s_nop 0
	v_pk_mul_f32 v[104:105], v[104:105], v[108:109]
	s_nop 0
	v_cvt_pk_bf16_f32 v108, v104, v105
	s_nop 1
	v_mov_b32_dpp v109, v108 quad_perm:[1,0,3,2] row_mask:0xf bank_mask:0xf
	v_perm_b32 v104, v109, v108, v250
	v_add_u32_e32 v105, 0x20020, v163
	global_store_dword v105, v104, s[2:3] nt
	v_pk_add_f32 v[104:105], v[106:107], v[138:139] op_sel_hi:[1,0]
	s_nop 0
	v_pk_mul_f32 v[106:107], v[104:105], v[104:105]
	s_nop 0
	v_pk_fma_f32 v[106:107], v[106:107], s[88:89], v[124:125] op_sel_hi:[1,0,0] neg_lo:[1,0,0] neg_hi:[1,0,0]
	s_nop 0
	v_pk_mul_f32 v[106:107], v[104:105], v[106:107]
	s_nop 0
	v_exp_f32_e32 v106, v106
	v_exp_f32_e32 v107, v107
	s_nop 0
	v_pk_add_f32 v[106:107], v[106:107], 1.0 op_sel_hi:[1,0]
	s_nop 0
	v_rcp_f32_e32 v106, v106
	v_rcp_f32_e32 v107, v107
	s_nop 0
	v_pk_mul_f32 v[104:105], v[104:105], v[106:107]
	s_nop 0
	v_cvt_pk_bf16_f32 v106, v104, v105
	s_nop 1
	v_mov_b32_dpp v107, v106 quad_perm:[1,0,3,2] row_mask:0xf bank_mask:0xf
	v_perm_b32 v104, v107, v106, v250
	v_add_u32_e32 v105, 0x24020, v163
	global_store_dword v105, v104, s[2:3] nt
	v_pk_mul_f32 v[104:105], v[100:101], v[100:101]
	s_nop 0
	v_pk_fma_f32 v[104:105], v[104:105], s[88:89], v[124:125] op_sel_hi:[1,0,0] neg_lo:[1,0,0] neg_hi:[1,0,0]
	s_nop 0
	v_pk_mul_f32 v[104:105], v[100:101], v[104:105]
	s_nop 0
	v_exp_f32_e32 v104, v104
	v_exp_f32_e32 v105, v105
	s_nop 0
	v_pk_add_f32 v[104:105], v[104:105], 1.0 op_sel_hi:[1,0]
	s_nop 0
	v_rcp_f32_e32 v104, v104
	v_rcp_f32_e32 v105, v105
	s_nop 0
	v_pk_mul_f32 v[100:101], v[100:101], v[104:105]
	s_nop 0
	v_cvt_pk_bf16_f32 v104, v100, v101
	s_nop 1
	v_mov_b32_dpp v105, v104 quad_perm:[1,0,3,2] row_mask:0xf bank_mask:0xf
	v_perm_b32 v100, v105, v104, v250
	v_add_u32_e32 v101, 0x20100, v163
	global_store_dword v101, v100, s[2:3] nt
	v_pk_add_f32 v[100:101], v[102:103], v[136:137] op_sel_hi:[1,0]
	s_nop 0
	v_pk_mul_f32 v[102:103], v[100:101], v[100:101]
	s_nop 0
	v_pk_fma_f32 v[102:103], v[102:103], s[88:89], v[124:125] op_sel_hi:[1,0,0] neg_lo:[1,0,0] neg_hi:[1,0,0]
	s_nop 0
	v_pk_mul_f32 v[102:103], v[100:101], v[102:103]
	s_nop 0
	v_exp_f32_e32 v102, v102
	v_exp_f32_e32 v103, v103
	s_nop 0
	v_pk_add_f32 v[102:103], v[102:103], 1.0 op_sel_hi:[1,0]
	s_nop 0
	v_rcp_f32_e32 v102, v102
	v_rcp_f32_e32 v103, v103
	s_nop 0
	v_pk_mul_f32 v[100:101], v[100:101], v[102:103]
	s_nop 0
	v_cvt_pk_bf16_f32 v102, v100, v101
	s_nop 1
	v_mov_b32_dpp v103, v102 quad_perm:[1,0,3,2] row_mask:0xf bank_mask:0xf
	v_perm_b32 v100, v103, v102, v250
	v_add_u32_e32 v101, 0x24100, v163
	global_store_dword v101, v100, s[2:3] nt
	v_pk_mul_f32 v[100:101], v[96:97], v[96:97]
	s_nop 0
	v_pk_fma_f32 v[100:101], v[100:101], s[88:89], v[124:125] op_sel_hi:[1,0,0] neg_lo:[1,0,0] neg_hi:[1,0,0]
	s_nop 0
	v_pk_mul_f32 v[100:101], v[96:97], v[100:101]
	s_nop 0
	v_exp_f32_e32 v100, v100
	v_exp_f32_e32 v101, v101
	s_nop 0
	v_pk_add_f32 v[100:101], v[100:101], 1.0 op_sel_hi:[1,0]
	s_nop 0
	v_rcp_f32_e32 v100, v100
	v_rcp_f32_e32 v101, v101
	s_nop 0
	v_pk_mul_f32 v[96:97], v[96:97], v[100:101]
	s_nop 0
	v_cvt_pk_bf16_f32 v100, v96, v97
	s_nop 1
	v_mov_b32_dpp v101, v100 quad_perm:[1,0,3,2] row_mask:0xf bank_mask:0xf
	v_perm_b32 v96, v101, v100, v250
	v_add_u32_e32 v97, 0x20120, v163
	global_store_dword v97, v96, s[2:3] nt
	v_pk_add_f32 v[96:97], v[98:99], v[134:135] op_sel_hi:[1,0]
	s_nop 0
	v_pk_mul_f32 v[98:99], v[96:97], v[96:97]
	s_nop 0
	v_pk_fma_f32 v[98:99], v[98:99], s[88:89], v[124:125] op_sel_hi:[1,0,0] neg_lo:[1,0,0] neg_hi:[1,0,0]
	s_nop 0
	v_pk_mul_f32 v[98:99], v[96:97], v[98:99]
	s_nop 0
	v_exp_f32_e32 v98, v98
	v_exp_f32_e32 v99, v99
	s_nop 0
	v_pk_add_f32 v[98:99], v[98:99], 1.0 op_sel_hi:[1,0]
	s_nop 0
	v_rcp_f32_e32 v98, v98
	v_rcp_f32_e32 v99, v99
	s_nop 0
	v_pk_mul_f32 v[96:97], v[96:97], v[98:99]
	s_nop 0
	v_cvt_pk_bf16_f32 v98, v96, v97
	s_nop 1
	v_mov_b32_dpp v99, v98 quad_perm:[1,0,3,2] row_mask:0xf bank_mask:0xf
	v_perm_b32 v96, v99, v98, v250
	v_add_u32_e32 v97, 0x24120, v163
	global_store_dword v97, v96, s[2:3] nt
	v_pk_add_f32 v[92:93], v[92:93], v[140:141] op_sel_hi:[1,0]
	v_pk_add_f32 v[88:89], v[88:89], v[138:139] op_sel_hi:[1,0]
	v_pk_mul_f32 v[96:97], v[92:93], v[92:93]
	v_pk_add_f32 v[84:85], v[84:85], v[136:137] op_sel_hi:[1,0]
	v_pk_fma_f32 v[96:97], v[96:97], s[88:89], v[124:125] op_sel_hi:[1,0,0] neg_lo:[1,0,0] neg_hi:[1,0,0]
	v_pk_add_f32 v[80:81], v[80:81], v[134:135] op_sel_hi:[1,0]
	v_pk_mul_f32 v[96:97], v[92:93], v[96:97]
	s_nop 0
	v_exp_f32_e32 v96, v96
	v_exp_f32_e32 v97, v97
	s_nop 0
	v_pk_add_f32 v[96:97], v[96:97], 1.0 op_sel_hi:[1,0]
	s_nop 0
	v_rcp_f32_e32 v96, v96
	v_rcp_f32_e32 v97, v97
	s_nop 0
	v_pk_mul_f32 v[92:93], v[92:93], v[96:97]
	s_nop 0
	v_cvt_pk_bf16_f32 v96, v92, v93
	s_nop 1
	v_mov_b32_dpp v97, v96 quad_perm:[1,0,3,2] row_mask:0xf bank_mask:0xf
	v_perm_b32 v92, v97, v96, v250
	v_add_u32_e32 v93, 0x40000, v163
	global_store_dword v93, v92, s[2:3] nt
	v_pk_add_f32 v[92:93], v[94:95], v[140:141] op_sel_hi:[1,0]
	s_nop 0
	v_pk_mul_f32 v[94:95], v[92:93], v[92:93]
	s_nop 0
	v_pk_fma_f32 v[94:95], v[94:95], s[88:89], v[124:125] op_sel_hi:[1,0,0] neg_lo:[1,0,0] neg_hi:[1,0,0]
	s_nop 0
	v_pk_mul_f32 v[94:95], v[92:93], v[94:95]
	s_nop 0
	v_exp_f32_e32 v94, v94
	v_exp_f32_e32 v95, v95
	s_nop 0
	v_pk_add_f32 v[94:95], v[94:95], 1.0 op_sel_hi:[1,0]
	s_nop 0
	v_rcp_f32_e32 v94, v94
	v_rcp_f32_e32 v95, v95
	s_nop 0
	v_pk_mul_f32 v[92:93], v[92:93], v[94:95]
	s_nop 0
	v_cvt_pk_bf16_f32 v94, v92, v93
	s_nop 1
	v_mov_b32_dpp v95, v94 quad_perm:[1,0,3,2] row_mask:0xf bank_mask:0xf
	v_perm_b32 v92, v95, v94, v250
	v_add_u32_e32 v93, 0x44000, v163
	global_store_dword v93, v92, s[2:3] nt
	v_pk_mul_f32 v[92:93], v[88:89], v[88:89]
	s_nop 0
	v_pk_fma_f32 v[92:93], v[92:93], s[88:89], v[124:125] op_sel_hi:[1,0,0] neg_lo:[1,0,0] neg_hi:[1,0,0]
	s_nop 0
	v_pk_mul_f32 v[92:93], v[88:89], v[92:93]
	s_nop 0
	v_exp_f32_e32 v92, v92
	v_exp_f32_e32 v93, v93
	s_nop 0
	v_pk_add_f32 v[92:93], v[92:93], 1.0 op_sel_hi:[1,0]
	s_nop 0
	v_rcp_f32_e32 v92, v92
	v_rcp_f32_e32 v93, v93
	s_nop 0
	v_pk_mul_f32 v[88:89], v[88:89], v[92:93]
	s_nop 0
	v_cvt_pk_bf16_f32 v92, v88, v89
	s_nop 1
	v_mov_b32_dpp v93, v92 quad_perm:[1,0,3,2] row_mask:0xf bank_mask:0xf
	v_perm_b32 v88, v93, v92, v250
	v_add_u32_e32 v89, 0x40020, v163
	global_store_dword v89, v88, s[2:3] nt
	v_pk_add_f32 v[88:89], v[90:91], v[138:139] op_sel_hi:[1,0]
	s_nop 0
	v_pk_mul_f32 v[90:91], v[88:89], v[88:89]
	s_nop 0
	v_pk_fma_f32 v[90:91], v[90:91], s[88:89], v[124:125] op_sel_hi:[1,0,0] neg_lo:[1,0,0] neg_hi:[1,0,0]
	s_nop 0
	v_pk_mul_f32 v[90:91], v[88:89], v[90:91]
	s_nop 0
	v_exp_f32_e32 v90, v90
	v_exp_f32_e32 v91, v91
	s_nop 0
	v_pk_add_f32 v[90:91], v[90:91], 1.0 op_sel_hi:[1,0]
	s_nop 0
	v_rcp_f32_e32 v90, v90
	v_rcp_f32_e32 v91, v91
	s_nop 0
	v_pk_mul_f32 v[88:89], v[88:89], v[90:91]
	s_nop 0
	v_cvt_pk_bf16_f32 v90, v88, v89
	s_nop 1
	v_mov_b32_dpp v91, v90 quad_perm:[1,0,3,2] row_mask:0xf bank_mask:0xf
	v_perm_b32 v88, v91, v90, v250
	v_add_u32_e32 v89, 0x44020, v163
	global_store_dword v89, v88, s[2:3] nt
	v_pk_mul_f32 v[88:89], v[84:85], v[84:85]
	s_nop 0
	v_pk_fma_f32 v[88:89], v[88:89], s[88:89], v[124:125] op_sel_hi:[1,0,0] neg_lo:[1,0,0] neg_hi:[1,0,0]
	s_nop 0
	v_pk_mul_f32 v[88:89], v[84:85], v[88:89]
	s_nop 0
	v_exp_f32_e32 v88, v88
	v_exp_f32_e32 v89, v89
	s_nop 0
	v_pk_add_f32 v[88:89], v[88:89], 1.0 op_sel_hi:[1,0]
	s_nop 0
	v_rcp_f32_e32 v88, v88
	v_rcp_f32_e32 v89, v89
	s_nop 0
	v_pk_mul_f32 v[84:85], v[84:85], v[88:89]
	s_nop 0
	v_cvt_pk_bf16_f32 v88, v84, v85
	s_nop 1
	v_mov_b32_dpp v89, v88 quad_perm:[1,0,3,2] row_mask:0xf bank_mask:0xf
	v_perm_b32 v84, v89, v88, v250
	v_add_u32_e32 v85, 0x40100, v163
	global_store_dword v85, v84, s[2:3] nt
	v_pk_add_f32 v[84:85], v[86:87], v[136:137] op_sel_hi:[1,0]
	s_nop 0
	v_pk_mul_f32 v[86:87], v[84:85], v[84:85]
	s_nop 0
	v_pk_fma_f32 v[86:87], v[86:87], s[88:89], v[124:125] op_sel_hi:[1,0,0] neg_lo:[1,0,0] neg_hi:[1,0,0]
	s_nop 0
	v_pk_mul_f32 v[86:87], v[84:85], v[86:87]
	s_nop 0
	v_exp_f32_e32 v86, v86
	v_exp_f32_e32 v87, v87
	s_nop 0
	v_pk_add_f32 v[86:87], v[86:87], 1.0 op_sel_hi:[1,0]
	s_nop 0
	v_rcp_f32_e32 v86, v86
	v_rcp_f32_e32 v87, v87
	s_nop 0
	v_pk_mul_f32 v[84:85], v[84:85], v[86:87]
	s_nop 0
	v_cvt_pk_bf16_f32 v86, v84, v85
	s_nop 1
	v_mov_b32_dpp v87, v86 quad_perm:[1,0,3,2] row_mask:0xf bank_mask:0xf
	v_perm_b32 v84, v87, v86, v250
	v_add_u32_e32 v85, 0x44100, v163
	global_store_dword v85, v84, s[2:3] nt
	v_pk_mul_f32 v[84:85], v[80:81], v[80:81]
	s_nop 0
	v_pk_fma_f32 v[84:85], v[84:85], s[88:89], v[124:125] op_sel_hi:[1,0,0] neg_lo:[1,0,0] neg_hi:[1,0,0]
	s_nop 0
	v_pk_mul_f32 v[84:85], v[80:81], v[84:85]
	s_nop 0
	v_exp_f32_e32 v84, v84
	v_exp_f32_e32 v85, v85
	s_nop 0
	v_pk_add_f32 v[84:85], v[84:85], 1.0 op_sel_hi:[1,0]
	s_nop 0
	v_rcp_f32_e32 v84, v84
	v_rcp_f32_e32 v85, v85
	s_nop 0
	v_pk_mul_f32 v[80:81], v[80:81], v[84:85]
	s_nop 0
	v_cvt_pk_bf16_f32 v84, v80, v81
	s_nop 1
	v_mov_b32_dpp v85, v84 quad_perm:[1,0,3,2] row_mask:0xf bank_mask:0xf
	v_perm_b32 v80, v85, v84, v250
	v_add_u32_e32 v81, 0x40120, v163
	global_store_dword v81, v80, s[2:3] nt
	v_pk_add_f32 v[80:81], v[82:83], v[134:135] op_sel_hi:[1,0]
	s_nop 0
	v_pk_mul_f32 v[82:83], v[80:81], v[80:81]
	s_nop 0
	v_pk_fma_f32 v[82:83], v[82:83], s[88:89], v[124:125] op_sel_hi:[1,0,0] neg_lo:[1,0,0] neg_hi:[1,0,0]
	s_nop 0
	v_pk_mul_f32 v[82:83], v[80:81], v[82:83]
	s_nop 0
	v_exp_f32_e32 v82, v82
	v_exp_f32_e32 v83, v83
	s_nop 0
	v_pk_add_f32 v[82:83], v[82:83], 1.0 op_sel_hi:[1,0]
	s_nop 0
	v_rcp_f32_e32 v82, v82
	v_rcp_f32_e32 v83, v83
	s_nop 0
	v_pk_mul_f32 v[80:81], v[80:81], v[82:83]
	s_nop 0
	v_cvt_pk_bf16_f32 v82, v80, v81
	s_nop 1
	v_mov_b32_dpp v83, v82 quad_perm:[1,0,3,2] row_mask:0xf bank_mask:0xf
	v_perm_b32 v80, v83, v82, v250
	v_add_u32_e32 v81, 0x44120, v163
	global_store_dword v81, v80, s[2:3] nt
	v_pk_add_f32 v[76:77], v[76:77], v[140:141] op_sel_hi:[1,0]
	v_pk_add_f32 v[72:73], v[72:73], v[138:139] op_sel_hi:[1,0]
	v_pk_mul_f32 v[80:81], v[76:77], v[76:77]
	v_pk_add_f32 v[68:69], v[68:69], v[136:137] op_sel_hi:[1,0]
	v_pk_fma_f32 v[80:81], v[80:81], s[88:89], v[124:125] op_sel_hi:[1,0,0] neg_lo:[1,0,0] neg_hi:[1,0,0]
	v_pk_add_f32 v[64:65], v[64:65], v[134:135] op_sel_hi:[1,0]
	v_pk_mul_f32 v[80:81], v[76:77], v[80:81]
	s_nop 0
	v_exp_f32_e32 v80, v80
	v_exp_f32_e32 v81, v81
	s_nop 0
	v_pk_add_f32 v[80:81], v[80:81], 1.0 op_sel_hi:[1,0]
	s_nop 0
	v_rcp_f32_e32 v80, v80
	v_rcp_f32_e32 v81, v81
	s_nop 0
	v_pk_mul_f32 v[76:77], v[76:77], v[80:81]
	s_nop 0
	v_cvt_pk_bf16_f32 v80, v76, v77
	s_nop 1
	v_mov_b32_dpp v81, v80 quad_perm:[1,0,3,2] row_mask:0xf bank_mask:0xf
	v_perm_b32 v76, v81, v80, v250
	v_add_u32_e32 v77, 0x60000, v163
	global_store_dword v77, v76, s[2:3] nt
	v_pk_add_f32 v[76:77], v[78:79], v[140:141] op_sel_hi:[1,0]
	s_nop 0
	v_pk_mul_f32 v[78:79], v[76:77], v[76:77]
	s_nop 0
	v_pk_fma_f32 v[78:79], v[78:79], s[88:89], v[124:125] op_sel_hi:[1,0,0] neg_lo:[1,0,0] neg_hi:[1,0,0]
	s_nop 0
	v_pk_mul_f32 v[78:79], v[76:77], v[78:79]
	s_nop 0
	v_exp_f32_e32 v78, v78
	v_exp_f32_e32 v79, v79
	s_nop 0
	v_pk_add_f32 v[78:79], v[78:79], 1.0 op_sel_hi:[1,0]
	s_nop 0
	v_rcp_f32_e32 v78, v78
	v_rcp_f32_e32 v79, v79
	s_nop 0
	v_pk_mul_f32 v[76:77], v[76:77], v[78:79]
	s_nop 0
	v_cvt_pk_bf16_f32 v78, v76, v77
	s_nop 1
	v_mov_b32_dpp v79, v78 quad_perm:[1,0,3,2] row_mask:0xf bank_mask:0xf
	v_perm_b32 v76, v79, v78, v250
	v_add_u32_e32 v77, 0x64000, v163
	global_store_dword v77, v76, s[2:3] nt
	v_pk_mul_f32 v[76:77], v[72:73], v[72:73]
	s_nop 0
	v_pk_fma_f32 v[76:77], v[76:77], s[88:89], v[124:125] op_sel_hi:[1,0,0] neg_lo:[1,0,0] neg_hi:[1,0,0]
	s_nop 0
	v_pk_mul_f32 v[76:77], v[72:73], v[76:77]
	s_nop 0
	v_exp_f32_e32 v76, v76
	v_exp_f32_e32 v77, v77
	s_nop 0
	v_pk_add_f32 v[76:77], v[76:77], 1.0 op_sel_hi:[1,0]
	s_nop 0
	v_rcp_f32_e32 v76, v76
	v_rcp_f32_e32 v77, v77
	s_nop 0
	v_pk_mul_f32 v[72:73], v[72:73], v[76:77]
	s_nop 0
	v_cvt_pk_bf16_f32 v76, v72, v73
	s_nop 1
	v_mov_b32_dpp v77, v76 quad_perm:[1,0,3,2] row_mask:0xf bank_mask:0xf
	v_perm_b32 v72, v77, v76, v250
	v_add_u32_e32 v73, 0x60020, v163
	global_store_dword v73, v72, s[2:3] nt
	v_pk_add_f32 v[72:73], v[74:75], v[138:139] op_sel_hi:[1,0]
	s_nop 0
	v_pk_mul_f32 v[74:75], v[72:73], v[72:73]
	s_nop 0
	v_pk_fma_f32 v[74:75], v[74:75], s[88:89], v[124:125] op_sel_hi:[1,0,0] neg_lo:[1,0,0] neg_hi:[1,0,0]
	s_nop 0
	v_pk_mul_f32 v[74:75], v[72:73], v[74:75]
	s_nop 0
	v_exp_f32_e32 v74, v74
	v_exp_f32_e32 v75, v75
	s_nop 0
	v_pk_add_f32 v[74:75], v[74:75], 1.0 op_sel_hi:[1,0]
	s_nop 0
	v_rcp_f32_e32 v74, v74
	v_rcp_f32_e32 v75, v75
	s_nop 0
	v_pk_mul_f32 v[72:73], v[72:73], v[74:75]
	s_nop 0
	v_cvt_pk_bf16_f32 v74, v72, v73
	s_nop 1
	v_mov_b32_dpp v75, v74 quad_perm:[1,0,3,2] row_mask:0xf bank_mask:0xf
	v_perm_b32 v72, v75, v74, v250
	v_add_u32_e32 v73, 0x64020, v163
	global_store_dword v73, v72, s[2:3] nt
	v_pk_mul_f32 v[72:73], v[68:69], v[68:69]
	s_nop 0
	v_pk_fma_f32 v[72:73], v[72:73], s[88:89], v[124:125] op_sel_hi:[1,0,0] neg_lo:[1,0,0] neg_hi:[1,0,0]
	s_nop 0
	v_pk_mul_f32 v[72:73], v[68:69], v[72:73]
	s_nop 0
	v_exp_f32_e32 v72, v72
	v_exp_f32_e32 v73, v73
	s_nop 0
	v_pk_add_f32 v[72:73], v[72:73], 1.0 op_sel_hi:[1,0]
	s_nop 0
	v_rcp_f32_e32 v72, v72
	v_rcp_f32_e32 v73, v73
	s_nop 0
	v_pk_mul_f32 v[68:69], v[68:69], v[72:73]
	s_nop 0
	v_cvt_pk_bf16_f32 v72, v68, v69
	s_nop 1
	v_mov_b32_dpp v73, v72 quad_perm:[1,0,3,2] row_mask:0xf bank_mask:0xf
	v_perm_b32 v68, v73, v72, v250
	v_add_u32_e32 v69, 0x60100, v163
	global_store_dword v69, v68, s[2:3] nt
	v_pk_add_f32 v[68:69], v[70:71], v[136:137] op_sel_hi:[1,0]
	s_nop 0
	v_pk_mul_f32 v[70:71], v[68:69], v[68:69]
	s_nop 0
	v_pk_fma_f32 v[70:71], v[70:71], s[88:89], v[124:125] op_sel_hi:[1,0,0] neg_lo:[1,0,0] neg_hi:[1,0,0]
	s_nop 0
	v_pk_mul_f32 v[70:71], v[68:69], v[70:71]
	s_nop 0
	v_exp_f32_e32 v70, v70
	v_exp_f32_e32 v71, v71
	s_nop 0
	v_pk_add_f32 v[70:71], v[70:71], 1.0 op_sel_hi:[1,0]
	s_nop 0
	v_rcp_f32_e32 v70, v70
	v_rcp_f32_e32 v71, v71
	s_nop 0
	v_pk_mul_f32 v[68:69], v[68:69], v[70:71]
	s_nop 0
	v_cvt_pk_bf16_f32 v70, v68, v69
	s_nop 1
	v_mov_b32_dpp v71, v70 quad_perm:[1,0,3,2] row_mask:0xf bank_mask:0xf
	v_perm_b32 v68, v71, v70, v250
	v_add_u32_e32 v69, 0x64100, v163
	global_store_dword v69, v68, s[2:3] nt
	v_pk_mul_f32 v[68:69], v[64:65], v[64:65]
	s_nop 0
	v_pk_fma_f32 v[68:69], v[68:69], s[88:89], v[124:125] op_sel_hi:[1,0,0] neg_lo:[1,0,0] neg_hi:[1,0,0]
	s_nop 0
	v_pk_mul_f32 v[68:69], v[64:65], v[68:69]
	s_nop 0
	v_exp_f32_e32 v68, v68
	v_exp_f32_e32 v69, v69
	s_nop 0
	v_pk_add_f32 v[68:69], v[68:69], 1.0 op_sel_hi:[1,0]
	s_nop 0
	v_rcp_f32_e32 v68, v68
	v_rcp_f32_e32 v69, v69
	s_nop 0
	v_pk_mul_f32 v[64:65], v[64:65], v[68:69]
	s_nop 0
	v_cvt_pk_bf16_f32 v68, v64, v65
	s_nop 1
	v_mov_b32_dpp v69, v68 quad_perm:[1,0,3,2] row_mask:0xf bank_mask:0xf
	v_perm_b32 v64, v69, v68, v250
	v_add_u32_e32 v65, 0x60120, v163
	global_store_dword v65, v64, s[2:3] nt
	v_pk_add_f32 v[64:65], v[66:67], v[134:135] op_sel_hi:[1,0]
	s_nop 0
	v_pk_mul_f32 v[66:67], v[64:65], v[64:65]
	s_nop 0
	v_pk_fma_f32 v[66:67], v[66:67], s[88:89], v[124:125] op_sel_hi:[1,0,0] neg_lo:[1,0,0] neg_hi:[1,0,0]
	s_nop 0
	v_pk_mul_f32 v[66:67], v[64:65], v[66:67]
	s_nop 0
	v_exp_f32_e32 v66, v66
	v_exp_f32_e32 v67, v67
	s_nop 0
	v_pk_add_f32 v[66:67], v[66:67], 1.0 op_sel_hi:[1,0]
	s_nop 0
	v_rcp_f32_e32 v66, v66
	v_rcp_f32_e32 v67, v67
	s_nop 0
	v_pk_mul_f32 v[64:65], v[64:65], v[66:67]
	s_nop 0
	v_cvt_pk_bf16_f32 v66, v64, v65
	s_nop 1
	v_mov_b32_dpp v67, v66 quad_perm:[1,0,3,2] row_mask:0xf bank_mask:0xf
	v_perm_b32 v64, v67, v66, v250
	v_add_u32_e32 v65, 0x64120, v163
	global_store_dword v65, v64, s[2:3] nt
	v_pk_add_f32 v[60:61], v[60:61], v[140:141] op_sel_hi:[1,0]
	v_pk_add_f32 v[56:57], v[56:57], v[138:139] op_sel_hi:[1,0]
	v_pk_mul_f32 v[64:65], v[60:61], v[60:61]
	v_pk_add_f32 v[52:53], v[52:53], v[136:137] op_sel_hi:[1,0]
	v_pk_fma_f32 v[64:65], v[64:65], s[88:89], v[124:125] op_sel_hi:[1,0,0] neg_lo:[1,0,0] neg_hi:[1,0,0]
	v_pk_add_f32 v[48:49], v[48:49], v[134:135] op_sel_hi:[1,0]
	v_pk_mul_f32 v[64:65], v[60:61], v[64:65]
	s_nop 0
	v_exp_f32_e32 v64, v64
	v_exp_f32_e32 v65, v65
	s_nop 0
	v_pk_add_f32 v[64:65], v[64:65], 1.0 op_sel_hi:[1,0]
	s_nop 0
	v_rcp_f32_e32 v64, v64
	v_rcp_f32_e32 v65, v65
	s_nop 0
	v_pk_mul_f32 v[60:61], v[60:61], v[64:65]
	s_nop 0
	v_cvt_pk_bf16_f32 v64, v60, v61
	s_nop 1
	v_mov_b32_dpp v65, v64 quad_perm:[1,0,3,2] row_mask:0xf bank_mask:0xf
	v_perm_b32 v60, v65, v64, v250
	v_add_u32_e32 v61, 0x100000, v163
	global_store_dword v61, v60, s[2:3] nt
	v_pk_add_f32 v[60:61], v[62:63], v[140:141] op_sel_hi:[1,0]
	s_nop 0
	v_pk_mul_f32 v[62:63], v[60:61], v[60:61]
	s_nop 0
	v_pk_fma_f32 v[62:63], v[62:63], s[88:89], v[124:125] op_sel_hi:[1,0,0] neg_lo:[1,0,0] neg_hi:[1,0,0]
	s_nop 0
	v_pk_mul_f32 v[62:63], v[60:61], v[62:63]
	s_nop 0
	v_exp_f32_e32 v62, v62
	v_exp_f32_e32 v63, v63
	s_nop 0
	v_pk_add_f32 v[62:63], v[62:63], 1.0 op_sel_hi:[1,0]
	s_nop 0
	v_rcp_f32_e32 v62, v62
	v_rcp_f32_e32 v63, v63
	s_nop 0
	v_pk_mul_f32 v[60:61], v[60:61], v[62:63]
	s_nop 0
	v_cvt_pk_bf16_f32 v62, v60, v61
	s_nop 1
	v_mov_b32_dpp v63, v62 quad_perm:[1,0,3,2] row_mask:0xf bank_mask:0xf
	v_perm_b32 v60, v63, v62, v250
	v_add_u32_e32 v61, 0x104000, v163
	global_store_dword v61, v60, s[2:3] nt
	v_pk_mul_f32 v[60:61], v[56:57], v[56:57]
	s_nop 0
	v_pk_fma_f32 v[60:61], v[60:61], s[88:89], v[124:125] op_sel_hi:[1,0,0] neg_lo:[1,0,0] neg_hi:[1,0,0]
	s_nop 0
	v_pk_mul_f32 v[60:61], v[56:57], v[60:61]
	s_nop 0
	v_exp_f32_e32 v60, v60
	v_exp_f32_e32 v61, v61
	s_nop 0
	v_pk_add_f32 v[60:61], v[60:61], 1.0 op_sel_hi:[1,0]
	s_nop 0
	v_rcp_f32_e32 v60, v60
	v_rcp_f32_e32 v61, v61
	s_nop 0
	v_pk_mul_f32 v[56:57], v[56:57], v[60:61]
	s_nop 0
	v_cvt_pk_bf16_f32 v60, v56, v57
	s_nop 1
	v_mov_b32_dpp v61, v60 quad_perm:[1,0,3,2] row_mask:0xf bank_mask:0xf
	v_perm_b32 v56, v61, v60, v250
	v_add_u32_e32 v57, 0x100020, v163
	global_store_dword v57, v56, s[2:3] nt
	v_pk_add_f32 v[56:57], v[58:59], v[138:139] op_sel_hi:[1,0]
	s_nop 0
	v_pk_mul_f32 v[58:59], v[56:57], v[56:57]
	s_nop 0
	v_pk_fma_f32 v[58:59], v[58:59], s[88:89], v[124:125] op_sel_hi:[1,0,0] neg_lo:[1,0,0] neg_hi:[1,0,0]
	s_nop 0
	v_pk_mul_f32 v[58:59], v[56:57], v[58:59]
	s_nop 0
	v_exp_f32_e32 v58, v58
	v_exp_f32_e32 v59, v59
	s_nop 0
	v_pk_add_f32 v[58:59], v[58:59], 1.0 op_sel_hi:[1,0]
	s_nop 0
	v_rcp_f32_e32 v58, v58
	v_rcp_f32_e32 v59, v59
	s_nop 0
	v_pk_mul_f32 v[56:57], v[56:57], v[58:59]
	s_nop 0
	v_cvt_pk_bf16_f32 v58, v56, v57
	s_nop 1
	v_mov_b32_dpp v59, v58 quad_perm:[1,0,3,2] row_mask:0xf bank_mask:0xf
	v_perm_b32 v56, v59, v58, v250
	v_add_u32_e32 v57, 0x104020, v163
	global_store_dword v57, v56, s[2:3] nt
	v_pk_mul_f32 v[56:57], v[52:53], v[52:53]
	s_nop 0
	v_pk_fma_f32 v[56:57], v[56:57], s[88:89], v[124:125] op_sel_hi:[1,0,0] neg_lo:[1,0,0] neg_hi:[1,0,0]
	s_nop 0
	v_pk_mul_f32 v[56:57], v[52:53], v[56:57]
	s_nop 0
	v_exp_f32_e32 v56, v56
	v_exp_f32_e32 v57, v57
	s_nop 0
	v_pk_add_f32 v[56:57], v[56:57], 1.0 op_sel_hi:[1,0]
	s_nop 0
	v_rcp_f32_e32 v56, v56
	v_rcp_f32_e32 v57, v57
	s_nop 0
	v_pk_mul_f32 v[52:53], v[52:53], v[56:57]
	s_nop 0
	v_cvt_pk_bf16_f32 v56, v52, v53
	s_nop 1
	v_mov_b32_dpp v57, v56 quad_perm:[1,0,3,2] row_mask:0xf bank_mask:0xf
	v_perm_b32 v52, v57, v56, v250
	v_add_u32_e32 v53, 0x100100, v163
	global_store_dword v53, v52, s[2:3] nt
	v_pk_add_f32 v[52:53], v[54:55], v[136:137] op_sel_hi:[1,0]
	s_nop 0
	v_pk_mul_f32 v[54:55], v[52:53], v[52:53]
	s_nop 0
	v_pk_fma_f32 v[54:55], v[54:55], s[88:89], v[124:125] op_sel_hi:[1,0,0] neg_lo:[1,0,0] neg_hi:[1,0,0]
	s_nop 0
	v_pk_mul_f32 v[54:55], v[52:53], v[54:55]
	s_nop 0
	v_exp_f32_e32 v54, v54
	v_exp_f32_e32 v55, v55
	s_nop 0
	v_pk_add_f32 v[54:55], v[54:55], 1.0 op_sel_hi:[1,0]
	s_nop 0
	v_rcp_f32_e32 v54, v54
	v_rcp_f32_e32 v55, v55
	s_nop 0
	v_pk_mul_f32 v[52:53], v[52:53], v[54:55]
	s_nop 0
	v_cvt_pk_bf16_f32 v54, v52, v53
	s_nop 1
	v_mov_b32_dpp v55, v54 quad_perm:[1,0,3,2] row_mask:0xf bank_mask:0xf
	v_perm_b32 v52, v55, v54, v250
	v_add_u32_e32 v53, 0x104100, v163
	global_store_dword v53, v52, s[2:3] nt
	v_pk_mul_f32 v[52:53], v[48:49], v[48:49]
	s_nop 0
	v_pk_fma_f32 v[52:53], v[52:53], s[88:89], v[124:125] op_sel_hi:[1,0,0] neg_lo:[1,0,0] neg_hi:[1,0,0]
	s_nop 0
	v_pk_mul_f32 v[52:53], v[48:49], v[52:53]
	s_nop 0
	v_exp_f32_e32 v52, v52
	v_exp_f32_e32 v53, v53
	s_nop 0
	v_pk_add_f32 v[52:53], v[52:53], 1.0 op_sel_hi:[1,0]
	s_nop 0
	v_rcp_f32_e32 v52, v52
	v_rcp_f32_e32 v53, v53
	s_nop 0
	v_pk_mul_f32 v[48:49], v[48:49], v[52:53]
	s_nop 0
	v_cvt_pk_bf16_f32 v52, v48, v49
	s_nop 1
	v_mov_b32_dpp v53, v52 quad_perm:[1,0,3,2] row_mask:0xf bank_mask:0xf
	v_perm_b32 v48, v53, v52, v250
	v_add_u32_e32 v49, 0x100120, v163
	global_store_dword v49, v48, s[2:3] nt
	v_pk_add_f32 v[48:49], v[50:51], v[134:135] op_sel_hi:[1,0]
	s_nop 0
	v_pk_mul_f32 v[50:51], v[48:49], v[48:49]
	s_nop 0
	v_pk_fma_f32 v[50:51], v[50:51], s[88:89], v[124:125] op_sel_hi:[1,0,0] neg_lo:[1,0,0] neg_hi:[1,0,0]
	s_nop 0
	v_pk_mul_f32 v[50:51], v[48:49], v[50:51]
	s_nop 0
	v_exp_f32_e32 v50, v50
	v_exp_f32_e32 v51, v51
	s_nop 0
	v_pk_add_f32 v[50:51], v[50:51], 1.0 op_sel_hi:[1,0]
	s_nop 0
	v_rcp_f32_e32 v50, v50
	v_rcp_f32_e32 v51, v51
	s_nop 0
	v_pk_mul_f32 v[48:49], v[48:49], v[50:51]
	s_nop 0
	v_cvt_pk_bf16_f32 v50, v48, v49
	s_nop 1
	v_mov_b32_dpp v51, v50 quad_perm:[1,0,3,2] row_mask:0xf bank_mask:0xf
	v_perm_b32 v48, v51, v50, v250
	v_add_u32_e32 v49, 0x104120, v163
	global_store_dword v49, v48, s[2:3] nt
	v_pk_add_f32 v[44:45], v[44:45], v[140:141] op_sel_hi:[1,0]
	v_pk_add_f32 v[40:41], v[40:41], v[138:139] op_sel_hi:[1,0]
	v_pk_mul_f32 v[48:49], v[44:45], v[44:45]
	v_pk_add_f32 v[36:37], v[36:37], v[136:137] op_sel_hi:[1,0]
	v_pk_fma_f32 v[48:49], v[48:49], s[88:89], v[124:125] op_sel_hi:[1,0,0] neg_lo:[1,0,0] neg_hi:[1,0,0]
	v_pk_add_f32 v[32:33], v[32:33], v[134:135] op_sel_hi:[1,0]
	v_pk_mul_f32 v[48:49], v[44:45], v[48:49]
	s_nop 0
	v_exp_f32_e32 v48, v48
	v_exp_f32_e32 v49, v49
	s_nop 0
	v_pk_add_f32 v[48:49], v[48:49], 1.0 op_sel_hi:[1,0]
	s_nop 0
	v_rcp_f32_e32 v48, v48
	v_rcp_f32_e32 v49, v49
	s_nop 0
	v_pk_mul_f32 v[44:45], v[44:45], v[48:49]
	s_nop 0
	v_cvt_pk_bf16_f32 v48, v44, v45
	s_nop 1
	v_mov_b32_dpp v49, v48 quad_perm:[1,0,3,2] row_mask:0xf bank_mask:0xf
	v_perm_b32 v44, v49, v48, v250
	v_add_u32_e32 v45, 0x120000, v163
	global_store_dword v45, v44, s[2:3] nt
	v_pk_add_f32 v[44:45], v[46:47], v[140:141] op_sel_hi:[1,0]
	s_nop 0
	v_pk_mul_f32 v[46:47], v[44:45], v[44:45]
	s_nop 0
	v_pk_fma_f32 v[46:47], v[46:47], s[88:89], v[124:125] op_sel_hi:[1,0,0] neg_lo:[1,0,0] neg_hi:[1,0,0]
	s_nop 0
	v_pk_mul_f32 v[46:47], v[44:45], v[46:47]
	s_nop 0
	v_exp_f32_e32 v46, v46
	v_exp_f32_e32 v47, v47
	s_nop 0
	v_pk_add_f32 v[46:47], v[46:47], 1.0 op_sel_hi:[1,0]
	s_nop 0
	v_rcp_f32_e32 v46, v46
	v_rcp_f32_e32 v47, v47
	s_nop 0
	v_pk_mul_f32 v[44:45], v[44:45], v[46:47]
	s_nop 0
	v_cvt_pk_bf16_f32 v46, v44, v45
	s_nop 1
	v_mov_b32_dpp v47, v46 quad_perm:[1,0,3,2] row_mask:0xf bank_mask:0xf
	v_perm_b32 v44, v47, v46, v250
	v_add_u32_e32 v45, 0x124000, v163
	global_store_dword v45, v44, s[2:3] nt
	v_pk_mul_f32 v[44:45], v[40:41], v[40:41]
	s_nop 0
	v_pk_fma_f32 v[44:45], v[44:45], s[88:89], v[124:125] op_sel_hi:[1,0,0] neg_lo:[1,0,0] neg_hi:[1,0,0]
	s_nop 0
	v_pk_mul_f32 v[44:45], v[40:41], v[44:45]
	s_nop 0
	v_exp_f32_e32 v44, v44
	v_exp_f32_e32 v45, v45
	s_nop 0
	v_pk_add_f32 v[44:45], v[44:45], 1.0 op_sel_hi:[1,0]
	s_nop 0
	v_rcp_f32_e32 v44, v44
	v_rcp_f32_e32 v45, v45
	s_nop 0
	v_pk_mul_f32 v[40:41], v[40:41], v[44:45]
	s_nop 0
	v_cvt_pk_bf16_f32 v44, v40, v41
	s_nop 1
	v_mov_b32_dpp v45, v44 quad_perm:[1,0,3,2] row_mask:0xf bank_mask:0xf
	v_perm_b32 v40, v45, v44, v250
	v_add_u32_e32 v41, 0x120020, v163
	global_store_dword v41, v40, s[2:3] nt
	v_pk_add_f32 v[40:41], v[42:43], v[138:139] op_sel_hi:[1,0]
	s_nop 0
	v_pk_mul_f32 v[42:43], v[40:41], v[40:41]
	s_nop 0
	v_pk_fma_f32 v[42:43], v[42:43], s[88:89], v[124:125] op_sel_hi:[1,0,0] neg_lo:[1,0,0] neg_hi:[1,0,0]
	s_nop 0
	v_pk_mul_f32 v[42:43], v[40:41], v[42:43]
	s_nop 0
	v_exp_f32_e32 v42, v42
	v_exp_f32_e32 v43, v43
	s_nop 0
	v_pk_add_f32 v[42:43], v[42:43], 1.0 op_sel_hi:[1,0]
	s_nop 0
	v_rcp_f32_e32 v42, v42
	v_rcp_f32_e32 v43, v43
	s_nop 0
	v_pk_mul_f32 v[40:41], v[40:41], v[42:43]
	s_nop 0
	v_cvt_pk_bf16_f32 v42, v40, v41
	s_nop 1
	v_mov_b32_dpp v43, v42 quad_perm:[1,0,3,2] row_mask:0xf bank_mask:0xf
	v_perm_b32 v40, v43, v42, v250
	v_add_u32_e32 v41, 0x124020, v163
	global_store_dword v41, v40, s[2:3] nt
	v_pk_mul_f32 v[40:41], v[36:37], v[36:37]
	s_nop 0
	v_pk_fma_f32 v[40:41], v[40:41], s[88:89], v[124:125] op_sel_hi:[1,0,0] neg_lo:[1,0,0] neg_hi:[1,0,0]
	s_nop 0
	v_pk_mul_f32 v[40:41], v[36:37], v[40:41]
	s_nop 0
	v_exp_f32_e32 v40, v40
	v_exp_f32_e32 v41, v41
	s_nop 0
	v_pk_add_f32 v[40:41], v[40:41], 1.0 op_sel_hi:[1,0]
	s_nop 0
	v_rcp_f32_e32 v40, v40
	v_rcp_f32_e32 v41, v41
	s_nop 0
	v_pk_mul_f32 v[36:37], v[36:37], v[40:41]
	s_nop 0
	v_cvt_pk_bf16_f32 v40, v36, v37
	s_nop 1
	v_mov_b32_dpp v41, v40 quad_perm:[1,0,3,2] row_mask:0xf bank_mask:0xf
	v_perm_b32 v36, v41, v40, v250
	v_add_u32_e32 v37, 0x120100, v163
	global_store_dword v37, v36, s[2:3] nt
	v_pk_add_f32 v[36:37], v[38:39], v[136:137] op_sel_hi:[1,0]
	s_nop 0
	v_pk_mul_f32 v[38:39], v[36:37], v[36:37]
	s_nop 0
	v_pk_fma_f32 v[38:39], v[38:39], s[88:89], v[124:125] op_sel_hi:[1,0,0] neg_lo:[1,0,0] neg_hi:[1,0,0]
	s_nop 0
	v_pk_mul_f32 v[38:39], v[36:37], v[38:39]
	s_nop 0
	v_exp_f32_e32 v38, v38
	v_exp_f32_e32 v39, v39
	s_nop 0
	v_pk_add_f32 v[38:39], v[38:39], 1.0 op_sel_hi:[1,0]
	s_nop 0
	v_rcp_f32_e32 v38, v38
	v_rcp_f32_e32 v39, v39
	s_nop 0
	v_pk_mul_f32 v[36:37], v[36:37], v[38:39]
	s_nop 0
	v_cvt_pk_bf16_f32 v38, v36, v37
	s_nop 1
	v_mov_b32_dpp v39, v38 quad_perm:[1,0,3,2] row_mask:0xf bank_mask:0xf
	v_perm_b32 v36, v39, v38, v250
	v_add_u32_e32 v37, 0x124100, v163
	global_store_dword v37, v36, s[2:3] nt
	v_pk_mul_f32 v[36:37], v[32:33], v[32:33]
	s_nop 0
	v_pk_fma_f32 v[36:37], v[36:37], s[88:89], v[124:125] op_sel_hi:[1,0,0] neg_lo:[1,0,0] neg_hi:[1,0,0]
	s_nop 0
	v_pk_mul_f32 v[36:37], v[32:33], v[36:37]
	s_nop 0
	v_exp_f32_e32 v36, v36
	v_exp_f32_e32 v37, v37
	s_nop 0
	v_pk_add_f32 v[36:37], v[36:37], 1.0 op_sel_hi:[1,0]
	s_nop 0
	v_rcp_f32_e32 v36, v36
	v_rcp_f32_e32 v37, v37
	s_nop 0
	v_pk_mul_f32 v[32:33], v[32:33], v[36:37]
	s_nop 0
	v_cvt_pk_bf16_f32 v36, v32, v33
	s_nop 1
	v_mov_b32_dpp v37, v36 quad_perm:[1,0,3,2] row_mask:0xf bank_mask:0xf
	v_perm_b32 v32, v37, v36, v250
	v_add_u32_e32 v33, 0x120120, v163
	global_store_dword v33, v32, s[2:3] nt
	v_pk_add_f32 v[32:33], v[34:35], v[134:135] op_sel_hi:[1,0]
	s_nop 0
	v_pk_mul_f32 v[34:35], v[32:33], v[32:33]
	s_nop 0
	v_pk_fma_f32 v[34:35], v[34:35], s[88:89], v[124:125] op_sel_hi:[1,0,0] neg_lo:[1,0,0] neg_hi:[1,0,0]
	s_nop 0
	v_pk_mul_f32 v[34:35], v[32:33], v[34:35]
	s_nop 0
	v_exp_f32_e32 v34, v34
	v_exp_f32_e32 v35, v35
	s_nop 0
	v_pk_add_f32 v[34:35], v[34:35], 1.0 op_sel_hi:[1,0]
	s_nop 0
	v_rcp_f32_e32 v34, v34
	v_rcp_f32_e32 v35, v35
	s_nop 0
	v_pk_mul_f32 v[32:33], v[32:33], v[34:35]
	s_nop 0
	v_cvt_pk_bf16_f32 v34, v32, v33
	s_nop 1
	v_mov_b32_dpp v35, v34 quad_perm:[1,0,3,2] row_mask:0xf bank_mask:0xf
	v_perm_b32 v32, v35, v34, v250
	v_add_u32_e32 v33, 0x124120, v163
	global_store_dword v33, v32, s[2:3] nt
	v_pk_add_f32 v[28:29], v[28:29], v[140:141] op_sel_hi:[1,0]
	v_pk_add_f32 v[24:25], v[24:25], v[138:139] op_sel_hi:[1,0]
	v_pk_mul_f32 v[32:33], v[28:29], v[28:29]
	v_pk_add_f32 v[20:21], v[20:21], v[136:137] op_sel_hi:[1,0]
	v_pk_fma_f32 v[32:33], v[32:33], s[88:89], v[124:125] op_sel_hi:[1,0,0] neg_lo:[1,0,0] neg_hi:[1,0,0]
	v_pk_add_f32 v[16:17], v[16:17], v[134:135] op_sel_hi:[1,0]
	v_pk_mul_f32 v[32:33], v[28:29], v[32:33]
	s_nop 0
	v_exp_f32_e32 v32, v32
	v_exp_f32_e32 v33, v33
	s_nop 0
	v_pk_add_f32 v[32:33], v[32:33], 1.0 op_sel_hi:[1,0]
	s_nop 0
	v_rcp_f32_e32 v32, v32
	v_rcp_f32_e32 v33, v33
	s_nop 0
	v_pk_mul_f32 v[28:29], v[28:29], v[32:33]
	s_nop 0
	v_cvt_pk_bf16_f32 v32, v28, v29
	s_nop 1
	v_mov_b32_dpp v33, v32 quad_perm:[1,0,3,2] row_mask:0xf bank_mask:0xf
	v_perm_b32 v28, v33, v32, v250
	v_add_u32_e32 v29, 0x140000, v163
	global_store_dword v29, v28, s[2:3] nt
	v_pk_add_f32 v[28:29], v[30:31], v[140:141] op_sel_hi:[1,0]
	s_nop 0
	v_pk_mul_f32 v[30:31], v[28:29], v[28:29]
	s_nop 0
	v_pk_fma_f32 v[30:31], v[30:31], s[88:89], v[124:125] op_sel_hi:[1,0,0] neg_lo:[1,0,0] neg_hi:[1,0,0]
	s_nop 0
	v_pk_mul_f32 v[30:31], v[28:29], v[30:31]
	s_nop 0
	v_exp_f32_e32 v30, v30
	v_exp_f32_e32 v31, v31
	s_nop 0
	v_pk_add_f32 v[30:31], v[30:31], 1.0 op_sel_hi:[1,0]
	s_nop 0
	v_rcp_f32_e32 v30, v30
	v_rcp_f32_e32 v31, v31
	s_nop 0
	v_pk_mul_f32 v[28:29], v[28:29], v[30:31]
	s_nop 0
	v_cvt_pk_bf16_f32 v30, v28, v29
	s_nop 1
	v_mov_b32_dpp v31, v30 quad_perm:[1,0,3,2] row_mask:0xf bank_mask:0xf
	v_perm_b32 v28, v31, v30, v250
	v_add_u32_e32 v29, 0x144000, v163
	global_store_dword v29, v28, s[2:3] nt
	v_pk_mul_f32 v[28:29], v[24:25], v[24:25]
	s_nop 0
	v_pk_fma_f32 v[28:29], v[28:29], s[88:89], v[124:125] op_sel_hi:[1,0,0] neg_lo:[1,0,0] neg_hi:[1,0,0]
	s_nop 0
	v_pk_mul_f32 v[28:29], v[24:25], v[28:29]
	s_nop 0
	v_exp_f32_e32 v28, v28
	v_exp_f32_e32 v29, v29
	s_nop 0
	v_pk_add_f32 v[28:29], v[28:29], 1.0 op_sel_hi:[1,0]
	s_nop 0
	v_rcp_f32_e32 v28, v28
	v_rcp_f32_e32 v29, v29
	s_nop 0
	v_pk_mul_f32 v[24:25], v[24:25], v[28:29]
	s_nop 0
	v_cvt_pk_bf16_f32 v28, v24, v25
	s_nop 1
	v_mov_b32_dpp v29, v28 quad_perm:[1,0,3,2] row_mask:0xf bank_mask:0xf
	v_perm_b32 v24, v29, v28, v250
	v_add_u32_e32 v25, 0x140020, v163
	global_store_dword v25, v24, s[2:3] nt
	v_pk_add_f32 v[24:25], v[26:27], v[138:139] op_sel_hi:[1,0]
	s_nop 0
	v_pk_mul_f32 v[26:27], v[24:25], v[24:25]
	s_nop 0
	v_pk_fma_f32 v[26:27], v[26:27], s[88:89], v[124:125] op_sel_hi:[1,0,0] neg_lo:[1,0,0] neg_hi:[1,0,0]
	s_nop 0
	v_pk_mul_f32 v[26:27], v[24:25], v[26:27]
	s_nop 0
	v_exp_f32_e32 v26, v26
	v_exp_f32_e32 v27, v27
	s_nop 0
	v_pk_add_f32 v[26:27], v[26:27], 1.0 op_sel_hi:[1,0]
	s_nop 0
	v_rcp_f32_e32 v26, v26
	v_rcp_f32_e32 v27, v27
	s_nop 0
	v_pk_mul_f32 v[24:25], v[24:25], v[26:27]
	s_nop 0
	v_cvt_pk_bf16_f32 v26, v24, v25
	s_nop 1
	v_mov_b32_dpp v27, v26 quad_perm:[1,0,3,2] row_mask:0xf bank_mask:0xf
	v_perm_b32 v24, v27, v26, v250
	v_add_u32_e32 v25, 0x144020, v163
	global_store_dword v25, v24, s[2:3] nt
	v_pk_mul_f32 v[24:25], v[20:21], v[20:21]
	s_nop 0
	v_pk_fma_f32 v[24:25], v[24:25], s[88:89], v[124:125] op_sel_hi:[1,0,0] neg_lo:[1,0,0] neg_hi:[1,0,0]
	s_nop 0
	v_pk_mul_f32 v[24:25], v[20:21], v[24:25]
	s_nop 0
	v_exp_f32_e32 v24, v24
	v_exp_f32_e32 v25, v25
	s_nop 0
	v_pk_add_f32 v[24:25], v[24:25], 1.0 op_sel_hi:[1,0]
	s_nop 0
	v_rcp_f32_e32 v24, v24
	v_rcp_f32_e32 v25, v25
	s_nop 0
	v_pk_mul_f32 v[20:21], v[20:21], v[24:25]
	s_nop 0
	v_cvt_pk_bf16_f32 v24, v20, v21
	s_nop 1
	v_mov_b32_dpp v25, v24 quad_perm:[1,0,3,2] row_mask:0xf bank_mask:0xf
	v_perm_b32 v20, v25, v24, v250
	v_add_u32_e32 v21, 0x140100, v163
	global_store_dword v21, v20, s[2:3] nt
	v_pk_add_f32 v[20:21], v[22:23], v[136:137] op_sel_hi:[1,0]
	s_nop 0
	v_pk_mul_f32 v[22:23], v[20:21], v[20:21]
	s_nop 0
	v_pk_fma_f32 v[22:23], v[22:23], s[88:89], v[124:125] op_sel_hi:[1,0,0] neg_lo:[1,0,0] neg_hi:[1,0,0]
	s_nop 0
	v_pk_mul_f32 v[22:23], v[20:21], v[22:23]
	s_nop 0
	v_exp_f32_e32 v22, v22
	v_exp_f32_e32 v23, v23
	s_nop 0
	v_pk_add_f32 v[22:23], v[22:23], 1.0 op_sel_hi:[1,0]
	s_nop 0
	v_rcp_f32_e32 v22, v22
	v_rcp_f32_e32 v23, v23
	s_nop 0
	v_pk_mul_f32 v[20:21], v[20:21], v[22:23]
	s_nop 0
	v_cvt_pk_bf16_f32 v22, v20, v21
	s_nop 1
	v_mov_b32_dpp v23, v22 quad_perm:[1,0,3,2] row_mask:0xf bank_mask:0xf
	v_perm_b32 v20, v23, v22, v250
	v_add_u32_e32 v21, 0x144100, v163
	global_store_dword v21, v20, s[2:3] nt
	v_pk_mul_f32 v[20:21], v[16:17], v[16:17]
	s_nop 0
	v_pk_fma_f32 v[20:21], v[20:21], s[88:89], v[124:125] op_sel_hi:[1,0,0] neg_lo:[1,0,0] neg_hi:[1,0,0]
	s_nop 0
	v_pk_mul_f32 v[20:21], v[16:17], v[20:21]
	s_nop 0
	v_exp_f32_e32 v20, v20
	v_exp_f32_e32 v21, v21
	s_nop 0
	v_pk_add_f32 v[20:21], v[20:21], 1.0 op_sel_hi:[1,0]
	s_nop 0
	v_rcp_f32_e32 v20, v20
	v_rcp_f32_e32 v21, v21
	s_nop 0
	v_pk_mul_f32 v[16:17], v[16:17], v[20:21]
	s_nop 0
	v_cvt_pk_bf16_f32 v20, v16, v17
	s_nop 1
	v_mov_b32_dpp v21, v20 quad_perm:[1,0,3,2] row_mask:0xf bank_mask:0xf
	v_perm_b32 v16, v21, v20, v250
	v_add_u32_e32 v17, 0x140120, v163
	global_store_dword v17, v16, s[2:3] nt
	v_pk_add_f32 v[16:17], v[18:19], v[134:135] op_sel_hi:[1,0]
	s_nop 0
	v_pk_mul_f32 v[18:19], v[16:17], v[16:17]
	s_nop 0
	v_pk_fma_f32 v[18:19], v[18:19], s[88:89], v[124:125] op_sel_hi:[1,0,0] neg_lo:[1,0,0] neg_hi:[1,0,0]
	s_nop 0
	v_pk_mul_f32 v[18:19], v[16:17], v[18:19]
	s_nop 0
	v_exp_f32_e32 v18, v18
	v_exp_f32_e32 v19, v19
	s_nop 0
	v_pk_add_f32 v[18:19], v[18:19], 1.0 op_sel_hi:[1,0]
	s_nop 0
	v_rcp_f32_e32 v18, v18
	v_rcp_f32_e32 v19, v19
	s_nop 0
	v_pk_mul_f32 v[16:17], v[16:17], v[18:19]
	s_nop 0
	v_cvt_pk_bf16_f32 v18, v16, v17
	s_nop 1
	v_mov_b32_dpp v19, v18 quad_perm:[1,0,3,2] row_mask:0xf bank_mask:0xf
	v_perm_b32 v16, v19, v18, v250
	v_add_u32_e32 v17, 0x144120, v163
	global_store_dword v17, v16, s[2:3] nt
	v_pk_add_f32 v[12:13], v[12:13], v[140:141] op_sel_hi:[1,0]
	v_pk_add_f32 v[8:9], v[8:9], v[138:139] op_sel_hi:[1,0]
	v_pk_mul_f32 v[16:17], v[12:13], v[12:13]
	v_pk_add_f32 v[4:5], v[4:5], v[136:137] op_sel_hi:[1,0]
	v_pk_fma_f32 v[16:17], v[16:17], s[88:89], v[124:125] op_sel_hi:[1,0,0] neg_lo:[1,0,0] neg_hi:[1,0,0]
	v_pk_add_f32 v[0:1], v[0:1], v[134:135] op_sel_hi:[1,0]
	v_pk_mul_f32 v[16:17], v[12:13], v[16:17]
	s_nop 0
	v_exp_f32_e32 v16, v16
	v_exp_f32_e32 v17, v17
	s_nop 0
	v_pk_add_f32 v[16:17], v[16:17], 1.0 op_sel_hi:[1,0]
	s_nop 0
	v_rcp_f32_e32 v16, v16
	v_rcp_f32_e32 v17, v17
	s_nop 0
	v_pk_mul_f32 v[12:13], v[12:13], v[16:17]
	s_nop 0
	v_cvt_pk_bf16_f32 v16, v12, v13
	s_nop 1
	v_mov_b32_dpp v17, v16 quad_perm:[1,0,3,2] row_mask:0xf bank_mask:0xf
	v_perm_b32 v12, v17, v16, v250
	v_add_u32_e32 v13, 0x160000, v163
	global_store_dword v13, v12, s[2:3] nt
	v_pk_add_f32 v[12:13], v[14:15], v[140:141] op_sel_hi:[1,0]
	s_nop 0
	v_pk_mul_f32 v[14:15], v[12:13], v[12:13]
	s_nop 0
	v_pk_fma_f32 v[14:15], v[14:15], s[88:89], v[124:125] op_sel_hi:[1,0,0] neg_lo:[1,0,0] neg_hi:[1,0,0]
	s_nop 0
	v_pk_mul_f32 v[14:15], v[12:13], v[14:15]
	s_nop 0
	v_exp_f32_e32 v14, v14
	v_exp_f32_e32 v15, v15
	s_nop 0
	v_pk_add_f32 v[14:15], v[14:15], 1.0 op_sel_hi:[1,0]
	s_nop 0
	v_rcp_f32_e32 v14, v14
	v_rcp_f32_e32 v15, v15
	s_nop 0
	v_pk_mul_f32 v[12:13], v[12:13], v[14:15]
	s_nop 0
	v_cvt_pk_bf16_f32 v14, v12, v13
	s_nop 1
	v_mov_b32_dpp v15, v14 quad_perm:[1,0,3,2] row_mask:0xf bank_mask:0xf
	v_perm_b32 v12, v15, v14, v250
	v_add_u32_e32 v13, 0x164000, v163
	global_store_dword v13, v12, s[2:3] nt
	v_pk_mul_f32 v[12:13], v[8:9], v[8:9]
	s_nop 0
	v_pk_fma_f32 v[12:13], v[12:13], s[88:89], v[124:125] op_sel_hi:[1,0,0] neg_lo:[1,0,0] neg_hi:[1,0,0]
	s_nop 0
	v_pk_mul_f32 v[12:13], v[8:9], v[12:13]
	s_nop 0
	v_exp_f32_e32 v12, v12
	v_exp_f32_e32 v13, v13
	s_nop 0
	v_pk_add_f32 v[12:13], v[12:13], 1.0 op_sel_hi:[1,0]
	s_nop 0
	v_rcp_f32_e32 v12, v12
	v_rcp_f32_e32 v13, v13
	s_nop 0
	v_pk_mul_f32 v[8:9], v[8:9], v[12:13]
	s_nop 0
	v_cvt_pk_bf16_f32 v12, v8, v9
	s_nop 1
	v_mov_b32_dpp v13, v12 quad_perm:[1,0,3,2] row_mask:0xf bank_mask:0xf
	v_perm_b32 v8, v13, v12, v250
	v_add_u32_e32 v9, 0x160020, v163
	global_store_dword v9, v8, s[2:3] nt
	v_pk_add_f32 v[8:9], v[10:11], v[138:139] op_sel_hi:[1,0]
	s_nop 0
	v_pk_mul_f32 v[10:11], v[8:9], v[8:9]
	s_nop 0
	v_pk_fma_f32 v[10:11], v[10:11], s[88:89], v[124:125] op_sel_hi:[1,0,0] neg_lo:[1,0,0] neg_hi:[1,0,0]
	s_nop 0
	v_pk_mul_f32 v[10:11], v[8:9], v[10:11]
	s_nop 0
	v_exp_f32_e32 v10, v10
	v_exp_f32_e32 v11, v11
	s_nop 0
	v_pk_add_f32 v[10:11], v[10:11], 1.0 op_sel_hi:[1,0]
	s_nop 0
	v_rcp_f32_e32 v10, v10
	v_rcp_f32_e32 v11, v11
	s_nop 0
	v_pk_mul_f32 v[8:9], v[8:9], v[10:11]
	s_nop 0
	v_cvt_pk_bf16_f32 v10, v8, v9
	s_nop 1
	v_mov_b32_dpp v11, v10 quad_perm:[1,0,3,2] row_mask:0xf bank_mask:0xf
	v_perm_b32 v8, v11, v10, v250
	v_add_u32_e32 v9, 0x164020, v163
	global_store_dword v9, v8, s[2:3] nt
	v_pk_mul_f32 v[8:9], v[4:5], v[4:5]
	s_nop 0
	v_pk_fma_f32 v[8:9], v[8:9], s[88:89], v[124:125] op_sel_hi:[1,0,0] neg_lo:[1,0,0] neg_hi:[1,0,0]
	s_nop 0
	v_pk_mul_f32 v[8:9], v[4:5], v[8:9]
	s_nop 0
	v_exp_f32_e32 v8, v8
	v_exp_f32_e32 v9, v9
	s_nop 0
	v_pk_add_f32 v[8:9], v[8:9], 1.0 op_sel_hi:[1,0]
	s_nop 0
	v_rcp_f32_e32 v8, v8
	v_rcp_f32_e32 v9, v9
	s_nop 0
	v_pk_mul_f32 v[4:5], v[4:5], v[8:9]
	s_nop 0
	v_cvt_pk_bf16_f32 v8, v4, v5
	s_nop 1
	v_mov_b32_dpp v9, v8 quad_perm:[1,0,3,2] row_mask:0xf bank_mask:0xf
	v_perm_b32 v4, v9, v8, v250
	v_add_u32_e32 v5, 0x160100, v163
	global_store_dword v5, v4, s[2:3] nt
	v_pk_add_f32 v[4:5], v[6:7], v[136:137] op_sel_hi:[1,0]
	s_nop 0
	v_pk_mul_f32 v[6:7], v[4:5], v[4:5]
	s_nop 0
	v_pk_fma_f32 v[6:7], v[6:7], s[88:89], v[124:125] op_sel_hi:[1,0,0] neg_lo:[1,0,0] neg_hi:[1,0,0]
	s_nop 0
	v_pk_mul_f32 v[6:7], v[4:5], v[6:7]
	s_nop 0
	v_exp_f32_e32 v6, v6
	v_exp_f32_e32 v7, v7
	s_nop 0
	v_pk_add_f32 v[6:7], v[6:7], 1.0 op_sel_hi:[1,0]
	s_nop 0
	v_rcp_f32_e32 v6, v6
	v_rcp_f32_e32 v7, v7
	s_nop 0
	v_pk_mul_f32 v[4:5], v[4:5], v[6:7]
	s_nop 0
	v_cvt_pk_bf16_f32 v6, v4, v5
	s_nop 1
	v_mov_b32_dpp v7, v6 quad_perm:[1,0,3,2] row_mask:0xf bank_mask:0xf
	v_perm_b32 v4, v7, v6, v250
	v_add_u32_e32 v5, 0x164100, v163
	global_store_dword v5, v4, s[2:3] nt
	v_pk_mul_f32 v[4:5], v[0:1], v[0:1]
	s_nop 0
	v_pk_fma_f32 v[4:5], v[4:5], s[88:89], v[124:125] op_sel_hi:[1,0,0] neg_lo:[1,0,0] neg_hi:[1,0,0]
	s_nop 0
	v_pk_mul_f32 v[4:5], v[0:1], v[4:5]
	s_nop 0
	v_exp_f32_e32 v4, v4
	v_exp_f32_e32 v5, v5
	s_nop 0
	v_pk_add_f32 v[4:5], v[4:5], 1.0 op_sel_hi:[1,0]
	s_nop 0
	v_rcp_f32_e32 v4, v4
	v_rcp_f32_e32 v5, v5
	s_nop 0
	v_pk_mul_f32 v[0:1], v[0:1], v[4:5]
	s_nop 0
	v_cvt_pk_bf16_f32 v4, v0, v1
	s_nop 1
	v_mov_b32_dpp v5, v4 quad_perm:[1,0,3,2] row_mask:0xf bank_mask:0xf
	v_perm_b32 v0, v5, v4, v250
	v_add_u32_e32 v1, 0x160120, v163
	global_store_dword v1, v0, s[2:3] nt
	v_pk_add_f32 v[0:1], v[2:3], v[134:135] op_sel_hi:[1,0]
	s_nop 0
	v_pk_mul_f32 v[2:3], v[0:1], v[0:1]
	s_nop 0
	v_pk_fma_f32 v[2:3], v[2:3], s[88:89], v[124:125] op_sel_hi:[1,0,0] neg_lo:[1,0,0] neg_hi:[1,0,0]
	s_nop 0
	v_pk_mul_f32 v[2:3], v[0:1], v[2:3]
	s_nop 0
	v_exp_f32_e32 v2, v2
	v_exp_f32_e32 v3, v3
	s_nop 0
	v_pk_add_f32 v[2:3], v[2:3], 1.0 op_sel_hi:[1,0]
	s_nop 0
	v_rcp_f32_e32 v2, v2
	v_rcp_f32_e32 v3, v3
	s_nop 0
	v_pk_mul_f32 v[0:1], v[0:1], v[2:3]
	s_nop 0
	v_cvt_pk_bf16_f32 v2, v0, v1
	s_nop 1
	v_mov_b32_dpp v3, v2 quad_perm:[1,0,3,2] row_mask:0xf bank_mask:0xf
	v_perm_b32 v0, v3, v2, v250
	v_add_u32_e32 v1, 0x164120, v163
	global_store_dword v1, v0, s[2:3] nt
	s_and_b64 vcc, exec, s[24:25]
	s_mov_b32 s38, s68
	s_mov_b32 s40, s70
	s_cbranch_vccnz .LBB0_1548

.LBB0_1569:
	s_and_b32 s25, s42, 0x300
	v_or_b32_e32 v158, s25, v149
	v_add_lshl_u32 v159, v148, s40, 11
	v_lshl_or_b32 v227, v158, 1, v159
	s_cmpk_gt_i32 s42, 0x3ff
	s_mov_b64 s[40:41], -1
	v_add_u32_e32 v226, 0x1000, v227
	v_or_b32_e32 v225, 32, v227
	v_add_u32_e32 v224, 0x1020, v227
	v_or_b32_e32 v223, 0x100, v227
	v_add_u32_e32 v222, 0x1100, v227
	v_or_b32_e32 v221, 0x120, v227
	v_add_u32_e32 v220, 0x1120, v227
	v_add_u32_e32 v219, 0x8000, v227
	v_add_u32_e32 v218, 0x9000, v227
	v_add_u32_e32 v217, 0x8020, v227
	v_add_u32_e32 v216, 0x9020, v227
	v_add_u32_e32 v215, 0x8100, v227
	v_add_u32_e32 v214, 0x9100, v227
	v_add_u32_e32 v213, 0x8120, v227
	v_add_u32_e32 v212, 0x9120, v227
	v_add_u32_e32 v211, 0x10000, v227
	v_add_u32_e32 v210, 0x11000, v227
	v_add_u32_e32 v209, 0x10020, v227
	v_add_u32_e32 v208, 0x11020, v227
	v_add_u32_e32 v207, 0x10100, v227
	v_add_u32_e32 v206, 0x11100, v227
	v_add_u32_e32 v205, 0x10120, v227
	v_add_u32_e32 v204, 0x11120, v227
	v_add_u32_e32 v203, 0x18000, v227
	v_add_u32_e32 v202, 0x19000, v227
	v_add_u32_e32 v201, 0x18020, v227
	v_add_u32_e32 v200, 0x19020, v227
	v_add_u32_e32 v199, 0x18100, v227
	v_add_u32_e32 v198, 0x19100, v227
	v_add_u32_e32 v197, 0x18120, v227
	v_add_u32_e32 v196, 0x19120, v227
	v_add_u32_e32 v195, 0x40000, v227
	v_add_u32_e32 v194, 0x41000, v227
	v_add_u32_e32 v193, 0x40020, v227
	v_add_u32_e32 v192, 0x41020, v227
	v_add_u32_e32 v191, 0x40100, v227
	v_add_u32_e32 v190, 0x41100, v227
	v_add_u32_e32 v189, 0x40120, v227
	v_add_u32_e32 v188, 0x41120, v227
	v_add_u32_e32 v187, 0x48000, v227
	v_add_u32_e32 v186, 0x49000, v227
	v_add_u32_e32 v185, 0x48020, v227
	v_add_u32_e32 v184, 0x49020, v227
	v_add_u32_e32 v183, 0x48100, v227
	v_add_u32_e32 v182, 0x49100, v227
	v_add_u32_e32 v181, 0x48120, v227
	v_add_u32_e32 v180, 0x49120, v227
	v_add_u32_e32 v173, 0x50000, v227
	v_add_u32_e32 v172, 0x51000, v227
	v_add_u32_e32 v171, 0x50020, v227
	v_add_u32_e32 v170, 0x51020, v227
	v_add_u32_e32 v169, 0x50100, v227
	v_add_u32_e32 v168, 0x51100, v227
	v_add_u32_e32 v167, 0x50120, v227
	v_add_u32_e32 v166, 0x51120, v227
	v_add_u32_e32 v165, 0x58000, v227
	v_add_u32_e32 v164, 0x59000, v227
	v_add_u32_e32 v163, 0x58020, v227
	v_add_u32_e32 v162, 0x59020, v227
	v_add_u32_e32 v161, 0x58100, v227
	v_add_u32_e32 v160, 0x59100, v227
	v_add_u32_e32 v159, 0x58120, v227
	v_add_u32_e32 v158, 0x59120, v227
	s_cbranch_scc1 .LBB0_1571
	v_cvt_pk_bf16_f32 v178, v124, v125
	s_nop 1
	v_mov_b32_dpp v179, v178 quad_perm:[1,0,3,2] row_mask:0xf bank_mask:0xf
	v_perm_b32 v178, v179, v178, v250
	global_store_dword v227, v178, s[2:3] nt
	v_cvt_pk_bf16_f32 v178, v126, v127
	s_nop 1
	v_mov_b32_dpp v179, v178 quad_perm:[1,0,3,2] row_mask:0xf bank_mask:0xf
	v_perm_b32 v178, v179, v178, v250
	global_store_dword v226, v178, s[2:3] nt
	v_cvt_pk_bf16_f32 v178, v120, v121
	s_nop 1
	v_mov_b32_dpp v179, v178 quad_perm:[1,0,3,2] row_mask:0xf bank_mask:0xf
	v_perm_b32 v178, v179, v178, v250
	global_store_dword v225, v178, s[2:3] nt
	v_cvt_pk_bf16_f32 v178, v122, v123
	s_nop 1
	v_mov_b32_dpp v179, v178 quad_perm:[1,0,3,2] row_mask:0xf bank_mask:0xf
	v_perm_b32 v178, v179, v178, v250
	global_store_dword v224, v178, s[2:3] nt
	v_cvt_pk_bf16_f32 v178, v116, v117
	s_nop 1
	v_mov_b32_dpp v179, v178 quad_perm:[1,0,3,2] row_mask:0xf bank_mask:0xf
	v_perm_b32 v178, v179, v178, v250
	global_store_dword v223, v178, s[2:3] nt
	v_cvt_pk_bf16_f32 v178, v118, v119
	s_nop 1
	v_mov_b32_dpp v179, v178 quad_perm:[1,0,3,2] row_mask:0xf bank_mask:0xf
	v_perm_b32 v178, v179, v178, v250
	global_store_dword v222, v178, s[2:3] nt
	v_cvt_pk_bf16_f32 v178, v112, v113
	s_nop 1
	v_mov_b32_dpp v179, v178 quad_perm:[1,0,3,2] row_mask:0xf bank_mask:0xf
	v_perm_b32 v178, v179, v178, v250
	global_store_dword v221, v178, s[2:3] nt
	v_cvt_pk_bf16_f32 v178, v114, v115
	s_nop 1
	v_mov_b32_dpp v179, v178 quad_perm:[1,0,3,2] row_mask:0xf bank_mask:0xf
	v_perm_b32 v178, v179, v178, v250
	global_store_dword v220, v178, s[2:3] nt
	v_cvt_pk_bf16_f32 v178, v108, v109
	s_nop 1
	v_mov_b32_dpp v179, v178 quad_perm:[1,0,3,2] row_mask:0xf bank_mask:0xf
	v_perm_b32 v178, v179, v178, v250
	global_store_dword v219, v178, s[2:3] nt
	v_cvt_pk_bf16_f32 v178, v110, v111
	s_nop 1
	v_mov_b32_dpp v179, v178 quad_perm:[1,0,3,2] row_mask:0xf bank_mask:0xf
	v_perm_b32 v178, v179, v178, v250
	global_store_dword v218, v178, s[2:3] nt
	v_cvt_pk_bf16_f32 v178, v104, v105
	s_nop 1
	v_mov_b32_dpp v179, v178 quad_perm:[1,0,3,2] row_mask:0xf bank_mask:0xf
	v_perm_b32 v178, v179, v178, v250
	global_store_dword v217, v178, s[2:3] nt
	v_cvt_pk_bf16_f32 v178, v106, v107
	s_nop 1
	v_mov_b32_dpp v179, v178 quad_perm:[1,0,3,2] row_mask:0xf bank_mask:0xf
	v_perm_b32 v178, v179, v178, v250
	global_store_dword v216, v178, s[2:3] nt
	v_cvt_pk_bf16_f32 v178, v100, v101
	s_nop 1
	v_mov_b32_dpp v179, v178 quad_perm:[1,0,3,2] row_mask:0xf bank_mask:0xf
	v_perm_b32 v178, v179, v178, v250
	global_store_dword v215, v178, s[2:3] nt
	v_cvt_pk_bf16_f32 v178, v102, v103
	s_nop 1
	v_mov_b32_dpp v179, v178 quad_perm:[1,0,3,2] row_mask:0xf bank_mask:0xf
	v_perm_b32 v178, v179, v178, v250
	global_store_dword v214, v178, s[2:3] nt
	v_cvt_pk_bf16_f32 v178, v96, v97
	s_nop 1
	v_mov_b32_dpp v179, v178 quad_perm:[1,0,3,2] row_mask:0xf bank_mask:0xf
	v_perm_b32 v178, v179, v178, v250
	global_store_dword v213, v178, s[2:3] nt
	v_cvt_pk_bf16_f32 v178, v98, v99
	s_nop 1
	v_mov_b32_dpp v179, v178 quad_perm:[1,0,3,2] row_mask:0xf bank_mask:0xf
	v_perm_b32 v178, v179, v178, v250
	global_store_dword v212, v178, s[2:3] nt
	v_cvt_pk_bf16_f32 v178, v92, v93
	s_nop 1
	v_mov_b32_dpp v179, v178 quad_perm:[1,0,3,2] row_mask:0xf bank_mask:0xf
	v_perm_b32 v178, v179, v178, v250
	global_store_dword v211, v178, s[2:3] nt
	v_cvt_pk_bf16_f32 v178, v94, v95
	s_nop 1
	v_mov_b32_dpp v179, v178 quad_perm:[1,0,3,2] row_mask:0xf bank_mask:0xf
	v_perm_b32 v178, v179, v178, v250
	global_store_dword v210, v178, s[2:3] nt
	v_cvt_pk_bf16_f32 v178, v88, v89
	s_nop 1
	v_mov_b32_dpp v179, v178 quad_perm:[1,0,3,2] row_mask:0xf bank_mask:0xf
	v_perm_b32 v178, v179, v178, v250
	global_store_dword v209, v178, s[2:3] nt
	v_cvt_pk_bf16_f32 v178, v90, v91
	s_nop 1
	v_mov_b32_dpp v179, v178 quad_perm:[1,0,3,2] row_mask:0xf bank_mask:0xf
	v_perm_b32 v178, v179, v178, v250
	global_store_dword v208, v178, s[2:3] nt
	v_cvt_pk_bf16_f32 v178, v84, v85
	s_nop 1
	v_mov_b32_dpp v179, v178 quad_perm:[1,0,3,2] row_mask:0xf bank_mask:0xf
	v_perm_b32 v178, v179, v178, v250
	global_store_dword v207, v178, s[2:3] nt
	v_cvt_pk_bf16_f32 v178, v86, v87
	s_nop 1
	v_mov_b32_dpp v179, v178 quad_perm:[1,0,3,2] row_mask:0xf bank_mask:0xf
	v_perm_b32 v178, v179, v178, v250
	global_store_dword v206, v178, s[2:3] nt
	v_cvt_pk_bf16_f32 v178, v80, v81
	s_nop 1
	v_mov_b32_dpp v179, v178 quad_perm:[1,0,3,2] row_mask:0xf bank_mask:0xf
	v_perm_b32 v178, v179, v178, v250
	global_store_dword v205, v178, s[2:3] nt
	v_cvt_pk_bf16_f32 v178, v82, v83
	s_nop 1
	v_mov_b32_dpp v179, v178 quad_perm:[1,0,3,2] row_mask:0xf bank_mask:0xf
	v_perm_b32 v178, v179, v178, v250
	global_store_dword v204, v178, s[2:3] nt
	v_cvt_pk_bf16_f32 v178, v76, v77
	s_nop 1
	v_mov_b32_dpp v179, v178 quad_perm:[1,0,3,2] row_mask:0xf bank_mask:0xf
	v_perm_b32 v178, v179, v178, v250
	global_store_dword v203, v178, s[2:3] nt
	v_cvt_pk_bf16_f32 v178, v78, v79
	s_nop 1
	v_mov_b32_dpp v179, v178 quad_perm:[1,0,3,2] row_mask:0xf bank_mask:0xf
	v_perm_b32 v178, v179, v178, v250
	global_store_dword v202, v178, s[2:3] nt
	v_cvt_pk_bf16_f32 v178, v72, v73
	s_nop 1
	v_mov_b32_dpp v179, v178 quad_perm:[1,0,3,2] row_mask:0xf bank_mask:0xf
	v_perm_b32 v178, v179, v178, v250
	global_store_dword v201, v178, s[2:3] nt
	v_cvt_pk_bf16_f32 v178, v74, v75
	s_nop 1
	v_mov_b32_dpp v179, v178 quad_perm:[1,0,3,2] row_mask:0xf bank_mask:0xf
	v_perm_b32 v178, v179, v178, v250
	global_store_dword v200, v178, s[2:3] nt
	v_cvt_pk_bf16_f32 v178, v68, v69
	s_nop 1
	v_mov_b32_dpp v179, v178 quad_perm:[1,0,3,2] row_mask:0xf bank_mask:0xf
	v_perm_b32 v178, v179, v178, v250
	global_store_dword v199, v178, s[2:3] nt
	v_cvt_pk_bf16_f32 v178, v70, v71
	s_nop 1
	v_mov_b32_dpp v179, v178 quad_perm:[1,0,3,2] row_mask:0xf bank_mask:0xf
	v_perm_b32 v178, v179, v178, v250
	global_store_dword v198, v178, s[2:3] nt
	v_cvt_pk_bf16_f32 v178, v64, v65
	s_nop 1
	v_mov_b32_dpp v179, v178 quad_perm:[1,0,3,2] row_mask:0xf bank_mask:0xf
	v_perm_b32 v178, v179, v178, v250
	global_store_dword v197, v178, s[2:3] nt
	v_cvt_pk_bf16_f32 v178, v66, v67
	s_nop 1
	v_mov_b32_dpp v179, v178 quad_perm:[1,0,3,2] row_mask:0xf bank_mask:0xf
	v_perm_b32 v178, v179, v178, v250
	global_store_dword v196, v178, s[2:3] nt
	v_cvt_pk_bf16_f32 v178, v60, v61
	s_nop 1
	v_mov_b32_dpp v179, v178 quad_perm:[1,0,3,2] row_mask:0xf bank_mask:0xf
	v_perm_b32 v178, v179, v178, v250
	global_store_dword v195, v178, s[2:3] nt
	v_cvt_pk_bf16_f32 v178, v62, v63
	s_nop 1
	v_mov_b32_dpp v179, v178 quad_perm:[1,0,3,2] row_mask:0xf bank_mask:0xf
	v_perm_b32 v178, v179, v178, v250
	global_store_dword v194, v178, s[2:3] nt
	v_cvt_pk_bf16_f32 v178, v56, v57
	s_nop 1
	v_mov_b32_dpp v179, v178 quad_perm:[1,0,3,2] row_mask:0xf bank_mask:0xf
	v_perm_b32 v178, v179, v178, v250
	global_store_dword v193, v178, s[2:3] nt
	v_cvt_pk_bf16_f32 v178, v58, v59
	s_nop 1
	v_mov_b32_dpp v179, v178 quad_perm:[1,0,3,2] row_mask:0xf bank_mask:0xf
	v_perm_b32 v178, v179, v178, v250
	global_store_dword v192, v178, s[2:3] nt
	v_cvt_pk_bf16_f32 v178, v52, v53
	s_nop 1
	v_mov_b32_dpp v179, v178 quad_perm:[1,0,3,2] row_mask:0xf bank_mask:0xf
	v_perm_b32 v178, v179, v178, v250
	global_store_dword v191, v178, s[2:3] nt
	v_cvt_pk_bf16_f32 v178, v54, v55
	s_nop 1
	v_mov_b32_dpp v179, v178 quad_perm:[1,0,3,2] row_mask:0xf bank_mask:0xf
	v_perm_b32 v178, v179, v178, v250
	global_store_dword v190, v178, s[2:3] nt
	v_cvt_pk_bf16_f32 v178, v48, v49
	s_nop 1
	v_mov_b32_dpp v179, v178 quad_perm:[1,0,3,2] row_mask:0xf bank_mask:0xf
	v_perm_b32 v178, v179, v178, v250
	global_store_dword v189, v178, s[2:3] nt
	v_cvt_pk_bf16_f32 v178, v50, v51
	s_nop 1
	v_mov_b32_dpp v179, v178 quad_perm:[1,0,3,2] row_mask:0xf bank_mask:0xf
	v_perm_b32 v178, v179, v178, v250
	global_store_dword v188, v178, s[2:3] nt
	v_cvt_pk_bf16_f32 v178, v44, v45
	s_nop 1
	v_mov_b32_dpp v179, v178 quad_perm:[1,0,3,2] row_mask:0xf bank_mask:0xf
	v_perm_b32 v178, v179, v178, v250
	global_store_dword v187, v178, s[2:3] nt
	v_cvt_pk_bf16_f32 v178, v46, v47
	s_nop 1
	v_mov_b32_dpp v179, v178 quad_perm:[1,0,3,2] row_mask:0xf bank_mask:0xf
	v_perm_b32 v178, v179, v178, v250
	global_store_dword v186, v178, s[2:3] nt
	v_cvt_pk_bf16_f32 v178, v40, v41
	s_nop 1
	v_mov_b32_dpp v179, v178 quad_perm:[1,0,3,2] row_mask:0xf bank_mask:0xf
	v_perm_b32 v178, v179, v178, v250
	global_store_dword v185, v178, s[2:3] nt
	v_cvt_pk_bf16_f32 v178, v42, v43
	s_nop 1
	v_mov_b32_dpp v179, v178 quad_perm:[1,0,3,2] row_mask:0xf bank_mask:0xf
	v_perm_b32 v178, v179, v178, v250
	global_store_dword v184, v178, s[2:3] nt
	v_cvt_pk_bf16_f32 v178, v36, v37
	s_nop 1
	v_mov_b32_dpp v179, v178 quad_perm:[1,0,3,2] row_mask:0xf bank_mask:0xf
	v_perm_b32 v178, v179, v178, v250
	global_store_dword v183, v178, s[2:3] nt
	v_cvt_pk_bf16_f32 v178, v38, v39
	s_nop 1
	v_mov_b32_dpp v179, v178 quad_perm:[1,0,3,2] row_mask:0xf bank_mask:0xf
	v_perm_b32 v178, v179, v178, v250
	global_store_dword v182, v178, s[2:3] nt
	v_cvt_pk_bf16_f32 v178, v32, v33
	s_nop 1
	v_mov_b32_dpp v179, v178 quad_perm:[1,0,3,2] row_mask:0xf bank_mask:0xf
	v_perm_b32 v178, v179, v178, v250
	global_store_dword v181, v178, s[2:3] nt
	v_cvt_pk_bf16_f32 v178, v34, v35
	s_nop 1
	v_mov_b32_dpp v179, v178 quad_perm:[1,0,3,2] row_mask:0xf bank_mask:0xf
	v_perm_b32 v178, v179, v178, v250
	global_store_dword v180, v178, s[2:3] nt
	v_cvt_pk_bf16_f32 v178, v28, v29
	s_nop 1
	v_mov_b32_dpp v179, v178 quad_perm:[1,0,3,2] row_mask:0xf bank_mask:0xf
	v_perm_b32 v178, v179, v178, v250
	global_store_dword v173, v178, s[2:3] nt
	v_cvt_pk_bf16_f32 v178, v30, v31
	s_nop 1
	v_mov_b32_dpp v179, v178 quad_perm:[1,0,3,2] row_mask:0xf bank_mask:0xf
	v_perm_b32 v178, v179, v178, v250
	global_store_dword v172, v178, s[2:3] nt
	v_cvt_pk_bf16_f32 v178, v24, v25
	s_nop 1
	v_mov_b32_dpp v179, v178 quad_perm:[1,0,3,2] row_mask:0xf bank_mask:0xf
	v_perm_b32 v178, v179, v178, v250
	global_store_dword v171, v178, s[2:3] nt
	v_cvt_pk_bf16_f32 v178, v26, v27
	s_nop 1
	v_mov_b32_dpp v179, v178 quad_perm:[1,0,3,2] row_mask:0xf bank_mask:0xf
	v_perm_b32 v178, v179, v178, v250
	global_store_dword v170, v178, s[2:3] nt
	v_cvt_pk_bf16_f32 v178, v20, v21
	s_nop 1
	v_mov_b32_dpp v179, v178 quad_perm:[1,0,3,2] row_mask:0xf bank_mask:0xf
	v_perm_b32 v178, v179, v178, v250
	global_store_dword v169, v178, s[2:3] nt
	v_cvt_pk_bf16_f32 v178, v22, v23
	s_nop 1
	v_mov_b32_dpp v179, v178 quad_perm:[1,0,3,2] row_mask:0xf bank_mask:0xf
	v_perm_b32 v178, v179, v178, v250
	global_store_dword v168, v178, s[2:3] nt
	v_cvt_pk_bf16_f32 v178, v16, v17
	s_nop 1
	v_mov_b32_dpp v179, v178 quad_perm:[1,0,3,2] row_mask:0xf bank_mask:0xf
	v_perm_b32 v178, v179, v178, v250
	global_store_dword v167, v178, s[2:3] nt
	v_cvt_pk_bf16_f32 v178, v18, v19
	s_nop 1
	v_mov_b32_dpp v179, v178 quad_perm:[1,0,3,2] row_mask:0xf bank_mask:0xf
	v_perm_b32 v178, v179, v178, v250
	global_store_dword v166, v178, s[2:3] nt
	v_cvt_pk_bf16_f32 v178, v12, v13
	s_nop 1
	v_mov_b32_dpp v179, v178 quad_perm:[1,0,3,2] row_mask:0xf bank_mask:0xf
	v_perm_b32 v178, v179, v178, v250
	global_store_dword v165, v178, s[2:3] nt
	v_cvt_pk_bf16_f32 v178, v14, v15
	s_nop 1
	v_mov_b32_dpp v179, v178 quad_perm:[1,0,3,2] row_mask:0xf bank_mask:0xf
	v_perm_b32 v178, v179, v178, v250
	global_store_dword v164, v178, s[2:3] nt
	v_cvt_pk_bf16_f32 v178, v8, v9
	s_nop 1
	v_mov_b32_dpp v179, v178 quad_perm:[1,0,3,2] row_mask:0xf bank_mask:0xf
	v_perm_b32 v178, v179, v178, v250
	global_store_dword v163, v178, s[2:3] nt
	v_cvt_pk_bf16_f32 v178, v10, v11
	s_nop 1
	v_mov_b32_dpp v179, v178 quad_perm:[1,0,3,2] row_mask:0xf bank_mask:0xf
	v_perm_b32 v178, v179, v178, v250
	global_store_dword v162, v178, s[2:3] nt
	v_cvt_pk_bf16_f32 v178, v4, v5
	s_nop 1
	v_mov_b32_dpp v179, v178 quad_perm:[1,0,3,2] row_mask:0xf bank_mask:0xf
	v_perm_b32 v178, v179, v178, v250
	global_store_dword v161, v178, s[2:3] nt
	v_cvt_pk_bf16_f32 v178, v6, v7
	s_nop 1
	v_mov_b32_dpp v179, v178 quad_perm:[1,0,3,2] row_mask:0xf bank_mask:0xf
	v_perm_b32 v178, v179, v178, v250
	global_store_dword v160, v178, s[2:3] nt
	v_cvt_pk_bf16_f32 v178, v0, v1
	s_nop 1
	v_mov_b32_dpp v179, v178 quad_perm:[1,0,3,2] row_mask:0xf bank_mask:0xf
	v_perm_b32 v178, v179, v178, v250
	global_store_dword v159, v178, s[2:3] nt
	v_cvt_pk_bf16_f32 v178, v2, v3
	s_nop 1
	v_mov_b32_dpp v179, v178 quad_perm:[1,0,3,2] row_mask:0xf bank_mask:0xf
	v_perm_b32 v178, v179, v178, v250
	global_store_dword v158, v178, s[2:3] nt
	s_cbranch_execnz .LBB0_1556
	s_branch .LBB0_1572

.LBB0_1572:
	v_mul_f32_e32 v124, 0xbfb8aa3b, v124
	v_mul_f32_e32 v125, 0xbfb8aa3b, v125
	v_exp_f32_e32 v124, v124
	v_exp_f32_e32 v125, v125
	v_mul_f32_e32 v126, 0xbfb8aa3b, v126
	v_mul_f32_e32 v127, 0xbfb8aa3b, v127
	v_add_f32_e32 v124, 1.0, v124
	v_add_f32_e32 v125, 1.0, v125
	v_exp_f32_e32 v126, v126
	v_exp_f32_e32 v127, v127
	v_rcp_f32_e32 v124, v124
	v_rcp_f32_e32 v125, v125
	v_mul_f32_e32 v120, 0xbfb8aa3b, v120
	v_mul_f32_e32 v121, 0xbfb8aa3b, v121
	v_add_f32_e32 v126, 1.0, v126
	v_add_f32_e32 v127, 1.0, v127
	v_exp_f32_e32 v120, v120
	v_exp_f32_e32 v121, v121
	v_mov_b32_e32 v178, v129
	v_cndmask_b32_e64 v179, v124, v125, s[10:11]
	v_rcp_f32_e32 v126, v126
	v_rcp_f32_e32 v127, v127
	v_mov_b32_dpp v178, v179 quad_perm:[1,0,3,2] row_mask:0xf bank_mask:0xf
	v_cndmask_b32_e64 v124, v178, v124, s[10:11]
	v_mul_f32_e32 v122, 0xbfb8aa3b, v122
	v_mul_f32_e32 v123, 0xbfb8aa3b, v123
	v_cndmask_b32_e64 v125, v125, v178, s[10:11]
	v_cvt_pk_bf16_f32 v124, v124, v125
	v_add_f32_e32 v120, 1.0, v120
	v_add_f32_e32 v121, 1.0, v121
	v_exp_f32_e32 v122, v122
	v_exp_f32_e32 v123, v123
	global_store_dword v227, v124, s[12:13] nt
	v_cndmask_b32_e64 v124, v126, v127, s[10:11]
	v_mov_b32_e32 v125, v129
	v_rcp_f32_e32 v120, v120
	v_rcp_f32_e32 v121, v121
	v_mov_b32_dpp v125, v124 quad_perm:[1,0,3,2] row_mask:0xf bank_mask:0xf
	v_cndmask_b32_e64 v124, v125, v126, s[10:11]
	v_mul_f32_e32 v116, 0xbfb8aa3b, v116
	v_mul_f32_e32 v117, 0xbfb8aa3b, v117
	v_cndmask_b32_e64 v125, v127, v125, s[10:11]
	v_cvt_pk_bf16_f32 v124, v124, v125
	v_add_f32_e32 v122, 1.0, v122
	v_add_f32_e32 v123, 1.0, v123
	v_exp_f32_e32 v116, v116
	v_exp_f32_e32 v117, v117
	global_store_dword v226, v124, s[12:13] nt
	v_cndmask_b32_e64 v124, v120, v121, s[10:11]
	v_mov_b32_e32 v125, v129
	v_rcp_f32_e32 v122, v122
	v_rcp_f32_e32 v123, v123
	v_mov_b32_dpp v125, v124 quad_perm:[1,0,3,2] row_mask:0xf bank_mask:0xf
	v_cndmask_b32_e64 v120, v125, v120, s[10:11]
	v_mul_f32_e32 v118, 0xbfb8aa3b, v118
	v_mul_f32_e32 v119, 0xbfb8aa3b, v119
	v_cndmask_b32_e64 v121, v121, v125, s[10:11]
	v_cvt_pk_bf16_f32 v120, v120, v121
	v_add_f32_e32 v116, 1.0, v116
	v_add_f32_e32 v117, 1.0, v117
	v_exp_f32_e32 v118, v118
	v_exp_f32_e32 v119, v119
	global_store_dword v225, v120, s[12:13] nt
	v_cndmask_b32_e64 v120, v122, v123, s[10:11]
	v_mov_b32_e32 v121, v129
	v_rcp_f32_e32 v116, v116
	v_rcp_f32_e32 v117, v117
	v_mov_b32_dpp v121, v120 quad_perm:[1,0,3,2] row_mask:0xf bank_mask:0xf
	v_cndmask_b32_e64 v120, v121, v122, s[10:11]
	v_mul_f32_e32 v112, 0xbfb8aa3b, v112
	v_mul_f32_e32 v113, 0xbfb8aa3b, v113
	v_cndmask_b32_e64 v121, v123, v121, s[10:11]
	v_cvt_pk_bf16_f32 v120, v120, v121
	v_add_f32_e32 v118, 1.0, v118
	v_add_f32_e32 v119, 1.0, v119
	v_exp_f32_e32 v112, v112
	v_exp_f32_e32 v113, v113
	global_store_dword v224, v120, s[12:13] nt
	v_cndmask_b32_e64 v120, v116, v117, s[10:11]
	v_mov_b32_e32 v121, v129
	v_rcp_f32_e32 v118, v118
	v_rcp_f32_e32 v119, v119
	v_mov_b32_dpp v121, v120 quad_perm:[1,0,3,2] row_mask:0xf bank_mask:0xf
	v_cndmask_b32_e64 v116, v121, v116, s[10:11]
	v_mul_f32_e32 v114, 0xbfb8aa3b, v114
	v_mul_f32_e32 v115, 0xbfb8aa3b, v115
	v_cndmask_b32_e64 v117, v117, v121, s[10:11]
	v_cvt_pk_bf16_f32 v116, v116, v117
	v_add_f32_e32 v112, 1.0, v112
	v_add_f32_e32 v113, 1.0, v113
	v_exp_f32_e32 v114, v114
	v_exp_f32_e32 v115, v115
	global_store_dword v223, v116, s[12:13] nt
	v_cndmask_b32_e64 v116, v118, v119, s[10:11]
	v_mov_b32_e32 v117, v129
	v_rcp_f32_e32 v112, v112
	v_rcp_f32_e32 v113, v113
	v_mov_b32_dpp v117, v116 quad_perm:[1,0,3,2] row_mask:0xf bank_mask:0xf
	v_cndmask_b32_e64 v116, v117, v118, s[10:11]
	v_cndmask_b32_e64 v117, v119, v117, s[10:11]
	v_cvt_pk_bf16_f32 v116, v116, v117
	v_add_f32_e32 v114, 1.0, v114
	v_add_f32_e32 v115, 1.0, v115
	global_store_dword v222, v116, s[12:13] nt
	v_cndmask_b32_e64 v116, v112, v113, s[10:11]
	v_mov_b32_e32 v117, v129
	v_rcp_f32_e32 v114, v114
	v_rcp_f32_e32 v115, v115
	v_mov_b32_dpp v117, v116 quad_perm:[1,0,3,2] row_mask:0xf bank_mask:0xf
	v_cndmask_b32_e64 v112, v117, v112, s[10:11]
	v_cndmask_b32_e64 v113, v113, v117, s[10:11]
	v_cvt_pk_bf16_f32 v112, v112, v113
	global_store_dword v221, v112, s[12:13] nt
	v_cvt_pk_bf16_f32 v112, v114, v115
	s_nop 1
	v_mov_b32_dpp v113, v112 quad_perm:[1,0,3,2] row_mask:0xf bank_mask:0xf
	v_perm_b32 v112, v113, v112, v250
	global_store_dword v220, v112, s[12:13] nt
	v_mul_f32_e32 v108, 0xbfb8aa3b, v108
	v_mul_f32_e32 v109, 0xbfb8aa3b, v109
	v_exp_f32_e32 v108, v108
	v_exp_f32_e32 v109, v109
	v_mul_f32_e32 v110, 0xbfb8aa3b, v110
	v_mul_f32_e32 v111, 0xbfb8aa3b, v111
	v_add_f32_e32 v108, 1.0, v108
	v_add_f32_e32 v109, 1.0, v109
	v_exp_f32_e32 v110, v110
	v_exp_f32_e32 v111, v111
	v_rcp_f32_e32 v108, v108
	v_rcp_f32_e32 v109, v109
	v_mul_f32_e32 v104, 0xbfb8aa3b, v104
	v_mul_f32_e32 v105, 0xbfb8aa3b, v105
	v_add_f32_e32 v110, 1.0, v110
	v_add_f32_e32 v111, 1.0, v111
	v_exp_f32_e32 v104, v104
	v_exp_f32_e32 v105, v105
	v_mov_b32_e32 v112, v129
	v_cndmask_b32_e64 v113, v108, v109, s[10:11]
	v_rcp_f32_e32 v110, v110
	v_rcp_f32_e32 v111, v111
	v_mov_b32_dpp v112, v113 quad_perm:[1,0,3,2] row_mask:0xf bank_mask:0xf
	v_cndmask_b32_e64 v108, v112, v108, s[10:11]
	v_mul_f32_e32 v106, 0xbfb8aa3b, v106
	v_mul_f32_e32 v107, 0xbfb8aa3b, v107
	v_cndmask_b32_e64 v109, v109, v112, s[10:11]
	v_cvt_pk_bf16_f32 v108, v108, v109
	v_add_f32_e32 v104, 1.0, v104
	v_add_f32_e32 v105, 1.0, v105
	v_exp_f32_e32 v106, v106
	v_exp_f32_e32 v107, v107
	global_store_dword v219, v108, s[12:13] nt
	v_cndmask_b32_e64 v108, v110, v111, s[10:11]
	v_mov_b32_e32 v109, v129
	v_rcp_f32_e32 v104, v104
	v_rcp_f32_e32 v105, v105
	v_mov_b32_dpp v109, v108 quad_perm:[1,0,3,2] row_mask:0xf bank_mask:0xf
	v_cndmask_b32_e64 v108, v109, v110, s[10:11]
	v_mul_f32_e32 v100, 0xbfb8aa3b, v100
	v_mul_f32_e32 v101, 0xbfb8aa3b, v101
	v_cndmask_b32_e64 v109, v111, v109, s[10:11]
	v_cvt_pk_bf16_f32 v108, v108, v109
	v_add_f32_e32 v106, 1.0, v106
	v_add_f32_e32 v107, 1.0, v107
	v_exp_f32_e32 v100, v100
	v_exp_f32_e32 v101, v101
	global_store_dword v218, v108, s[12:13] nt
	v_cndmask_b32_e64 v108, v104, v105, s[10:11]
	v_mov_b32_e32 v109, v129
	v_rcp_f32_e32 v106, v106
	v_rcp_f32_e32 v107, v107
	v_mov_b32_dpp v109, v108 quad_perm:[1,0,3,2] row_mask:0xf bank_mask:0xf
	v_cndmask_b32_e64 v104, v109, v104, s[10:11]
	v_mul_f32_e32 v102, 0xbfb8aa3b, v102
	v_mul_f32_e32 v103, 0xbfb8aa3b, v103
	v_cndmask_b32_e64 v105, v105, v109, s[10:11]
	v_cvt_pk_bf16_f32 v104, v104, v105
	v_add_f32_e32 v100, 1.0, v100
	v_add_f32_e32 v101, 1.0, v101
	v_exp_f32_e32 v102, v102
	v_exp_f32_e32 v103, v103
	global_store_dword v217, v104, s[12:13] nt
	v_cndmask_b32_e64 v104, v106, v107, s[10:11]
	v_mov_b32_e32 v105, v129
	v_rcp_f32_e32 v100, v100
	v_rcp_f32_e32 v101, v101
	v_mov_b32_dpp v105, v104 quad_perm:[1,0,3,2] row_mask:0xf bank_mask:0xf
	v_cndmask_b32_e64 v104, v105, v106, s[10:11]
	v_mul_f32_e32 v96, 0xbfb8aa3b, v96
	v_mul_f32_e32 v97, 0xbfb8aa3b, v97
	v_cndmask_b32_e64 v105, v107, v105, s[10:11]
	v_cvt_pk_bf16_f32 v104, v104, v105
	v_add_f32_e32 v102, 1.0, v102
	v_add_f32_e32 v103, 1.0, v103
	v_exp_f32_e32 v96, v96
	v_exp_f32_e32 v97, v97
	global_store_dword v216, v104, s[12:13] nt
	v_cndmask_b32_e64 v104, v100, v101, s[10:11]
	v_mov_b32_e32 v105, v129
	v_rcp_f32_e32 v102, v102
	v_rcp_f32_e32 v103, v103
	v_mov_b32_dpp v105, v104 quad_perm:[1,0,3,2] row_mask:0xf bank_mask:0xf
	v_cndmask_b32_e64 v100, v105, v100, s[10:11]
	v_mul_f32_e32 v98, 0xbfb8aa3b, v98
	v_mul_f32_e32 v99, 0xbfb8aa3b, v99
	v_cndmask_b32_e64 v101, v101, v105, s[10:11]
	v_cvt_pk_bf16_f32 v100, v100, v101
	v_add_f32_e32 v96, 1.0, v96
	v_add_f32_e32 v97, 1.0, v97
	v_exp_f32_e32 v98, v98
	v_exp_f32_e32 v99, v99
	global_store_dword v215, v100, s[12:13] nt
	v_cndmask_b32_e64 v100, v102, v103, s[10:11]
	v_mov_b32_e32 v101, v129
	v_rcp_f32_e32 v96, v96
	v_rcp_f32_e32 v97, v97
	v_mov_b32_dpp v101, v100 quad_perm:[1,0,3,2] row_mask:0xf bank_mask:0xf
	v_cndmask_b32_e64 v100, v101, v102, s[10:11]
	v_cndmask_b32_e64 v101, v103, v101, s[10:11]
	v_cvt_pk_bf16_f32 v100, v100, v101
	v_add_f32_e32 v98, 1.0, v98
	v_add_f32_e32 v99, 1.0, v99
	global_store_dword v214, v100, s[12:13] nt
	v_cndmask_b32_e64 v100, v96, v97, s[10:11]
	v_mov_b32_e32 v101, v129
	v_rcp_f32_e32 v98, v98
	v_rcp_f32_e32 v99, v99
	v_mov_b32_dpp v101, v100 quad_perm:[1,0,3,2] row_mask:0xf bank_mask:0xf
	v_cndmask_b32_e64 v96, v101, v96, s[10:11]
	v_cndmask_b32_e64 v97, v97, v101, s[10:11]
	v_cvt_pk_bf16_f32 v96, v96, v97
	global_store_dword v213, v96, s[12:13] nt
	v_cvt_pk_bf16_f32 v96, v98, v99
	s_nop 1
	v_mov_b32_dpp v97, v96 quad_perm:[1,0,3,2] row_mask:0xf bank_mask:0xf
	v_perm_b32 v96, v97, v96, v250
	global_store_dword v212, v96, s[12:13] nt
	v_mul_f32_e32 v92, 0xbfb8aa3b, v92
	v_mul_f32_e32 v93, 0xbfb8aa3b, v93
	v_exp_f32_e32 v92, v92
	v_exp_f32_e32 v93, v93
	v_mul_f32_e32 v94, 0xbfb8aa3b, v94
	v_mul_f32_e32 v95, 0xbfb8aa3b, v95
	v_add_f32_e32 v92, 1.0, v92
	v_add_f32_e32 v93, 1.0, v93
	v_exp_f32_e32 v94, v94
	v_exp_f32_e32 v95, v95
	v_rcp_f32_e32 v92, v92
	v_rcp_f32_e32 v93, v93
	v_mul_f32_e32 v88, 0xbfb8aa3b, v88
	v_mul_f32_e32 v89, 0xbfb8aa3b, v89
	v_add_f32_e32 v94, 1.0, v94
	v_add_f32_e32 v95, 1.0, v95
	v_exp_f32_e32 v88, v88
	v_exp_f32_e32 v89, v89
	v_mov_b32_e32 v96, v129
	v_cndmask_b32_e64 v97, v92, v93, s[10:11]
	v_rcp_f32_e32 v94, v94
	v_rcp_f32_e32 v95, v95
	v_mov_b32_dpp v96, v97 quad_perm:[1,0,3,2] row_mask:0xf bank_mask:0xf
	v_cndmask_b32_e64 v92, v96, v92, s[10:11]
	v_mul_f32_e32 v90, 0xbfb8aa3b, v90
	v_mul_f32_e32 v91, 0xbfb8aa3b, v91
	v_cndmask_b32_e64 v93, v93, v96, s[10:11]
	v_cvt_pk_bf16_f32 v92, v92, v93
	v_add_f32_e32 v88, 1.0, v88
	v_add_f32_e32 v89, 1.0, v89
	v_exp_f32_e32 v90, v90
	v_exp_f32_e32 v91, v91
	global_store_dword v211, v92, s[12:13] nt
	v_cndmask_b32_e64 v92, v94, v95, s[10:11]
	v_mov_b32_e32 v93, v129
	v_rcp_f32_e32 v88, v88
	v_rcp_f32_e32 v89, v89
	v_mov_b32_dpp v93, v92 quad_perm:[1,0,3,2] row_mask:0xf bank_mask:0xf
	v_cndmask_b32_e64 v92, v93, v94, s[10:11]
	v_mul_f32_e32 v84, 0xbfb8aa3b, v84
	v_mul_f32_e32 v85, 0xbfb8aa3b, v85
	v_cndmask_b32_e64 v93, v95, v93, s[10:11]
	v_cvt_pk_bf16_f32 v92, v92, v93
	v_add_f32_e32 v90, 1.0, v90
	v_add_f32_e32 v91, 1.0, v91
	v_exp_f32_e32 v84, v84
	v_exp_f32_e32 v85, v85
	global_store_dword v210, v92, s[12:13] nt
	v_cndmask_b32_e64 v92, v88, v89, s[10:11]
	v_mov_b32_e32 v93, v129
	v_rcp_f32_e32 v90, v90
	v_rcp_f32_e32 v91, v91
	v_mov_b32_dpp v93, v92 quad_perm:[1,0,3,2] row_mask:0xf bank_mask:0xf
	v_cndmask_b32_e64 v88, v93, v88, s[10:11]
	v_mul_f32_e32 v86, 0xbfb8aa3b, v86
	v_mul_f32_e32 v87, 0xbfb8aa3b, v87
	v_cndmask_b32_e64 v89, v89, v93, s[10:11]
	v_cvt_pk_bf16_f32 v88, v88, v89
	v_add_f32_e32 v84, 1.0, v84
	v_add_f32_e32 v85, 1.0, v85
	v_exp_f32_e32 v86, v86
	v_exp_f32_e32 v87, v87
	global_store_dword v209, v88, s[12:13] nt
	v_cndmask_b32_e64 v88, v90, v91, s[10:11]
	v_mov_b32_e32 v89, v129
	v_rcp_f32_e32 v84, v84
	v_rcp_f32_e32 v85, v85
	v_mov_b32_dpp v89, v88 quad_perm:[1,0,3,2] row_mask:0xf bank_mask:0xf
	v_cndmask_b32_e64 v88, v89, v90, s[10:11]
	v_mul_f32_e32 v80, 0xbfb8aa3b, v80
	v_mul_f32_e32 v81, 0xbfb8aa3b, v81
	v_cndmask_b32_e64 v89, v91, v89, s[10:11]
	v_cvt_pk_bf16_f32 v88, v88, v89
	v_add_f32_e32 v86, 1.0, v86
	v_add_f32_e32 v87, 1.0, v87
	v_exp_f32_e32 v80, v80
	v_exp_f32_e32 v81, v81
	global_store_dword v208, v88, s[12:13] nt
	v_cndmask_b32_e64 v88, v84, v85, s[10:11]
	v_mov_b32_e32 v89, v129
	v_rcp_f32_e32 v86, v86
	v_rcp_f32_e32 v87, v87
	v_mov_b32_dpp v89, v88 quad_perm:[1,0,3,2] row_mask:0xf bank_mask:0xf
	v_cndmask_b32_e64 v84, v89, v84, s[10:11]
	v_mul_f32_e32 v82, 0xbfb8aa3b, v82
	v_mul_f32_e32 v83, 0xbfb8aa3b, v83
	v_cndmask_b32_e64 v85, v85, v89, s[10:11]
	v_cvt_pk_bf16_f32 v84, v84, v85
	v_add_f32_e32 v80, 1.0, v80
	v_add_f32_e32 v81, 1.0, v81
	v_exp_f32_e32 v82, v82
	v_exp_f32_e32 v83, v83
	global_store_dword v207, v84, s[12:13] nt
	v_cndmask_b32_e64 v84, v86, v87, s[10:11]
	v_mov_b32_e32 v85, v129
	v_rcp_f32_e32 v80, v80
	v_rcp_f32_e32 v81, v81
	v_mov_b32_dpp v85, v84 quad_perm:[1,0,3,2] row_mask:0xf bank_mask:0xf
	v_cndmask_b32_e64 v84, v85, v86, s[10:11]
	v_cndmask_b32_e64 v85, v87, v85, s[10:11]
	v_cvt_pk_bf16_f32 v84, v84, v85
	v_add_f32_e32 v82, 1.0, v82
	v_add_f32_e32 v83, 1.0, v83
	global_store_dword v206, v84, s[12:13] nt
	v_cndmask_b32_e64 v84, v80, v81, s[10:11]
	v_mov_b32_e32 v85, v129
	v_rcp_f32_e32 v82, v82
	v_rcp_f32_e32 v83, v83
	v_mov_b32_dpp v85, v84 quad_perm:[1,0,3,2] row_mask:0xf bank_mask:0xf
	v_cndmask_b32_e64 v80, v85, v80, s[10:11]
	v_cndmask_b32_e64 v81, v81, v85, s[10:11]
	v_cvt_pk_bf16_f32 v80, v80, v81
	global_store_dword v205, v80, s[12:13] nt
	v_cvt_pk_bf16_f32 v80, v82, v83
	s_nop 1
	v_mov_b32_dpp v81, v80 quad_perm:[1,0,3,2] row_mask:0xf bank_mask:0xf
	v_perm_b32 v80, v81, v80, v250
	global_store_dword v204, v80, s[12:13] nt
	v_mul_f32_e32 v76, 0xbfb8aa3b, v76
	v_mul_f32_e32 v77, 0xbfb8aa3b, v77
	v_exp_f32_e32 v76, v76
	v_exp_f32_e32 v77, v77
	v_mul_f32_e32 v78, 0xbfb8aa3b, v78
	v_mul_f32_e32 v79, 0xbfb8aa3b, v79
	v_add_f32_e32 v76, 1.0, v76
	v_add_f32_e32 v77, 1.0, v77
	v_exp_f32_e32 v78, v78
	v_exp_f32_e32 v79, v79
	v_rcp_f32_e32 v76, v76
	v_rcp_f32_e32 v77, v77
	v_mul_f32_e32 v72, 0xbfb8aa3b, v72
	v_mul_f32_e32 v73, 0xbfb8aa3b, v73
	v_add_f32_e32 v78, 1.0, v78
	v_add_f32_e32 v79, 1.0, v79
	v_exp_f32_e32 v72, v72
	v_exp_f32_e32 v73, v73
	v_mov_b32_e32 v80, v129
	v_cndmask_b32_e64 v81, v76, v77, s[10:11]
	v_rcp_f32_e32 v78, v78
	v_rcp_f32_e32 v79, v79
	v_mov_b32_dpp v80, v81 quad_perm:[1,0,3,2] row_mask:0xf bank_mask:0xf
	v_cndmask_b32_e64 v76, v80, v76, s[10:11]
	v_mul_f32_e32 v74, 0xbfb8aa3b, v74
	v_mul_f32_e32 v75, 0xbfb8aa3b, v75
	v_cndmask_b32_e64 v77, v77, v80, s[10:11]
	v_cvt_pk_bf16_f32 v76, v76, v77
	v_add_f32_e32 v72, 1.0, v72
	v_add_f32_e32 v73, 1.0, v73
	v_exp_f32_e32 v74, v74
	v_exp_f32_e32 v75, v75
	global_store_dword v203, v76, s[12:13] nt
	v_cndmask_b32_e64 v76, v78, v79, s[10:11]
	v_mov_b32_e32 v77, v129
	v_rcp_f32_e32 v72, v72
	v_rcp_f32_e32 v73, v73
	v_mov_b32_dpp v77, v76 quad_perm:[1,0,3,2] row_mask:0xf bank_mask:0xf
	v_cndmask_b32_e64 v76, v77, v78, s[10:11]
	v_mul_f32_e32 v68, 0xbfb8aa3b, v68
	v_mul_f32_e32 v69, 0xbfb8aa3b, v69
	v_cndmask_b32_e64 v77, v79, v77, s[10:11]
	v_cvt_pk_bf16_f32 v76, v76, v77
	v_add_f32_e32 v74, 1.0, v74
	v_add_f32_e32 v75, 1.0, v75
	v_exp_f32_e32 v68, v68
	v_exp_f32_e32 v69, v69
	global_store_dword v202, v76, s[12:13] nt
	v_cndmask_b32_e64 v76, v72, v73, s[10:11]
	v_mov_b32_e32 v77, v129
	v_rcp_f32_e32 v74, v74
	v_rcp_f32_e32 v75, v75
	v_mov_b32_dpp v77, v76 quad_perm:[1,0,3,2] row_mask:0xf bank_mask:0xf
	v_cndmask_b32_e64 v72, v77, v72, s[10:11]
	v_mul_f32_e32 v70, 0xbfb8aa3b, v70
	v_mul_f32_e32 v71, 0xbfb8aa3b, v71
	v_cndmask_b32_e64 v73, v73, v77, s[10:11]
	v_cvt_pk_bf16_f32 v72, v72, v73
	v_add_f32_e32 v68, 1.0, v68
	v_add_f32_e32 v69, 1.0, v69
	v_exp_f32_e32 v70, v70
	v_exp_f32_e32 v71, v71
	global_store_dword v201, v72, s[12:13] nt
	v_cndmask_b32_e64 v72, v74, v75, s[10:11]
	v_mov_b32_e32 v73, v129
	v_rcp_f32_e32 v68, v68
	v_rcp_f32_e32 v69, v69
	v_mov_b32_dpp v73, v72 quad_perm:[1,0,3,2] row_mask:0xf bank_mask:0xf
	v_cndmask_b32_e64 v72, v73, v74, s[10:11]
	v_mul_f32_e32 v64, 0xbfb8aa3b, v64
	v_mul_f32_e32 v65, 0xbfb8aa3b, v65
	v_cndmask_b32_e64 v73, v75, v73, s[10:11]
	v_cvt_pk_bf16_f32 v72, v72, v73
	v_add_f32_e32 v70, 1.0, v70
	v_add_f32_e32 v71, 1.0, v71
	v_exp_f32_e32 v64, v64
	v_exp_f32_e32 v65, v65
	global_store_dword v200, v72, s[12:13] nt
	v_cndmask_b32_e64 v72, v68, v69, s[10:11]
	v_mov_b32_e32 v73, v129
	v_rcp_f32_e32 v70, v70
	v_rcp_f32_e32 v71, v71
	v_mov_b32_dpp v73, v72 quad_perm:[1,0,3,2] row_mask:0xf bank_mask:0xf
	v_cndmask_b32_e64 v68, v73, v68, s[10:11]
	v_mul_f32_e32 v66, 0xbfb8aa3b, v66
	v_mul_f32_e32 v67, 0xbfb8aa3b, v67
	v_cndmask_b32_e64 v69, v69, v73, s[10:11]
	v_cvt_pk_bf16_f32 v68, v68, v69
	v_add_f32_e32 v64, 1.0, v64
	v_add_f32_e32 v65, 1.0, v65
	v_exp_f32_e32 v66, v66
	v_exp_f32_e32 v67, v67
	global_store_dword v199, v68, s[12:13] nt
	v_cndmask_b32_e64 v68, v70, v71, s[10:11]
	v_mov_b32_e32 v69, v129
	v_rcp_f32_e32 v64, v64
	v_rcp_f32_e32 v65, v65
	v_mov_b32_dpp v69, v68 quad_perm:[1,0,3,2] row_mask:0xf bank_mask:0xf
	v_cndmask_b32_e64 v68, v69, v70, s[10:11]
	v_cndmask_b32_e64 v69, v71, v69, s[10:11]
	v_cvt_pk_bf16_f32 v68, v68, v69
	v_add_f32_e32 v66, 1.0, v66
	v_add_f32_e32 v67, 1.0, v67
	global_store_dword v198, v68, s[12:13] nt
	v_cndmask_b32_e64 v68, v64, v65, s[10:11]
	v_mov_b32_e32 v69, v129
	v_rcp_f32_e32 v66, v66
	v_rcp_f32_e32 v67, v67
	v_mov_b32_dpp v69, v68 quad_perm:[1,0,3,2] row_mask:0xf bank_mask:0xf
	v_cndmask_b32_e64 v64, v69, v64, s[10:11]
	v_cndmask_b32_e64 v65, v65, v69, s[10:11]
	v_cvt_pk_bf16_f32 v64, v64, v65
	global_store_dword v197, v64, s[12:13] nt
	v_cvt_pk_bf16_f32 v64, v66, v67
	s_nop 1
	v_mov_b32_dpp v65, v64 quad_perm:[1,0,3,2] row_mask:0xf bank_mask:0xf
	v_perm_b32 v64, v65, v64, v250
	global_store_dword v196, v64, s[12:13] nt
	v_mul_f32_e32 v60, 0xbfb8aa3b, v60
	v_mul_f32_e32 v61, 0xbfb8aa3b, v61
	v_exp_f32_e32 v60, v60
	v_exp_f32_e32 v61, v61
	v_mul_f32_e32 v62, 0xbfb8aa3b, v62
	v_mul_f32_e32 v63, 0xbfb8aa3b, v63
	v_add_f32_e32 v60, 1.0, v60
	v_add_f32_e32 v61, 1.0, v61
	v_exp_f32_e32 v62, v62
	v_exp_f32_e32 v63, v63
	v_rcp_f32_e32 v60, v60
	v_rcp_f32_e32 v61, v61
	v_mul_f32_e32 v56, 0xbfb8aa3b, v56
	v_mul_f32_e32 v57, 0xbfb8aa3b, v57
	v_add_f32_e32 v62, 1.0, v62
	v_add_f32_e32 v63, 1.0, v63
	v_exp_f32_e32 v56, v56
	v_exp_f32_e32 v57, v57
	v_mov_b32_e32 v64, v129
	v_cndmask_b32_e64 v65, v60, v61, s[10:11]
	v_rcp_f32_e32 v62, v62
	v_rcp_f32_e32 v63, v63
	v_mov_b32_dpp v64, v65 quad_perm:[1,0,3,2] row_mask:0xf bank_mask:0xf
	v_cndmask_b32_e64 v60, v64, v60, s[10:11]
	v_mul_f32_e32 v58, 0xbfb8aa3b, v58
	v_mul_f32_e32 v59, 0xbfb8aa3b, v59
	v_cndmask_b32_e64 v61, v61, v64, s[10:11]
	v_cvt_pk_bf16_f32 v60, v60, v61
	v_add_f32_e32 v56, 1.0, v56
	v_add_f32_e32 v57, 1.0, v57
	v_exp_f32_e32 v58, v58
	v_exp_f32_e32 v59, v59
	global_store_dword v195, v60, s[12:13] nt
	v_cndmask_b32_e64 v60, v62, v63, s[10:11]
	v_mov_b32_e32 v61, v129
	v_rcp_f32_e32 v56, v56
	v_rcp_f32_e32 v57, v57
	v_mov_b32_dpp v61, v60 quad_perm:[1,0,3,2] row_mask:0xf bank_mask:0xf
	v_cndmask_b32_e64 v60, v61, v62, s[10:11]
	v_mul_f32_e32 v52, 0xbfb8aa3b, v52
	v_mul_f32_e32 v53, 0xbfb8aa3b, v53
	v_cndmask_b32_e64 v61, v63, v61, s[10:11]
	v_cvt_pk_bf16_f32 v60, v60, v61
	v_add_f32_e32 v58, 1.0, v58
	v_add_f32_e32 v59, 1.0, v59
	v_exp_f32_e32 v52, v52
	v_exp_f32_e32 v53, v53
	global_store_dword v194, v60, s[12:13] nt
	v_cndmask_b32_e64 v60, v56, v57, s[10:11]
	v_mov_b32_e32 v61, v129
	v_rcp_f32_e32 v58, v58
	v_rcp_f32_e32 v59, v59
	v_mov_b32_dpp v61, v60 quad_perm:[1,0,3,2] row_mask:0xf bank_mask:0xf
	v_cndmask_b32_e64 v56, v61, v56, s[10:11]
	v_mul_f32_e32 v54, 0xbfb8aa3b, v54
	v_mul_f32_e32 v55, 0xbfb8aa3b, v55
	v_cndmask_b32_e64 v57, v57, v61, s[10:11]
	v_cvt_pk_bf16_f32 v56, v56, v57
	v_add_f32_e32 v52, 1.0, v52
	v_add_f32_e32 v53, 1.0, v53
	v_exp_f32_e32 v54, v54
	v_exp_f32_e32 v55, v55
	global_store_dword v193, v56, s[12:13] nt
	v_cndmask_b32_e64 v56, v58, v59, s[10:11]
	v_mov_b32_e32 v57, v129
	v_rcp_f32_e32 v52, v52
	v_rcp_f32_e32 v53, v53
	v_mov_b32_dpp v57, v56 quad_perm:[1,0,3,2] row_mask:0xf bank_mask:0xf
	v_cndmask_b32_e64 v56, v57, v58, s[10:11]
	v_mul_f32_e32 v48, 0xbfb8aa3b, v48
	v_mul_f32_e32 v49, 0xbfb8aa3b, v49
	v_cndmask_b32_e64 v57, v59, v57, s[10:11]
	v_cvt_pk_bf16_f32 v56, v56, v57
	v_add_f32_e32 v54, 1.0, v54
	v_add_f32_e32 v55, 1.0, v55
	v_exp_f32_e32 v48, v48
	v_exp_f32_e32 v49, v49
	global_store_dword v192, v56, s[12:13] nt
	v_cndmask_b32_e64 v56, v52, v53, s[10:11]
	v_mov_b32_e32 v57, v129
	v_rcp_f32_e32 v54, v54
	v_rcp_f32_e32 v55, v55
	v_mov_b32_dpp v57, v56 quad_perm:[1,0,3,2] row_mask:0xf bank_mask:0xf
	v_cndmask_b32_e64 v52, v57, v52, s[10:11]
	v_mul_f32_e32 v50, 0xbfb8aa3b, v50
	v_mul_f32_e32 v51, 0xbfb8aa3b, v51
	v_cndmask_b32_e64 v53, v53, v57, s[10:11]
	v_cvt_pk_bf16_f32 v52, v52, v53
	v_add_f32_e32 v48, 1.0, v48
	v_add_f32_e32 v49, 1.0, v49
	v_exp_f32_e32 v50, v50
	v_exp_f32_e32 v51, v51
	global_store_dword v191, v52, s[12:13] nt
	v_cndmask_b32_e64 v52, v54, v55, s[10:11]
	v_mov_b32_e32 v53, v129
	v_rcp_f32_e32 v48, v48
	v_rcp_f32_e32 v49, v49
	v_mov_b32_dpp v53, v52 quad_perm:[1,0,3,2] row_mask:0xf bank_mask:0xf
	v_cndmask_b32_e64 v52, v53, v54, s[10:11]
	v_cndmask_b32_e64 v53, v55, v53, s[10:11]
	v_cvt_pk_bf16_f32 v52, v52, v53
	v_add_f32_e32 v50, 1.0, v50
	v_add_f32_e32 v51, 1.0, v51
	global_store_dword v190, v52, s[12:13] nt
	v_cndmask_b32_e64 v52, v48, v49, s[10:11]
	v_mov_b32_e32 v53, v129
	v_rcp_f32_e32 v50, v50
	v_rcp_f32_e32 v51, v51
	v_mov_b32_dpp v53, v52 quad_perm:[1,0,3,2] row_mask:0xf bank_mask:0xf
	v_cndmask_b32_e64 v48, v53, v48, s[10:11]
	v_cndmask_b32_e64 v49, v49, v53, s[10:11]
	v_cvt_pk_bf16_f32 v48, v48, v49
	global_store_dword v189, v48, s[12:13] nt
	v_cvt_pk_bf16_f32 v48, v50, v51
	s_nop 1
	v_mov_b32_dpp v49, v48 quad_perm:[1,0,3,2] row_mask:0xf bank_mask:0xf
	v_perm_b32 v48, v49, v48, v250
	global_store_dword v188, v48, s[12:13] nt
	v_mul_f32_e32 v44, 0xbfb8aa3b, v44
	v_mul_f32_e32 v45, 0xbfb8aa3b, v45
	v_exp_f32_e32 v44, v44
	v_exp_f32_e32 v45, v45
	v_mul_f32_e32 v46, 0xbfb8aa3b, v46
	v_mul_f32_e32 v47, 0xbfb8aa3b, v47
	v_add_f32_e32 v44, 1.0, v44
	v_add_f32_e32 v45, 1.0, v45
	v_exp_f32_e32 v46, v46
	v_exp_f32_e32 v47, v47
	v_rcp_f32_e32 v44, v44
	v_rcp_f32_e32 v45, v45
	v_mul_f32_e32 v40, 0xbfb8aa3b, v40
	v_mul_f32_e32 v41, 0xbfb8aa3b, v41
	v_add_f32_e32 v46, 1.0, v46
	v_add_f32_e32 v47, 1.0, v47
	v_exp_f32_e32 v40, v40
	v_exp_f32_e32 v41, v41
	v_mov_b32_e32 v48, v129
	v_cndmask_b32_e64 v49, v44, v45, s[10:11]
	v_rcp_f32_e32 v46, v46
	v_rcp_f32_e32 v47, v47
	v_mov_b32_dpp v48, v49 quad_perm:[1,0,3,2] row_mask:0xf bank_mask:0xf
	v_cndmask_b32_e64 v44, v48, v44, s[10:11]
	v_mul_f32_e32 v42, 0xbfb8aa3b, v42
	v_mul_f32_e32 v43, 0xbfb8aa3b, v43
	v_cndmask_b32_e64 v45, v45, v48, s[10:11]
	v_cvt_pk_bf16_f32 v44, v44, v45
	v_add_f32_e32 v40, 1.0, v40
	v_add_f32_e32 v41, 1.0, v41
	v_exp_f32_e32 v42, v42
	v_exp_f32_e32 v43, v43
	global_store_dword v187, v44, s[12:13] nt
	v_cndmask_b32_e64 v44, v46, v47, s[10:11]
	v_mov_b32_e32 v45, v129
	v_rcp_f32_e32 v40, v40
	v_rcp_f32_e32 v41, v41
	v_mov_b32_dpp v45, v44 quad_perm:[1,0,3,2] row_mask:0xf bank_mask:0xf
	v_cndmask_b32_e64 v44, v45, v46, s[10:11]
	v_mul_f32_e32 v36, 0xbfb8aa3b, v36
	v_mul_f32_e32 v37, 0xbfb8aa3b, v37
	v_cndmask_b32_e64 v45, v47, v45, s[10:11]
	v_cvt_pk_bf16_f32 v44, v44, v45
	v_add_f32_e32 v42, 1.0, v42
	v_add_f32_e32 v43, 1.0, v43
	v_exp_f32_e32 v36, v36
	v_exp_f32_e32 v37, v37
	global_store_dword v186, v44, s[12:13] nt
	v_cndmask_b32_e64 v44, v40, v41, s[10:11]
	v_mov_b32_e32 v45, v129
	v_rcp_f32_e32 v42, v42
	v_rcp_f32_e32 v43, v43
	v_mov_b32_dpp v45, v44 quad_perm:[1,0,3,2] row_mask:0xf bank_mask:0xf
	v_cndmask_b32_e64 v40, v45, v40, s[10:11]
	v_mul_f32_e32 v38, 0xbfb8aa3b, v38
	v_mul_f32_e32 v39, 0xbfb8aa3b, v39
	v_cndmask_b32_e64 v41, v41, v45, s[10:11]
	v_cvt_pk_bf16_f32 v40, v40, v41
	v_add_f32_e32 v36, 1.0, v36
	v_add_f32_e32 v37, 1.0, v37
	v_exp_f32_e32 v38, v38
	v_exp_f32_e32 v39, v39
	global_store_dword v185, v40, s[12:13] nt
	v_cndmask_b32_e64 v40, v42, v43, s[10:11]
	v_mov_b32_e32 v41, v129
	v_rcp_f32_e32 v36, v36
	v_rcp_f32_e32 v37, v37
	v_mov_b32_dpp v41, v40 quad_perm:[1,0,3,2] row_mask:0xf bank_mask:0xf
	v_cndmask_b32_e64 v40, v41, v42, s[10:11]
	v_mul_f32_e32 v32, 0xbfb8aa3b, v32
	v_mul_f32_e32 v33, 0xbfb8aa3b, v33
	v_cndmask_b32_e64 v41, v43, v41, s[10:11]
	v_cvt_pk_bf16_f32 v40, v40, v41
	v_add_f32_e32 v38, 1.0, v38
	v_add_f32_e32 v39, 1.0, v39
	v_exp_f32_e32 v32, v32
	v_exp_f32_e32 v33, v33
	global_store_dword v184, v40, s[12:13] nt
	v_cndmask_b32_e64 v40, v36, v37, s[10:11]
	v_mov_b32_e32 v41, v129
	v_rcp_f32_e32 v38, v38
	v_rcp_f32_e32 v39, v39
	v_mov_b32_dpp v41, v40 quad_perm:[1,0,3,2] row_mask:0xf bank_mask:0xf
	v_cndmask_b32_e64 v36, v41, v36, s[10:11]
	v_mul_f32_e32 v34, 0xbfb8aa3b, v34
	v_mul_f32_e32 v35, 0xbfb8aa3b, v35
	v_cndmask_b32_e64 v37, v37, v41, s[10:11]
	v_cvt_pk_bf16_f32 v36, v36, v37
	v_add_f32_e32 v32, 1.0, v32
	v_add_f32_e32 v33, 1.0, v33
	v_exp_f32_e32 v34, v34
	v_exp_f32_e32 v35, v35
	global_store_dword v183, v36, s[12:13] nt
	v_cndmask_b32_e64 v36, v38, v39, s[10:11]
	v_mov_b32_e32 v37, v129
	v_rcp_f32_e32 v32, v32
	v_rcp_f32_e32 v33, v33
	v_mov_b32_dpp v37, v36 quad_perm:[1,0,3,2] row_mask:0xf bank_mask:0xf
	v_cndmask_b32_e64 v36, v37, v38, s[10:11]
	v_cndmask_b32_e64 v37, v39, v37, s[10:11]
	v_cvt_pk_bf16_f32 v36, v36, v37
	v_add_f32_e32 v34, 1.0, v34
	v_add_f32_e32 v35, 1.0, v35
	global_store_dword v182, v36, s[12:13] nt
	v_cndmask_b32_e64 v36, v32, v33, s[10:11]
	v_mov_b32_e32 v37, v129
	v_rcp_f32_e32 v34, v34
	v_rcp_f32_e32 v35, v35
	v_mov_b32_dpp v37, v36 quad_perm:[1,0,3,2] row_mask:0xf bank_mask:0xf
	v_cndmask_b32_e64 v32, v37, v32, s[10:11]
	v_cndmask_b32_e64 v33, v33, v37, s[10:11]
	v_cvt_pk_bf16_f32 v32, v32, v33
	global_store_dword v181, v32, s[12:13] nt
	v_cvt_pk_bf16_f32 v32, v34, v35
	s_nop 1
	v_mov_b32_dpp v33, v32 quad_perm:[1,0,3,2] row_mask:0xf bank_mask:0xf
	v_perm_b32 v32, v33, v32, v250
	global_store_dword v180, v32, s[12:13] nt
	v_mul_f32_e32 v28, 0xbfb8aa3b, v28
	v_mul_f32_e32 v29, 0xbfb8aa3b, v29
	v_exp_f32_e32 v28, v28
	v_exp_f32_e32 v29, v29
	v_mul_f32_e32 v30, 0xbfb8aa3b, v30
	v_mul_f32_e32 v31, 0xbfb8aa3b, v31
	v_add_f32_e32 v28, 1.0, v28
	v_add_f32_e32 v29, 1.0, v29
	v_exp_f32_e32 v30, v30
	v_exp_f32_e32 v31, v31
	v_rcp_f32_e32 v28, v28
	v_rcp_f32_e32 v29, v29
	v_mul_f32_e32 v24, 0xbfb8aa3b, v24
	v_mul_f32_e32 v25, 0xbfb8aa3b, v25
	v_add_f32_e32 v30, 1.0, v30
	v_add_f32_e32 v31, 1.0, v31
	v_exp_f32_e32 v24, v24
	v_exp_f32_e32 v25, v25
	v_mov_b32_e32 v32, v129
	v_cndmask_b32_e64 v33, v28, v29, s[10:11]
	v_rcp_f32_e32 v30, v30
	v_rcp_f32_e32 v31, v31
	v_mov_b32_dpp v32, v33 quad_perm:[1,0,3,2] row_mask:0xf bank_mask:0xf
	v_cndmask_b32_e64 v28, v32, v28, s[10:11]
	v_mul_f32_e32 v26, 0xbfb8aa3b, v26
	v_mul_f32_e32 v27, 0xbfb8aa3b, v27
	v_cndmask_b32_e64 v29, v29, v32, s[10:11]
	v_cvt_pk_bf16_f32 v28, v28, v29
	v_add_f32_e32 v24, 1.0, v24
	v_add_f32_e32 v25, 1.0, v25
	v_exp_f32_e32 v26, v26
	v_exp_f32_e32 v27, v27
	global_store_dword v173, v28, s[12:13] nt
	v_cndmask_b32_e64 v28, v30, v31, s[10:11]
	v_mov_b32_e32 v29, v129
	v_rcp_f32_e32 v24, v24
	v_rcp_f32_e32 v25, v25
	v_mov_b32_dpp v29, v28 quad_perm:[1,0,3,2] row_mask:0xf bank_mask:0xf
	v_cndmask_b32_e64 v28, v29, v30, s[10:11]
	v_mul_f32_e32 v20, 0xbfb8aa3b, v20
	v_mul_f32_e32 v21, 0xbfb8aa3b, v21
	v_cndmask_b32_e64 v29, v31, v29, s[10:11]
	v_cvt_pk_bf16_f32 v28, v28, v29
	v_add_f32_e32 v26, 1.0, v26
	v_add_f32_e32 v27, 1.0, v27
	v_exp_f32_e32 v20, v20
	v_exp_f32_e32 v21, v21
	global_store_dword v172, v28, s[12:13] nt
	v_cndmask_b32_e64 v28, v24, v25, s[10:11]
	v_mov_b32_e32 v29, v129
	v_rcp_f32_e32 v26, v26
	v_rcp_f32_e32 v27, v27
	v_mov_b32_dpp v29, v28 quad_perm:[1,0,3,2] row_mask:0xf bank_mask:0xf
	v_cndmask_b32_e64 v24, v29, v24, s[10:11]
	v_mul_f32_e32 v22, 0xbfb8aa3b, v22
	v_mul_f32_e32 v23, 0xbfb8aa3b, v23
	v_cndmask_b32_e64 v25, v25, v29, s[10:11]
	v_cvt_pk_bf16_f32 v24, v24, v25
	v_add_f32_e32 v20, 1.0, v20
	v_add_f32_e32 v21, 1.0, v21
	v_exp_f32_e32 v22, v22
	v_exp_f32_e32 v23, v23
	global_store_dword v171, v24, s[12:13] nt
	v_cndmask_b32_e64 v24, v26, v27, s[10:11]
	v_mov_b32_e32 v25, v129
	v_rcp_f32_e32 v20, v20
	v_rcp_f32_e32 v21, v21
	v_mov_b32_dpp v25, v24 quad_perm:[1,0,3,2] row_mask:0xf bank_mask:0xf
	v_cndmask_b32_e64 v24, v25, v26, s[10:11]
	v_mul_f32_e32 v16, 0xbfb8aa3b, v16
	v_mul_f32_e32 v17, 0xbfb8aa3b, v17
	v_cndmask_b32_e64 v25, v27, v25, s[10:11]
	v_cvt_pk_bf16_f32 v24, v24, v25
	v_add_f32_e32 v22, 1.0, v22
	v_add_f32_e32 v23, 1.0, v23
	v_exp_f32_e32 v16, v16
	v_exp_f32_e32 v17, v17
	global_store_dword v170, v24, s[12:13] nt
	v_cndmask_b32_e64 v24, v20, v21, s[10:11]
	v_mov_b32_e32 v25, v129
	v_rcp_f32_e32 v22, v22
	v_rcp_f32_e32 v23, v23
	v_mov_b32_dpp v25, v24 quad_perm:[1,0,3,2] row_mask:0xf bank_mask:0xf
	v_cndmask_b32_e64 v20, v25, v20, s[10:11]
	v_mul_f32_e32 v18, 0xbfb8aa3b, v18
	v_mul_f32_e32 v19, 0xbfb8aa3b, v19
	v_cndmask_b32_e64 v21, v21, v25, s[10:11]
	v_cvt_pk_bf16_f32 v20, v20, v21
	v_add_f32_e32 v16, 1.0, v16
	v_add_f32_e32 v17, 1.0, v17
	v_exp_f32_e32 v18, v18
	v_exp_f32_e32 v19, v19
	global_store_dword v169, v20, s[12:13] nt
	v_cndmask_b32_e64 v20, v22, v23, s[10:11]
	v_mov_b32_e32 v21, v129
	v_rcp_f32_e32 v16, v16
	v_rcp_f32_e32 v17, v17
	v_mov_b32_dpp v21, v20 quad_perm:[1,0,3,2] row_mask:0xf bank_mask:0xf
	v_cndmask_b32_e64 v20, v21, v22, s[10:11]
	v_cndmask_b32_e64 v21, v23, v21, s[10:11]
	v_cvt_pk_bf16_f32 v20, v20, v21
	v_add_f32_e32 v18, 1.0, v18
	v_add_f32_e32 v19, 1.0, v19
	global_store_dword v168, v20, s[12:13] nt
	v_cndmask_b32_e64 v20, v16, v17, s[10:11]
	v_mov_b32_e32 v21, v129
	v_rcp_f32_e32 v18, v18
	v_rcp_f32_e32 v19, v19
	v_mov_b32_dpp v21, v20 quad_perm:[1,0,3,2] row_mask:0xf bank_mask:0xf
	v_cndmask_b32_e64 v16, v21, v16, s[10:11]
	v_cndmask_b32_e64 v17, v17, v21, s[10:11]
	v_cvt_pk_bf16_f32 v16, v16, v17
	global_store_dword v167, v16, s[12:13] nt
	v_cvt_pk_bf16_f32 v16, v18, v19
	s_nop 1
	v_mov_b32_dpp v17, v16 quad_perm:[1,0,3,2] row_mask:0xf bank_mask:0xf
	v_perm_b32 v16, v17, v16, v250
	global_store_dword v166, v16, s[12:13] nt
	v_mul_f32_e32 v12, 0xbfb8aa3b, v12
	v_mul_f32_e32 v13, 0xbfb8aa3b, v13
	v_exp_f32_e32 v12, v12
	v_exp_f32_e32 v13, v13
	v_mul_f32_e32 v14, 0xbfb8aa3b, v14
	v_mul_f32_e32 v15, 0xbfb8aa3b, v15
	v_add_f32_e32 v12, 1.0, v12
	v_add_f32_e32 v13, 1.0, v13
	v_exp_f32_e32 v14, v14
	v_exp_f32_e32 v15, v15
	v_rcp_f32_e32 v12, v12
	v_rcp_f32_e32 v13, v13
	v_mul_f32_e32 v8, 0xbfb8aa3b, v8
	v_mul_f32_e32 v9, 0xbfb8aa3b, v9
	v_add_f32_e32 v14, 1.0, v14
	v_add_f32_e32 v15, 1.0, v15
	v_exp_f32_e32 v8, v8
	v_exp_f32_e32 v9, v9
	v_mov_b32_e32 v16, v129
	v_cndmask_b32_e64 v17, v12, v13, s[10:11]
	v_rcp_f32_e32 v14, v14
	v_rcp_f32_e32 v15, v15
	v_mov_b32_dpp v16, v17 quad_perm:[1,0,3,2] row_mask:0xf bank_mask:0xf
	v_cndmask_b32_e64 v12, v16, v12, s[10:11]
	v_mul_f32_e32 v10, 0xbfb8aa3b, v10
	v_mul_f32_e32 v11, 0xbfb8aa3b, v11
	v_cndmask_b32_e64 v13, v13, v16, s[10:11]
	v_cvt_pk_bf16_f32 v12, v12, v13
	v_add_f32_e32 v8, 1.0, v8
	v_add_f32_e32 v9, 1.0, v9
	v_exp_f32_e32 v10, v10
	v_exp_f32_e32 v11, v11
	global_store_dword v165, v12, s[12:13] nt
	v_cndmask_b32_e64 v12, v14, v15, s[10:11]
	v_mov_b32_e32 v13, v129
	v_rcp_f32_e32 v8, v8
	v_rcp_f32_e32 v9, v9
	v_mov_b32_dpp v13, v12 quad_perm:[1,0,3,2] row_mask:0xf bank_mask:0xf
	v_cndmask_b32_e64 v12, v13, v14, s[10:11]
	v_mul_f32_e32 v4, 0xbfb8aa3b, v4
	v_mul_f32_e32 v5, 0xbfb8aa3b, v5
	v_cndmask_b32_e64 v13, v15, v13, s[10:11]
	v_cvt_pk_bf16_f32 v12, v12, v13
	v_add_f32_e32 v10, 1.0, v10
	v_add_f32_e32 v11, 1.0, v11
	v_exp_f32_e32 v4, v4
	v_exp_f32_e32 v5, v5
	global_store_dword v164, v12, s[12:13] nt
	v_cndmask_b32_e64 v12, v8, v9, s[10:11]
	v_mov_b32_e32 v13, v129
	v_rcp_f32_e32 v10, v10
	v_rcp_f32_e32 v11, v11
	v_mov_b32_dpp v13, v12 quad_perm:[1,0,3,2] row_mask:0xf bank_mask:0xf
	v_cndmask_b32_e64 v8, v13, v8, s[10:11]
	v_mul_f32_e32 v6, 0xbfb8aa3b, v6
	v_mul_f32_e32 v7, 0xbfb8aa3b, v7
	v_cndmask_b32_e64 v9, v9, v13, s[10:11]
	v_cvt_pk_bf16_f32 v8, v8, v9
	v_add_f32_e32 v4, 1.0, v4
	v_add_f32_e32 v5, 1.0, v5
	v_exp_f32_e32 v6, v6
	v_exp_f32_e32 v7, v7
	global_store_dword v163, v8, s[12:13] nt
	v_cndmask_b32_e64 v8, v10, v11, s[10:11]
	v_mov_b32_e32 v9, v129
	v_rcp_f32_e32 v4, v4
	v_rcp_f32_e32 v5, v5
	v_mov_b32_dpp v9, v8 quad_perm:[1,0,3,2] row_mask:0xf bank_mask:0xf
	v_cndmask_b32_e64 v8, v9, v10, s[10:11]
	v_mul_f32_e32 v0, 0xbfb8aa3b, v0
	v_mul_f32_e32 v1, 0xbfb8aa3b, v1
	v_cndmask_b32_e64 v9, v11, v9, s[10:11]
	v_cvt_pk_bf16_f32 v8, v8, v9
	v_add_f32_e32 v6, 1.0, v6
	v_add_f32_e32 v7, 1.0, v7
	v_exp_f32_e32 v0, v0
	v_exp_f32_e32 v1, v1
	global_store_dword v162, v8, s[12:13] nt
	v_cndmask_b32_e64 v8, v4, v5, s[10:11]
	v_mov_b32_e32 v9, v129
	v_rcp_f32_e32 v6, v6
	v_rcp_f32_e32 v7, v7
	v_mov_b32_dpp v9, v8 quad_perm:[1,0,3,2] row_mask:0xf bank_mask:0xf
	v_cndmask_b32_e64 v4, v9, v4, s[10:11]
	v_mul_f32_e32 v2, 0xbfb8aa3b, v2
	v_mul_f32_e32 v3, 0xbfb8aa3b, v3
	v_cndmask_b32_e64 v5, v5, v9, s[10:11]
	v_cvt_pk_bf16_f32 v4, v4, v5
	v_add_f32_e32 v0, 1.0, v0
	v_add_f32_e32 v1, 1.0, v1
	v_exp_f32_e32 v2, v2
	v_exp_f32_e32 v3, v3
	global_store_dword v161, v4, s[12:13] nt
	v_cndmask_b32_e64 v4, v6, v7, s[10:11]
	v_mov_b32_e32 v5, v129
	v_rcp_f32_e32 v0, v0
	v_rcp_f32_e32 v1, v1
	v_mov_b32_dpp v5, v4 quad_perm:[1,0,3,2] row_mask:0xf bank_mask:0xf
	v_cndmask_b32_e64 v4, v5, v6, s[10:11]
	v_cndmask_b32_e64 v5, v7, v5, s[10:11]
	v_cvt_pk_bf16_f32 v4, v4, v5
	v_add_f32_e32 v2, 1.0, v2
	v_add_f32_e32 v3, 1.0, v3
	global_store_dword v160, v4, s[12:13] nt
	v_cndmask_b32_e64 v4, v0, v1, s[10:11]
	v_mov_b32_e32 v5, v129
	v_rcp_f32_e32 v2, v2
	v_rcp_f32_e32 v3, v3
	v_mov_b32_dpp v5, v4 quad_perm:[1,0,3,2] row_mask:0xf bank_mask:0xf
	v_cndmask_b32_e64 v0, v5, v0, s[10:11]
	v_cndmask_b32_e64 v1, v1, v5, s[10:11]
	v_cvt_pk_bf16_f32 v0, v0, v1
	global_store_dword v159, v0, s[12:13] nt
	v_cvt_pk_bf16_f32 v0, v2, v3
	s_nop 1
	v_mov_b32_dpp v1, v0 quad_perm:[1,0,3,2] row_mask:0xf bank_mask:0xf
	v_perm_b32 v0, v1, v0, v250
	global_store_dword v158, v0, s[12:13] nt
	s_branch .LBB0_1556
